# s_pass 8-row batched fast path; attention Zg loads batched in epilogue; gate epilogue scalar VALU
# speedup vs baseline: 1.0074x; 1.0074x over previous
.LBB0_160:
	s_cmp_eq_u32 s34, 0
	s_cbranch_scc1 .Lgate_epi_b0
	v_lshl_add_u32 v120, s10, 8, v212
	s_lshl_b32 s10, s38, 8
	v_or_b32_e32 v121, s10, v213
	v_lshlrev_b32_e32 v124, 2, v121
	global_load_dwordx4 v[142:145], v124, s[66:67]
	global_load_dwordx4 v[146:149], v124, s[66:67] offset:16
	global_load_dwordx4 v[150:153], v124, s[66:67] offset:512
	global_load_dwordx4 v[154:157], v124, s[66:67] offset:528
	v_lshlrev_b32_e32 v122, 13, v120
	v_lshl_add_u32 v122, v121, 1, v122
	v_and_b32_e32 v121, 0x3ff, v121
	v_lshlrev_b32_e32 v123, 11, v120
	v_lshl_add_u32 v123, v121, 1, v123
	v_mov_b32_e32 v138, 0xbfb8aa3b
	v_mov_b32_e32 v140, 1.0
	global_load_dwordx4 v[158:161], v122, s[54:55]
	global_load_dwordx4 v[162:165], v123, s[58:59]
	v_add_u32_e32 v125, 0x20000, v122
	global_load_dwordx4 v[172:175], v125, s[54:55]
	v_add_u32_e32 v125, 0x8000, v123
	global_load_dwordx4 v[176:179], v125, s[58:59]
	v_add_u32_e32 v125, 0x40000, v122
	global_load_dwordx4 v[180:183], v125, s[54:55]
	v_add_u32_e32 v125, 0x10000, v123
	global_load_dwordx4 v[184:187], v125, s[58:59]
	v_add_u32_e32 v125, 0x60000, v122
	global_load_dwordx4 v[188:191], v125, s[54:55]
	v_add_u32_e32 v125, 0x18000, v123
	global_load_dwordx4 v[192:195], v125, s[58:59]
	v_add_u32_e32 v125, 0x100000, v122
	global_load_dwordx4 v[216:219], v125, s[54:55]
	v_add_u32_e32 v125, 0x40000, v123
	global_load_dwordx4 v[220:223], v125, s[58:59]
	v_add_u32_e32 v125, 0x120000, v122
	global_load_dwordx4 v[224:227], v125, s[54:55]
	v_add_u32_e32 v125, 0x48000, v123
	global_load_dwordx4 v[228:231], v125, s[58:59]
	v_add_u32_e32 v125, 0x140000, v122
	global_load_dwordx4 v[236:239], v125, s[54:55]
	v_add_u32_e32 v125, 0x50000, v123
	global_load_dwordx4 v[240:243], v125, s[58:59]
	v_add_u32_e32 v125, 0x160000, v122
	global_load_dwordx4 v[244:247], v125, s[54:55]
	v_add_u32_e32 v125, 0x58000, v123
	global_load_dwordx4 v[248:251], v125, s[58:59]
	global_load_dwordx4 v[252:255], v122, s[54:55] offset:256
	s_waitcnt vmcnt(15)
	v_add_f32_e32 v132, v132, v142
	v_add_f32_e32 v133, v133, v143
	v_add_f32_e32 v134, v134, v144
	v_add_f32_e32 v135, v135, v145
	v_add_f32_e32 v128, v128, v146
	v_add_f32_e32 v129, v129, v147
	v_add_f32_e32 v130, v130, v148
	v_add_f32_e32 v131, v131, v149
	v_mul_f32_e32 v132, 0xbfb8aa3b, v132
	v_mul_f32_e32 v133, 0xbfb8aa3b, v133
	v_mul_f32_e32 v134, 0xbfb8aa3b, v134
	v_mul_f32_e32 v135, 0xbfb8aa3b, v135
	v_mul_f32_e32 v128, 0xbfb8aa3b, v128
	v_mul_f32_e32 v129, 0xbfb8aa3b, v129
	v_mul_f32_e32 v130, 0xbfb8aa3b, v130
	v_mul_f32_e32 v131, 0xbfb8aa3b, v131
	v_exp_f32_e32 v132, v132
	v_exp_f32_e32 v133, v133
	v_exp_f32_e32 v134, v134
	v_exp_f32_e32 v135, v135
	v_exp_f32_e32 v128, v128
	v_exp_f32_e32 v129, v129
	v_exp_f32_e32 v130, v130
	v_exp_f32_e32 v131, v131
	v_add_f32_e32 v132, 1.0, v132
	v_add_f32_e32 v133, 1.0, v133
	v_add_f32_e32 v134, 1.0, v134
	v_add_f32_e32 v135, 1.0, v135
	v_add_f32_e32 v128, 1.0, v128
	v_add_f32_e32 v129, 1.0, v129
	v_add_f32_e32 v130, 1.0, v130
	v_add_f32_e32 v131, 1.0, v131
	v_rcp_f32_e32 v132, v132
	v_rcp_f32_e32 v133, v133
	v_rcp_f32_e32 v134, v134
	v_rcp_f32_e32 v135, v135
	v_rcp_f32_e32 v128, v128
	v_rcp_f32_e32 v129, v129
	v_rcp_f32_e32 v130, v130
	v_rcp_f32_e32 v131, v131
	v_lshlrev_b32_e32 v127, 16, v158
	v_and_b32_e32 v158, 0xffff0000, v158
	v_lshlrev_b32_e32 v136, 16, v162
	v_and_b32_e32 v162, 0xffff0000, v162
	v_fmac_f32_e32 v136, v132, v127
	v_fmac_f32_e32 v162, v133, v158
	v_cvt_pk_bf16_f32 v162, v136, v162
	v_lshlrev_b32_e32 v127, 16, v159
	v_and_b32_e32 v159, 0xffff0000, v159
	v_lshlrev_b32_e32 v136, 16, v163
	v_and_b32_e32 v163, 0xffff0000, v163
	v_fmac_f32_e32 v136, v134, v127
	v_fmac_f32_e32 v163, v135, v159
	v_cvt_pk_bf16_f32 v163, v136, v163
	v_lshlrev_b32_e32 v127, 16, v160
	v_and_b32_e32 v160, 0xffff0000, v160
	v_lshlrev_b32_e32 v136, 16, v164
	v_and_b32_e32 v164, 0xffff0000, v164
	v_fmac_f32_e32 v136, v128, v127
	v_fmac_f32_e32 v164, v129, v160
	v_cvt_pk_bf16_f32 v164, v136, v164
	v_lshlrev_b32_e32 v127, 16, v161
	v_and_b32_e32 v161, 0xffff0000, v161
	v_lshlrev_b32_e32 v136, 16, v165
	v_and_b32_e32 v165, 0xffff0000, v165
	v_fmac_f32_e32 v136, v130, v127
	v_fmac_f32_e32 v165, v131, v161
	v_cvt_pk_bf16_f32 v165, v136, v165
	global_store_dwordx4 v123, v[162:165], s[58:59]
	global_load_dwordx4 v[132:135], v123, s[58:59] offset:256
	v_add_u32_e32 v125, 0x20000, v122
	global_load_dwordx4 v[128:131], v125, s[54:55] offset:256
	v_add_u32_e32 v125, 0x8000, v123
	global_load_dwordx4 v[158:161], v125, s[58:59] offset:256
	v_add_u32_e32 v125, 0x40000, v122
	global_load_dwordx4 v[162:165], v125, s[54:55] offset:256
	s_waitcnt vmcnt(18)
	v_add_f32_e32 v116, v116, v142
	v_add_f32_e32 v117, v117, v143
	v_add_f32_e32 v118, v118, v144
	v_add_f32_e32 v119, v119, v145
	v_add_f32_e32 v112, v112, v146
	v_add_f32_e32 v113, v113, v147
	v_add_f32_e32 v114, v114, v148
	v_add_f32_e32 v115, v115, v149
	v_mul_f32_e32 v116, 0xbfb8aa3b, v116
	v_mul_f32_e32 v117, 0xbfb8aa3b, v117
	v_mul_f32_e32 v118, 0xbfb8aa3b, v118
	v_mul_f32_e32 v119, 0xbfb8aa3b, v119
	v_mul_f32_e32 v112, 0xbfb8aa3b, v112
	v_mul_f32_e32 v113, 0xbfb8aa3b, v113
	v_mul_f32_e32 v114, 0xbfb8aa3b, v114
	v_mul_f32_e32 v115, 0xbfb8aa3b, v115
	v_exp_f32_e32 v116, v116
	v_exp_f32_e32 v117, v117
	v_exp_f32_e32 v118, v118
	v_exp_f32_e32 v119, v119
	v_exp_f32_e32 v112, v112
	v_exp_f32_e32 v113, v113
	v_exp_f32_e32 v114, v114
	v_exp_f32_e32 v115, v115
	v_add_f32_e32 v116, 1.0, v116
	v_add_f32_e32 v117, 1.0, v117
	v_add_f32_e32 v118, 1.0, v118
	v_add_f32_e32 v119, 1.0, v119
	v_add_f32_e32 v112, 1.0, v112
	v_add_f32_e32 v113, 1.0, v113
	v_add_f32_e32 v114, 1.0, v114
	v_add_f32_e32 v115, 1.0, v115
	v_rcp_f32_e32 v116, v116
	v_rcp_f32_e32 v117, v117
	v_rcp_f32_e32 v118, v118
	v_rcp_f32_e32 v119, v119
	v_rcp_f32_e32 v112, v112
	v_rcp_f32_e32 v113, v113
	v_rcp_f32_e32 v114, v114
	v_rcp_f32_e32 v115, v115
	v_lshlrev_b32_e32 v127, 16, v172
	v_and_b32_e32 v172, 0xffff0000, v172
	v_lshlrev_b32_e32 v136, 16, v176
	v_and_b32_e32 v176, 0xffff0000, v176
	v_fmac_f32_e32 v136, v116, v127
	v_fmac_f32_e32 v176, v117, v172
	v_cvt_pk_bf16_f32 v176, v136, v176
	v_lshlrev_b32_e32 v127, 16, v173
	v_and_b32_e32 v173, 0xffff0000, v173
	v_lshlrev_b32_e32 v136, 16, v177
	v_and_b32_e32 v177, 0xffff0000, v177
	v_fmac_f32_e32 v136, v118, v127
	v_fmac_f32_e32 v177, v119, v173
	v_cvt_pk_bf16_f32 v177, v136, v177
	v_lshlrev_b32_e32 v127, 16, v174
	v_and_b32_e32 v174, 0xffff0000, v174
	v_lshlrev_b32_e32 v136, 16, v178
	v_and_b32_e32 v178, 0xffff0000, v178
	v_fmac_f32_e32 v136, v112, v127
	v_fmac_f32_e32 v178, v113, v174
	v_cvt_pk_bf16_f32 v178, v136, v178
	v_lshlrev_b32_e32 v127, 16, v175
	v_and_b32_e32 v175, 0xffff0000, v175
	v_lshlrev_b32_e32 v136, 16, v179
	v_and_b32_e32 v179, 0xffff0000, v179
	v_fmac_f32_e32 v136, v114, v127
	v_fmac_f32_e32 v179, v115, v175
	v_cvt_pk_bf16_f32 v179, v136, v179
	v_add_u32_e32 v126, 0x8000, v123
	global_store_dwordx4 v126, v[176:179], s[58:59]
	v_add_u32_e32 v125, 0x10000, v123
	global_load_dwordx4 v[116:119], v125, s[58:59] offset:256
	v_add_u32_e32 v125, 0x60000, v122
	global_load_dwordx4 v[112:115], v125, s[54:55] offset:256
	v_add_u32_e32 v125, 0x18000, v123
	global_load_dwordx4 v[172:175], v125, s[58:59] offset:256
	v_add_u32_e32 v125, 0x100000, v122
	global_load_dwordx4 v[176:179], v125, s[54:55] offset:256
	s_waitcnt vmcnt(21)
	v_add_f32_e32 v108, v108, v142
	v_add_f32_e32 v109, v109, v143
	v_add_f32_e32 v110, v110, v144
	v_add_f32_e32 v111, v111, v145
	v_add_f32_e32 v104, v104, v146
	v_add_f32_e32 v105, v105, v147
	v_add_f32_e32 v106, v106, v148
	v_add_f32_e32 v107, v107, v149
	v_mul_f32_e32 v108, 0xbfb8aa3b, v108
	v_mul_f32_e32 v109, 0xbfb8aa3b, v109
	v_mul_f32_e32 v110, 0xbfb8aa3b, v110
	v_mul_f32_e32 v111, 0xbfb8aa3b, v111
	v_mul_f32_e32 v104, 0xbfb8aa3b, v104
	v_mul_f32_e32 v105, 0xbfb8aa3b, v105
	v_mul_f32_e32 v106, 0xbfb8aa3b, v106
	v_mul_f32_e32 v107, 0xbfb8aa3b, v107
	v_exp_f32_e32 v108, v108
	v_exp_f32_e32 v109, v109
	v_exp_f32_e32 v110, v110
	v_exp_f32_e32 v111, v111
	v_exp_f32_e32 v104, v104
	v_exp_f32_e32 v105, v105
	v_exp_f32_e32 v106, v106
	v_exp_f32_e32 v107, v107
	v_add_f32_e32 v108, 1.0, v108
	v_add_f32_e32 v109, 1.0, v109
	v_add_f32_e32 v110, 1.0, v110
	v_add_f32_e32 v111, 1.0, v111
	v_add_f32_e32 v104, 1.0, v104
	v_add_f32_e32 v105, 1.0, v105
	v_add_f32_e32 v106, 1.0, v106
	v_add_f32_e32 v107, 1.0, v107
	v_rcp_f32_e32 v108, v108
	v_rcp_f32_e32 v109, v109
	v_rcp_f32_e32 v110, v110
	v_rcp_f32_e32 v111, v111
	v_rcp_f32_e32 v104, v104
	v_rcp_f32_e32 v105, v105
	v_rcp_f32_e32 v106, v106
	v_rcp_f32_e32 v107, v107
	v_lshlrev_b32_e32 v127, 16, v180
	v_and_b32_e32 v180, 0xffff0000, v180
	v_lshlrev_b32_e32 v136, 16, v184
	v_and_b32_e32 v184, 0xffff0000, v184
	v_fmac_f32_e32 v136, v108, v127
	v_fmac_f32_e32 v184, v109, v180
	v_cvt_pk_bf16_f32 v184, v136, v184
	v_lshlrev_b32_e32 v127, 16, v181
	v_and_b32_e32 v181, 0xffff0000, v181
	v_lshlrev_b32_e32 v136, 16, v185
	v_and_b32_e32 v185, 0xffff0000, v185
	v_fmac_f32_e32 v136, v110, v127
	v_fmac_f32_e32 v185, v111, v181
	v_cvt_pk_bf16_f32 v185, v136, v185
	v_lshlrev_b32_e32 v127, 16, v182
	v_and_b32_e32 v182, 0xffff0000, v182
	v_lshlrev_b32_e32 v136, 16, v186
	v_and_b32_e32 v186, 0xffff0000, v186
	v_fmac_f32_e32 v136, v104, v127
	v_fmac_f32_e32 v186, v105, v182
	v_cvt_pk_bf16_f32 v186, v136, v186
	v_lshlrev_b32_e32 v127, 16, v183
	v_and_b32_e32 v183, 0xffff0000, v183
	v_lshlrev_b32_e32 v136, 16, v187
	v_and_b32_e32 v187, 0xffff0000, v187
	v_fmac_f32_e32 v136, v106, v127
	v_fmac_f32_e32 v187, v107, v183
	v_cvt_pk_bf16_f32 v187, v136, v187
	v_add_u32_e32 v126, 0x10000, v123
	global_store_dwordx4 v126, v[184:187], s[58:59]
	v_add_u32_e32 v125, 0x40000, v123
	global_load_dwordx4 v[108:111], v125, s[58:59] offset:256
	v_add_u32_e32 v125, 0x120000, v122
	global_load_dwordx4 v[104:107], v125, s[54:55] offset:256
	v_add_u32_e32 v125, 0x48000, v123
	global_load_dwordx4 v[180:183], v125, s[58:59] offset:256
	v_add_u32_e32 v125, 0x140000, v122
	global_load_dwordx4 v[184:187], v125, s[54:55] offset:256
	s_waitcnt vmcnt(24)
	v_add_f32_e32 v100, v100, v142
	v_add_f32_e32 v101, v101, v143
	v_add_f32_e32 v102, v102, v144
	v_add_f32_e32 v103, v103, v145
	v_add_f32_e32 v96, v96, v146
	v_add_f32_e32 v97, v97, v147
	v_add_f32_e32 v98, v98, v148
	v_add_f32_e32 v99, v99, v149
	v_mul_f32_e32 v100, 0xbfb8aa3b, v100
	v_mul_f32_e32 v101, 0xbfb8aa3b, v101
	v_mul_f32_e32 v102, 0xbfb8aa3b, v102
	v_mul_f32_e32 v103, 0xbfb8aa3b, v103
	v_mul_f32_e32 v96, 0xbfb8aa3b, v96
	v_mul_f32_e32 v97, 0xbfb8aa3b, v97
	v_mul_f32_e32 v98, 0xbfb8aa3b, v98
	v_mul_f32_e32 v99, 0xbfb8aa3b, v99
	v_exp_f32_e32 v100, v100
	v_exp_f32_e32 v101, v101
	v_exp_f32_e32 v102, v102
	v_exp_f32_e32 v103, v103
	v_exp_f32_e32 v96, v96
	v_exp_f32_e32 v97, v97
	v_exp_f32_e32 v98, v98
	v_exp_f32_e32 v99, v99
	v_add_f32_e32 v100, 1.0, v100
	v_add_f32_e32 v101, 1.0, v101
	v_add_f32_e32 v102, 1.0, v102
	v_add_f32_e32 v103, 1.0, v103
	v_add_f32_e32 v96, 1.0, v96
	v_add_f32_e32 v97, 1.0, v97
	v_add_f32_e32 v98, 1.0, v98
	v_add_f32_e32 v99, 1.0, v99
	v_rcp_f32_e32 v100, v100
	v_rcp_f32_e32 v101, v101
	v_rcp_f32_e32 v102, v102
	v_rcp_f32_e32 v103, v103
	v_rcp_f32_e32 v96, v96
	v_rcp_f32_e32 v97, v97
	v_rcp_f32_e32 v98, v98
	v_rcp_f32_e32 v99, v99
	v_lshlrev_b32_e32 v127, 16, v188
	v_and_b32_e32 v188, 0xffff0000, v188
	v_lshlrev_b32_e32 v136, 16, v192
	v_and_b32_e32 v192, 0xffff0000, v192
	v_fmac_f32_e32 v136, v100, v127
	v_fmac_f32_e32 v192, v101, v188
	v_cvt_pk_bf16_f32 v192, v136, v192
	v_lshlrev_b32_e32 v127, 16, v189
	v_and_b32_e32 v189, 0xffff0000, v189
	v_lshlrev_b32_e32 v136, 16, v193
	v_and_b32_e32 v193, 0xffff0000, v193
	v_fmac_f32_e32 v136, v102, v127
	v_fmac_f32_e32 v193, v103, v189
	v_cvt_pk_bf16_f32 v193, v136, v193
	v_lshlrev_b32_e32 v127, 16, v190
	v_and_b32_e32 v190, 0xffff0000, v190
	v_lshlrev_b32_e32 v136, 16, v194
	v_and_b32_e32 v194, 0xffff0000, v194
	v_fmac_f32_e32 v136, v96, v127
	v_fmac_f32_e32 v194, v97, v190
	v_cvt_pk_bf16_f32 v194, v136, v194
	v_lshlrev_b32_e32 v127, 16, v191
	v_and_b32_e32 v191, 0xffff0000, v191
	v_lshlrev_b32_e32 v136, 16, v195
	v_and_b32_e32 v195, 0xffff0000, v195
	v_fmac_f32_e32 v136, v98, v127
	v_fmac_f32_e32 v195, v99, v191
	v_cvt_pk_bf16_f32 v195, v136, v195
	v_add_u32_e32 v126, 0x18000, v123
	global_store_dwordx4 v126, v[192:195], s[58:59]
	v_add_u32_e32 v125, 0x50000, v123
	global_load_dwordx4 v[100:103], v125, s[58:59] offset:256
	v_add_u32_e32 v125, 0x160000, v122
	global_load_dwordx4 v[96:99], v125, s[54:55] offset:256
	v_add_u32_e32 v125, 0x58000, v123
	global_load_dwordx4 v[188:191], v125, s[58:59] offset:256
	s_waitcnt vmcnt(26)
	v_add_f32_e32 v92, v92, v142
	v_add_f32_e32 v93, v93, v143
	v_add_f32_e32 v94, v94, v144
	v_add_f32_e32 v95, v95, v145
	v_add_f32_e32 v88, v88, v146
	v_add_f32_e32 v89, v89, v147
	v_add_f32_e32 v90, v90, v148
	v_add_f32_e32 v91, v91, v149
	v_mul_f32_e32 v92, 0xbfb8aa3b, v92
	v_mul_f32_e32 v93, 0xbfb8aa3b, v93
	v_mul_f32_e32 v94, 0xbfb8aa3b, v94
	v_mul_f32_e32 v95, 0xbfb8aa3b, v95
	v_mul_f32_e32 v88, 0xbfb8aa3b, v88
	v_mul_f32_e32 v89, 0xbfb8aa3b, v89
	v_mul_f32_e32 v90, 0xbfb8aa3b, v90
	v_mul_f32_e32 v91, 0xbfb8aa3b, v91
	v_exp_f32_e32 v92, v92
	v_exp_f32_e32 v93, v93
	v_exp_f32_e32 v94, v94
	v_exp_f32_e32 v95, v95
	v_exp_f32_e32 v88, v88
	v_exp_f32_e32 v89, v89
	v_exp_f32_e32 v90, v90
	v_exp_f32_e32 v91, v91
	v_add_f32_e32 v92, 1.0, v92
	v_add_f32_e32 v93, 1.0, v93
	v_add_f32_e32 v94, 1.0, v94
	v_add_f32_e32 v95, 1.0, v95
	v_add_f32_e32 v88, 1.0, v88
	v_add_f32_e32 v89, 1.0, v89
	v_add_f32_e32 v90, 1.0, v90
	v_add_f32_e32 v91, 1.0, v91
	v_rcp_f32_e32 v92, v92
	v_rcp_f32_e32 v93, v93
	v_rcp_f32_e32 v94, v94
	v_rcp_f32_e32 v95, v95
	v_rcp_f32_e32 v88, v88
	v_rcp_f32_e32 v89, v89
	v_rcp_f32_e32 v90, v90
	v_rcp_f32_e32 v91, v91
	v_lshlrev_b32_e32 v127, 16, v216
	v_and_b32_e32 v216, 0xffff0000, v216
	v_lshlrev_b32_e32 v136, 16, v220
	v_and_b32_e32 v220, 0xffff0000, v220
	v_fmac_f32_e32 v136, v92, v127
	v_fmac_f32_e32 v220, v93, v216
	v_cvt_pk_bf16_f32 v220, v136, v220
	v_lshlrev_b32_e32 v127, 16, v217
	v_and_b32_e32 v217, 0xffff0000, v217
	v_lshlrev_b32_e32 v136, 16, v221
	v_and_b32_e32 v221, 0xffff0000, v221
	v_fmac_f32_e32 v136, v94, v127
	v_fmac_f32_e32 v221, v95, v217
	v_cvt_pk_bf16_f32 v221, v136, v221
	v_lshlrev_b32_e32 v127, 16, v218
	v_and_b32_e32 v218, 0xffff0000, v218
	v_lshlrev_b32_e32 v136, 16, v222
	v_and_b32_e32 v222, 0xffff0000, v222
	v_fmac_f32_e32 v136, v88, v127
	v_fmac_f32_e32 v222, v89, v218
	v_cvt_pk_bf16_f32 v222, v136, v222
	v_lshlrev_b32_e32 v127, 16, v219
	v_and_b32_e32 v219, 0xffff0000, v219
	v_lshlrev_b32_e32 v136, 16, v223
	v_and_b32_e32 v223, 0xffff0000, v223
	v_fmac_f32_e32 v136, v90, v127
	v_fmac_f32_e32 v223, v91, v219
	v_cvt_pk_bf16_f32 v223, v136, v223
	v_add_u32_e32 v126, 0x40000, v123
	global_store_dwordx4 v126, v[220:223], s[58:59]
	s_waitcnt vmcnt(25)
	v_add_f32_e32 v84, v84, v142
	v_add_f32_e32 v85, v85, v143
	v_add_f32_e32 v86, v86, v144
	v_add_f32_e32 v87, v87, v145
	v_add_f32_e32 v80, v80, v146
	v_add_f32_e32 v81, v81, v147
	v_add_f32_e32 v82, v82, v148
	v_add_f32_e32 v83, v83, v149
	v_mul_f32_e32 v84, 0xbfb8aa3b, v84
	v_mul_f32_e32 v85, 0xbfb8aa3b, v85
	v_mul_f32_e32 v86, 0xbfb8aa3b, v86
	v_mul_f32_e32 v87, 0xbfb8aa3b, v87
	v_mul_f32_e32 v80, 0xbfb8aa3b, v80
	v_mul_f32_e32 v81, 0xbfb8aa3b, v81
	v_mul_f32_e32 v82, 0xbfb8aa3b, v82
	v_mul_f32_e32 v83, 0xbfb8aa3b, v83
	v_exp_f32_e32 v84, v84
	v_exp_f32_e32 v85, v85
	v_exp_f32_e32 v86, v86
	v_exp_f32_e32 v87, v87
	v_exp_f32_e32 v80, v80
	v_exp_f32_e32 v81, v81
	v_exp_f32_e32 v82, v82
	v_exp_f32_e32 v83, v83
	v_add_f32_e32 v84, 1.0, v84
	v_add_f32_e32 v85, 1.0, v85
	v_add_f32_e32 v86, 1.0, v86
	v_add_f32_e32 v87, 1.0, v87
	v_add_f32_e32 v80, 1.0, v80
	v_add_f32_e32 v81, 1.0, v81
	v_add_f32_e32 v82, 1.0, v82
	v_add_f32_e32 v83, 1.0, v83
	v_rcp_f32_e32 v84, v84
	v_rcp_f32_e32 v85, v85
	v_rcp_f32_e32 v86, v86
	v_rcp_f32_e32 v87, v87
	v_rcp_f32_e32 v80, v80
	v_rcp_f32_e32 v81, v81
	v_rcp_f32_e32 v82, v82
	v_rcp_f32_e32 v83, v83
	v_lshlrev_b32_e32 v127, 16, v224
	v_and_b32_e32 v224, 0xffff0000, v224
	v_lshlrev_b32_e32 v136, 16, v228
	v_and_b32_e32 v228, 0xffff0000, v228
	v_fmac_f32_e32 v136, v84, v127
	v_fmac_f32_e32 v228, v85, v224
	v_cvt_pk_bf16_f32 v228, v136, v228
	v_lshlrev_b32_e32 v127, 16, v225
	v_and_b32_e32 v225, 0xffff0000, v225
	v_lshlrev_b32_e32 v136, 16, v229
	v_and_b32_e32 v229, 0xffff0000, v229
	v_fmac_f32_e32 v136, v86, v127
	v_fmac_f32_e32 v229, v87, v225
	v_cvt_pk_bf16_f32 v229, v136, v229
	v_lshlrev_b32_e32 v127, 16, v226
	v_and_b32_e32 v226, 0xffff0000, v226
	v_lshlrev_b32_e32 v136, 16, v230
	v_and_b32_e32 v230, 0xffff0000, v230
	v_fmac_f32_e32 v136, v80, v127
	v_fmac_f32_e32 v230, v81, v226
	v_cvt_pk_bf16_f32 v230, v136, v230
	v_lshlrev_b32_e32 v127, 16, v227
	v_and_b32_e32 v227, 0xffff0000, v227
	v_lshlrev_b32_e32 v136, 16, v231
	v_and_b32_e32 v231, 0xffff0000, v231
	v_fmac_f32_e32 v136, v82, v127
	v_fmac_f32_e32 v231, v83, v227
	v_cvt_pk_bf16_f32 v231, v136, v231
	v_add_u32_e32 v126, 0x48000, v123
	global_store_dwordx4 v126, v[228:231], s[58:59]
	s_waitcnt vmcnt(24)
	v_add_f32_e32 v76, v76, v142
	v_add_f32_e32 v77, v77, v143
	v_add_f32_e32 v78, v78, v144
	v_add_f32_e32 v79, v79, v145
	v_add_f32_e32 v72, v72, v146
	v_add_f32_e32 v73, v73, v147
	v_add_f32_e32 v74, v74, v148
	v_add_f32_e32 v75, v75, v149
	v_mul_f32_e32 v76, 0xbfb8aa3b, v76
	v_mul_f32_e32 v77, 0xbfb8aa3b, v77
	v_mul_f32_e32 v78, 0xbfb8aa3b, v78
	v_mul_f32_e32 v79, 0xbfb8aa3b, v79
	v_mul_f32_e32 v72, 0xbfb8aa3b, v72
	v_mul_f32_e32 v73, 0xbfb8aa3b, v73
	v_mul_f32_e32 v74, 0xbfb8aa3b, v74
	v_mul_f32_e32 v75, 0xbfb8aa3b, v75
	v_exp_f32_e32 v76, v76
	v_exp_f32_e32 v77, v77
	v_exp_f32_e32 v78, v78
	v_exp_f32_e32 v79, v79
	v_exp_f32_e32 v72, v72
	v_exp_f32_e32 v73, v73
	v_exp_f32_e32 v74, v74
	v_exp_f32_e32 v75, v75
	v_add_f32_e32 v76, 1.0, v76
	v_add_f32_e32 v77, 1.0, v77
	v_add_f32_e32 v78, 1.0, v78
	v_add_f32_e32 v79, 1.0, v79
	v_add_f32_e32 v72, 1.0, v72
	v_add_f32_e32 v73, 1.0, v73
	v_add_f32_e32 v74, 1.0, v74
	v_add_f32_e32 v75, 1.0, v75
	v_rcp_f32_e32 v76, v76
	v_rcp_f32_e32 v77, v77
	v_rcp_f32_e32 v78, v78
	v_rcp_f32_e32 v79, v79
	v_rcp_f32_e32 v72, v72
	v_rcp_f32_e32 v73, v73
	v_rcp_f32_e32 v74, v74
	v_rcp_f32_e32 v75, v75
	v_lshlrev_b32_e32 v127, 16, v236
	v_and_b32_e32 v236, 0xffff0000, v236
	v_lshlrev_b32_e32 v136, 16, v240
	v_and_b32_e32 v240, 0xffff0000, v240
	v_fmac_f32_e32 v136, v76, v127
	v_fmac_f32_e32 v240, v77, v236
	v_cvt_pk_bf16_f32 v240, v136, v240
	v_lshlrev_b32_e32 v127, 16, v237
	v_and_b32_e32 v237, 0xffff0000, v237
	v_lshlrev_b32_e32 v136, 16, v241
	v_and_b32_e32 v241, 0xffff0000, v241
	v_fmac_f32_e32 v136, v78, v127
	v_fmac_f32_e32 v241, v79, v237
	v_cvt_pk_bf16_f32 v241, v136, v241
	v_lshlrev_b32_e32 v127, 16, v238
	v_and_b32_e32 v238, 0xffff0000, v238
	v_lshlrev_b32_e32 v136, 16, v242
	v_and_b32_e32 v242, 0xffff0000, v242
	v_fmac_f32_e32 v136, v72, v127
	v_fmac_f32_e32 v242, v73, v238
	v_cvt_pk_bf16_f32 v242, v136, v242
	v_lshlrev_b32_e32 v127, 16, v239
	v_and_b32_e32 v239, 0xffff0000, v239
	v_lshlrev_b32_e32 v136, 16, v243
	v_and_b32_e32 v243, 0xffff0000, v243
	v_fmac_f32_e32 v136, v74, v127
	v_fmac_f32_e32 v243, v75, v239
	v_cvt_pk_bf16_f32 v243, v136, v243
	v_add_u32_e32 v126, 0x50000, v123
	global_store_dwordx4 v126, v[240:243], s[58:59]
	s_waitcnt vmcnt(23)
	v_add_f32_e32 v68, v68, v142
	v_add_f32_e32 v69, v69, v143
	v_add_f32_e32 v70, v70, v144
	v_add_f32_e32 v71, v71, v145
	v_add_f32_e32 v64, v64, v146
	v_add_f32_e32 v65, v65, v147
	v_add_f32_e32 v66, v66, v148
	v_add_f32_e32 v67, v67, v149
	v_mul_f32_e32 v68, 0xbfb8aa3b, v68
	v_mul_f32_e32 v69, 0xbfb8aa3b, v69
	v_mul_f32_e32 v70, 0xbfb8aa3b, v70
	v_mul_f32_e32 v71, 0xbfb8aa3b, v71
	v_mul_f32_e32 v64, 0xbfb8aa3b, v64
	v_mul_f32_e32 v65, 0xbfb8aa3b, v65
	v_mul_f32_e32 v66, 0xbfb8aa3b, v66
	v_mul_f32_e32 v67, 0xbfb8aa3b, v67
	v_exp_f32_e32 v68, v68
	v_exp_f32_e32 v69, v69
	v_exp_f32_e32 v70, v70
	v_exp_f32_e32 v71, v71
	v_exp_f32_e32 v64, v64
	v_exp_f32_e32 v65, v65
	v_exp_f32_e32 v66, v66
	v_exp_f32_e32 v67, v67
	v_add_f32_e32 v68, 1.0, v68
	v_add_f32_e32 v69, 1.0, v69
	v_add_f32_e32 v70, 1.0, v70
	v_add_f32_e32 v71, 1.0, v71
	v_add_f32_e32 v64, 1.0, v64
	v_add_f32_e32 v65, 1.0, v65
	v_add_f32_e32 v66, 1.0, v66
	v_add_f32_e32 v67, 1.0, v67
	v_rcp_f32_e32 v68, v68
	v_rcp_f32_e32 v69, v69
	v_rcp_f32_e32 v70, v70
	v_rcp_f32_e32 v71, v71
	v_rcp_f32_e32 v64, v64
	v_rcp_f32_e32 v65, v65
	v_rcp_f32_e32 v66, v66
	v_rcp_f32_e32 v67, v67
	v_lshlrev_b32_e32 v127, 16, v244
	v_and_b32_e32 v244, 0xffff0000, v244
	v_lshlrev_b32_e32 v136, 16, v248
	v_and_b32_e32 v248, 0xffff0000, v248
	v_fmac_f32_e32 v136, v68, v127
	v_fmac_f32_e32 v248, v69, v244
	v_cvt_pk_bf16_f32 v248, v136, v248
	v_lshlrev_b32_e32 v127, 16, v245
	v_and_b32_e32 v245, 0xffff0000, v245
	v_lshlrev_b32_e32 v136, 16, v249
	v_and_b32_e32 v249, 0xffff0000, v249
	v_fmac_f32_e32 v136, v70, v127
	v_fmac_f32_e32 v249, v71, v245
	v_cvt_pk_bf16_f32 v249, v136, v249
	v_lshlrev_b32_e32 v127, 16, v246
	v_and_b32_e32 v246, 0xffff0000, v246
	v_lshlrev_b32_e32 v136, 16, v250
	v_and_b32_e32 v250, 0xffff0000, v250
	v_fmac_f32_e32 v136, v64, v127
	v_fmac_f32_e32 v250, v65, v246
	v_cvt_pk_bf16_f32 v250, v136, v250
	v_lshlrev_b32_e32 v127, 16, v247
	v_and_b32_e32 v247, 0xffff0000, v247
	v_lshlrev_b32_e32 v136, 16, v251
	v_and_b32_e32 v251, 0xffff0000, v251
	v_fmac_f32_e32 v136, v66, v127
	v_fmac_f32_e32 v251, v67, v247
	v_cvt_pk_bf16_f32 v251, v136, v251
	v_add_u32_e32 v126, 0x58000, v123
	global_store_dwordx4 v126, v[248:251], s[58:59]
	s_waitcnt vmcnt(21)
	v_add_f32_e32 v60, v60, v150
	v_add_f32_e32 v61, v61, v151
	v_add_f32_e32 v62, v62, v152
	v_add_f32_e32 v63, v63, v153
	v_add_f32_e32 v56, v56, v154
	v_add_f32_e32 v57, v57, v155
	v_add_f32_e32 v58, v58, v156
	v_add_f32_e32 v59, v59, v157
	v_mul_f32_e32 v60, 0xbfb8aa3b, v60
	v_mul_f32_e32 v61, 0xbfb8aa3b, v61
	v_mul_f32_e32 v62, 0xbfb8aa3b, v62
	v_mul_f32_e32 v63, 0xbfb8aa3b, v63
	v_mul_f32_e32 v56, 0xbfb8aa3b, v56
	v_mul_f32_e32 v57, 0xbfb8aa3b, v57
	v_mul_f32_e32 v58, 0xbfb8aa3b, v58
	v_mul_f32_e32 v59, 0xbfb8aa3b, v59
	v_exp_f32_e32 v60, v60
	v_exp_f32_e32 v61, v61
	v_exp_f32_e32 v62, v62
	v_exp_f32_e32 v63, v63
	v_exp_f32_e32 v56, v56
	v_exp_f32_e32 v57, v57
	v_exp_f32_e32 v58, v58
	v_exp_f32_e32 v59, v59
	v_add_f32_e32 v60, 1.0, v60
	v_add_f32_e32 v61, 1.0, v61
	v_add_f32_e32 v62, 1.0, v62
	v_add_f32_e32 v63, 1.0, v63
	v_add_f32_e32 v56, 1.0, v56
	v_add_f32_e32 v57, 1.0, v57
	v_add_f32_e32 v58, 1.0, v58
	v_add_f32_e32 v59, 1.0, v59
	v_rcp_f32_e32 v60, v60
	v_rcp_f32_e32 v61, v61
	v_rcp_f32_e32 v62, v62
	v_rcp_f32_e32 v63, v63
	v_rcp_f32_e32 v56, v56
	v_rcp_f32_e32 v57, v57
	v_rcp_f32_e32 v58, v58
	v_rcp_f32_e32 v59, v59
	v_lshlrev_b32_e32 v127, 16, v252
	v_and_b32_e32 v252, 0xffff0000, v252
	v_lshlrev_b32_e32 v136, 16, v132
	v_and_b32_e32 v132, 0xffff0000, v132
	v_fmac_f32_e32 v136, v60, v127
	v_fmac_f32_e32 v132, v61, v252
	v_cvt_pk_bf16_f32 v132, v136, v132
	v_lshlrev_b32_e32 v127, 16, v253
	v_and_b32_e32 v253, 0xffff0000, v253
	v_lshlrev_b32_e32 v136, 16, v133
	v_and_b32_e32 v133, 0xffff0000, v133
	v_fmac_f32_e32 v136, v62, v127
	v_fmac_f32_e32 v133, v63, v253
	v_cvt_pk_bf16_f32 v133, v136, v133
	v_lshlrev_b32_e32 v127, 16, v254
	v_and_b32_e32 v254, 0xffff0000, v254
	v_lshlrev_b32_e32 v136, 16, v134
	v_and_b32_e32 v134, 0xffff0000, v134
	v_fmac_f32_e32 v136, v56, v127
	v_fmac_f32_e32 v134, v57, v254
	v_cvt_pk_bf16_f32 v134, v136, v134
	v_lshlrev_b32_e32 v127, 16, v255
	v_and_b32_e32 v255, 0xffff0000, v255
	v_lshlrev_b32_e32 v136, 16, v135
	v_and_b32_e32 v135, 0xffff0000, v135
	v_fmac_f32_e32 v136, v58, v127
	v_fmac_f32_e32 v135, v59, v255
	v_cvt_pk_bf16_f32 v135, v136, v135
	global_store_dwordx4 v123, v[132:135], s[58:59] offset:256
	s_waitcnt vmcnt(20)
	v_add_f32_e32 v52, v52, v150
	v_add_f32_e32 v53, v53, v151
	v_add_f32_e32 v54, v54, v152
	v_add_f32_e32 v55, v55, v153
	v_add_f32_e32 v48, v48, v154
	v_add_f32_e32 v49, v49, v155
	v_add_f32_e32 v50, v50, v156
	v_add_f32_e32 v51, v51, v157
	v_mul_f32_e32 v52, 0xbfb8aa3b, v52
	v_mul_f32_e32 v53, 0xbfb8aa3b, v53
	v_mul_f32_e32 v54, 0xbfb8aa3b, v54
	v_mul_f32_e32 v55, 0xbfb8aa3b, v55
	v_mul_f32_e32 v48, 0xbfb8aa3b, v48
	v_mul_f32_e32 v49, 0xbfb8aa3b, v49
	v_mul_f32_e32 v50, 0xbfb8aa3b, v50
	v_mul_f32_e32 v51, 0xbfb8aa3b, v51
	v_exp_f32_e32 v52, v52
	v_exp_f32_e32 v53, v53
	v_exp_f32_e32 v54, v54
	v_exp_f32_e32 v55, v55
	v_exp_f32_e32 v48, v48
	v_exp_f32_e32 v49, v49
	v_exp_f32_e32 v50, v50
	v_exp_f32_e32 v51, v51
	v_add_f32_e32 v52, 1.0, v52
	v_add_f32_e32 v53, 1.0, v53
	v_add_f32_e32 v54, 1.0, v54
	v_add_f32_e32 v55, 1.0, v55
	v_add_f32_e32 v48, 1.0, v48
	v_add_f32_e32 v49, 1.0, v49
	v_add_f32_e32 v50, 1.0, v50
	v_add_f32_e32 v51, 1.0, v51
	v_rcp_f32_e32 v52, v52
	v_rcp_f32_e32 v53, v53
	v_rcp_f32_e32 v54, v54
	v_rcp_f32_e32 v55, v55
	v_rcp_f32_e32 v48, v48
	v_rcp_f32_e32 v49, v49
	v_rcp_f32_e32 v50, v50
	v_rcp_f32_e32 v51, v51
	v_lshlrev_b32_e32 v127, 16, v128
	v_and_b32_e32 v128, 0xffff0000, v128
	v_lshlrev_b32_e32 v136, 16, v158
	v_and_b32_e32 v158, 0xffff0000, v158
	v_fmac_f32_e32 v136, v52, v127
	v_fmac_f32_e32 v158, v53, v128
	v_cvt_pk_bf16_f32 v158, v136, v158
	v_lshlrev_b32_e32 v127, 16, v129
	v_and_b32_e32 v129, 0xffff0000, v129
	v_lshlrev_b32_e32 v136, 16, v159
	v_and_b32_e32 v159, 0xffff0000, v159
	v_fmac_f32_e32 v136, v54, v127
	v_fmac_f32_e32 v159, v55, v129
	v_cvt_pk_bf16_f32 v159, v136, v159
	v_lshlrev_b32_e32 v127, 16, v130
	v_and_b32_e32 v130, 0xffff0000, v130
	v_lshlrev_b32_e32 v136, 16, v160
	v_and_b32_e32 v160, 0xffff0000, v160
	v_fmac_f32_e32 v136, v48, v127
	v_fmac_f32_e32 v160, v49, v130
	v_cvt_pk_bf16_f32 v160, v136, v160
	v_lshlrev_b32_e32 v127, 16, v131
	v_and_b32_e32 v131, 0xffff0000, v131
	v_lshlrev_b32_e32 v136, 16, v161
	v_and_b32_e32 v161, 0xffff0000, v161
	v_fmac_f32_e32 v136, v50, v127
	v_fmac_f32_e32 v161, v51, v131
	v_cvt_pk_bf16_f32 v161, v136, v161
	v_add_u32_e32 v126, 0x8000, v123
	global_store_dwordx4 v126, v[158:161], s[58:59] offset:256
	s_waitcnt vmcnt(18)
	v_add_f32_e32 v44, v44, v150
	v_add_f32_e32 v45, v45, v151
	v_add_f32_e32 v46, v46, v152
	v_add_f32_e32 v47, v47, v153
	v_add_f32_e32 v40, v40, v154
	v_add_f32_e32 v41, v41, v155
	v_add_f32_e32 v42, v42, v156
	v_add_f32_e32 v43, v43, v157
	v_mul_f32_e32 v44, 0xbfb8aa3b, v44
	v_mul_f32_e32 v45, 0xbfb8aa3b, v45
	v_mul_f32_e32 v46, 0xbfb8aa3b, v46
	v_mul_f32_e32 v47, 0xbfb8aa3b, v47
	v_mul_f32_e32 v40, 0xbfb8aa3b, v40
	v_mul_f32_e32 v41, 0xbfb8aa3b, v41
	v_mul_f32_e32 v42, 0xbfb8aa3b, v42
	v_mul_f32_e32 v43, 0xbfb8aa3b, v43
	v_exp_f32_e32 v44, v44
	v_exp_f32_e32 v45, v45
	v_exp_f32_e32 v46, v46
	v_exp_f32_e32 v47, v47
	v_exp_f32_e32 v40, v40
	v_exp_f32_e32 v41, v41
	v_exp_f32_e32 v42, v42
	v_exp_f32_e32 v43, v43
	v_add_f32_e32 v44, 1.0, v44
	v_add_f32_e32 v45, 1.0, v45
	v_add_f32_e32 v46, 1.0, v46
	v_add_f32_e32 v47, 1.0, v47
	v_add_f32_e32 v40, 1.0, v40
	v_add_f32_e32 v41, 1.0, v41
	v_add_f32_e32 v42, 1.0, v42
	v_add_f32_e32 v43, 1.0, v43
	v_rcp_f32_e32 v44, v44
	v_rcp_f32_e32 v45, v45
	v_rcp_f32_e32 v46, v46
	v_rcp_f32_e32 v47, v47
	v_rcp_f32_e32 v40, v40
	v_rcp_f32_e32 v41, v41
	v_rcp_f32_e32 v42, v42
	v_rcp_f32_e32 v43, v43
	v_lshlrev_b32_e32 v127, 16, v162
	v_and_b32_e32 v162, 0xffff0000, v162
	v_lshlrev_b32_e32 v136, 16, v116
	v_and_b32_e32 v116, 0xffff0000, v116
	v_fmac_f32_e32 v136, v44, v127
	v_fmac_f32_e32 v116, v45, v162
	v_cvt_pk_bf16_f32 v116, v136, v116
	v_lshlrev_b32_e32 v127, 16, v163
	v_and_b32_e32 v163, 0xffff0000, v163
	v_lshlrev_b32_e32 v136, 16, v117
	v_and_b32_e32 v117, 0xffff0000, v117
	v_fmac_f32_e32 v136, v46, v127
	v_fmac_f32_e32 v117, v47, v163
	v_cvt_pk_bf16_f32 v117, v136, v117
	v_lshlrev_b32_e32 v127, 16, v164
	v_and_b32_e32 v164, 0xffff0000, v164
	v_lshlrev_b32_e32 v136, 16, v118
	v_and_b32_e32 v118, 0xffff0000, v118
	v_fmac_f32_e32 v136, v40, v127
	v_fmac_f32_e32 v118, v41, v164
	v_cvt_pk_bf16_f32 v118, v136, v118
	v_lshlrev_b32_e32 v127, 16, v165
	v_and_b32_e32 v165, 0xffff0000, v165
	v_lshlrev_b32_e32 v136, 16, v119
	v_and_b32_e32 v119, 0xffff0000, v119
	v_fmac_f32_e32 v136, v42, v127
	v_fmac_f32_e32 v119, v43, v165
	v_cvt_pk_bf16_f32 v119, v136, v119
	v_add_u32_e32 v126, 0x10000, v123
	global_store_dwordx4 v126, v[116:119], s[58:59] offset:256
	s_waitcnt vmcnt(17)
	v_add_f32_e32 v36, v36, v150
	v_add_f32_e32 v37, v37, v151
	v_add_f32_e32 v38, v38, v152
	v_add_f32_e32 v39, v39, v153
	v_add_f32_e32 v32, v32, v154
	v_add_f32_e32 v33, v33, v155
	v_add_f32_e32 v34, v34, v156
	v_add_f32_e32 v35, v35, v157
	v_mul_f32_e32 v36, 0xbfb8aa3b, v36
	v_mul_f32_e32 v37, 0xbfb8aa3b, v37
	v_mul_f32_e32 v38, 0xbfb8aa3b, v38
	v_mul_f32_e32 v39, 0xbfb8aa3b, v39
	v_mul_f32_e32 v32, 0xbfb8aa3b, v32
	v_mul_f32_e32 v33, 0xbfb8aa3b, v33
	v_mul_f32_e32 v34, 0xbfb8aa3b, v34
	v_mul_f32_e32 v35, 0xbfb8aa3b, v35
	v_exp_f32_e32 v36, v36
	v_exp_f32_e32 v37, v37
	v_exp_f32_e32 v38, v38
	v_exp_f32_e32 v39, v39
	v_exp_f32_e32 v32, v32
	v_exp_f32_e32 v33, v33
	v_exp_f32_e32 v34, v34
	v_exp_f32_e32 v35, v35
	v_add_f32_e32 v36, 1.0, v36
	v_add_f32_e32 v37, 1.0, v37
	v_add_f32_e32 v38, 1.0, v38
	v_add_f32_e32 v39, 1.0, v39
	v_add_f32_e32 v32, 1.0, v32
	v_add_f32_e32 v33, 1.0, v33
	v_add_f32_e32 v34, 1.0, v34
	v_add_f32_e32 v35, 1.0, v35
	v_rcp_f32_e32 v36, v36
	v_rcp_f32_e32 v37, v37
	v_rcp_f32_e32 v38, v38
	v_rcp_f32_e32 v39, v39
	v_rcp_f32_e32 v32, v32
	v_rcp_f32_e32 v33, v33
	v_rcp_f32_e32 v34, v34
	v_rcp_f32_e32 v35, v35
	v_lshlrev_b32_e32 v127, 16, v112
	v_and_b32_e32 v112, 0xffff0000, v112
	v_lshlrev_b32_e32 v136, 16, v172
	v_and_b32_e32 v172, 0xffff0000, v172
	v_fmac_f32_e32 v136, v36, v127
	v_fmac_f32_e32 v172, v37, v112
	v_cvt_pk_bf16_f32 v172, v136, v172
	v_lshlrev_b32_e32 v127, 16, v113
	v_and_b32_e32 v113, 0xffff0000, v113
	v_lshlrev_b32_e32 v136, 16, v173
	v_and_b32_e32 v173, 0xffff0000, v173
	v_fmac_f32_e32 v136, v38, v127
	v_fmac_f32_e32 v173, v39, v113
	v_cvt_pk_bf16_f32 v173, v136, v173
	v_lshlrev_b32_e32 v127, 16, v114
	v_and_b32_e32 v114, 0xffff0000, v114
	v_lshlrev_b32_e32 v136, 16, v174
	v_and_b32_e32 v174, 0xffff0000, v174
	v_fmac_f32_e32 v136, v32, v127
	v_fmac_f32_e32 v174, v33, v114
	v_cvt_pk_bf16_f32 v174, v136, v174
	v_lshlrev_b32_e32 v127, 16, v115
	v_and_b32_e32 v115, 0xffff0000, v115
	v_lshlrev_b32_e32 v136, 16, v175
	v_and_b32_e32 v175, 0xffff0000, v175
	v_fmac_f32_e32 v136, v34, v127
	v_fmac_f32_e32 v175, v35, v115
	v_cvt_pk_bf16_f32 v175, v136, v175
	v_add_u32_e32 v126, 0x18000, v123
	global_store_dwordx4 v126, v[172:175], s[58:59] offset:256
	s_waitcnt vmcnt(15)
	v_add_f32_e32 v28, v28, v150
	v_add_f32_e32 v29, v29, v151
	v_add_f32_e32 v30, v30, v152
	v_add_f32_e32 v31, v31, v153
	v_add_f32_e32 v24, v24, v154
	v_add_f32_e32 v25, v25, v155
	v_add_f32_e32 v26, v26, v156
	v_add_f32_e32 v27, v27, v157
	v_mul_f32_e32 v28, 0xbfb8aa3b, v28
	v_mul_f32_e32 v29, 0xbfb8aa3b, v29
	v_mul_f32_e32 v30, 0xbfb8aa3b, v30
	v_mul_f32_e32 v31, 0xbfb8aa3b, v31
	v_mul_f32_e32 v24, 0xbfb8aa3b, v24
	v_mul_f32_e32 v25, 0xbfb8aa3b, v25
	v_mul_f32_e32 v26, 0xbfb8aa3b, v26
	v_mul_f32_e32 v27, 0xbfb8aa3b, v27
	v_exp_f32_e32 v28, v28
	v_exp_f32_e32 v29, v29
	v_exp_f32_e32 v30, v30
	v_exp_f32_e32 v31, v31
	v_exp_f32_e32 v24, v24
	v_exp_f32_e32 v25, v25
	v_exp_f32_e32 v26, v26
	v_exp_f32_e32 v27, v27
	v_add_f32_e32 v28, 1.0, v28
	v_add_f32_e32 v29, 1.0, v29
	v_add_f32_e32 v30, 1.0, v30
	v_add_f32_e32 v31, 1.0, v31
	v_add_f32_e32 v24, 1.0, v24
	v_add_f32_e32 v25, 1.0, v25
	v_add_f32_e32 v26, 1.0, v26
	v_add_f32_e32 v27, 1.0, v27
	v_rcp_f32_e32 v28, v28
	v_rcp_f32_e32 v29, v29
	v_rcp_f32_e32 v30, v30
	v_rcp_f32_e32 v31, v31
	v_rcp_f32_e32 v24, v24
	v_rcp_f32_e32 v25, v25
	v_rcp_f32_e32 v26, v26
	v_rcp_f32_e32 v27, v27
	v_lshlrev_b32_e32 v127, 16, v176
	v_and_b32_e32 v176, 0xffff0000, v176
	v_lshlrev_b32_e32 v136, 16, v108
	v_and_b32_e32 v108, 0xffff0000, v108
	v_fmac_f32_e32 v136, v28, v127
	v_fmac_f32_e32 v108, v29, v176
	v_cvt_pk_bf16_f32 v108, v136, v108
	v_lshlrev_b32_e32 v127, 16, v177
	v_and_b32_e32 v177, 0xffff0000, v177
	v_lshlrev_b32_e32 v136, 16, v109
	v_and_b32_e32 v109, 0xffff0000, v109
	v_fmac_f32_e32 v136, v30, v127
	v_fmac_f32_e32 v109, v31, v177
	v_cvt_pk_bf16_f32 v109, v136, v109
	v_lshlrev_b32_e32 v127, 16, v178
	v_and_b32_e32 v178, 0xffff0000, v178
	v_lshlrev_b32_e32 v136, 16, v110
	v_and_b32_e32 v110, 0xffff0000, v110
	v_fmac_f32_e32 v136, v24, v127
	v_fmac_f32_e32 v110, v25, v178
	v_cvt_pk_bf16_f32 v110, v136, v110
	v_lshlrev_b32_e32 v127, 16, v179
	v_and_b32_e32 v179, 0xffff0000, v179
	v_lshlrev_b32_e32 v136, 16, v111
	v_and_b32_e32 v111, 0xffff0000, v111
	v_fmac_f32_e32 v136, v26, v127
	v_fmac_f32_e32 v111, v27, v179
	v_cvt_pk_bf16_f32 v111, v136, v111
	v_add_u32_e32 v126, 0x40000, v123
	global_store_dwordx4 v126, v[108:111], s[58:59] offset:256
	s_waitcnt vmcnt(14)
	v_add_f32_e32 v20, v20, v150
	v_add_f32_e32 v21, v21, v151
	v_add_f32_e32 v22, v22, v152
	v_add_f32_e32 v23, v23, v153
	v_add_f32_e32 v16, v16, v154
	v_add_f32_e32 v17, v17, v155
	v_add_f32_e32 v18, v18, v156
	v_add_f32_e32 v19, v19, v157
	v_mul_f32_e32 v20, 0xbfb8aa3b, v20
	v_mul_f32_e32 v21, 0xbfb8aa3b, v21
	v_mul_f32_e32 v22, 0xbfb8aa3b, v22
	v_mul_f32_e32 v23, 0xbfb8aa3b, v23
	v_mul_f32_e32 v16, 0xbfb8aa3b, v16
	v_mul_f32_e32 v17, 0xbfb8aa3b, v17
	v_mul_f32_e32 v18, 0xbfb8aa3b, v18
	v_mul_f32_e32 v19, 0xbfb8aa3b, v19
	v_exp_f32_e32 v20, v20
	v_exp_f32_e32 v21, v21
	v_exp_f32_e32 v22, v22
	v_exp_f32_e32 v23, v23
	v_exp_f32_e32 v16, v16
	v_exp_f32_e32 v17, v17
	v_exp_f32_e32 v18, v18
	v_exp_f32_e32 v19, v19
	v_add_f32_e32 v20, 1.0, v20
	v_add_f32_e32 v21, 1.0, v21
	v_add_f32_e32 v22, 1.0, v22
	v_add_f32_e32 v23, 1.0, v23
	v_add_f32_e32 v16, 1.0, v16
	v_add_f32_e32 v17, 1.0, v17
	v_add_f32_e32 v18, 1.0, v18
	v_add_f32_e32 v19, 1.0, v19
	v_rcp_f32_e32 v20, v20
	v_rcp_f32_e32 v21, v21
	v_rcp_f32_e32 v22, v22
	v_rcp_f32_e32 v23, v23
	v_rcp_f32_e32 v16, v16
	v_rcp_f32_e32 v17, v17
	v_rcp_f32_e32 v18, v18
	v_rcp_f32_e32 v19, v19
	v_lshlrev_b32_e32 v127, 16, v104
	v_and_b32_e32 v104, 0xffff0000, v104
	v_lshlrev_b32_e32 v136, 16, v180
	v_and_b32_e32 v180, 0xffff0000, v180
	v_fmac_f32_e32 v136, v20, v127
	v_fmac_f32_e32 v180, v21, v104
	v_cvt_pk_bf16_f32 v180, v136, v180
	v_lshlrev_b32_e32 v127, 16, v105
	v_and_b32_e32 v105, 0xffff0000, v105
	v_lshlrev_b32_e32 v136, 16, v181
	v_and_b32_e32 v181, 0xffff0000, v181
	v_fmac_f32_e32 v136, v22, v127
	v_fmac_f32_e32 v181, v23, v105
	v_cvt_pk_bf16_f32 v181, v136, v181
	v_lshlrev_b32_e32 v127, 16, v106
	v_and_b32_e32 v106, 0xffff0000, v106
	v_lshlrev_b32_e32 v136, 16, v182
	v_and_b32_e32 v182, 0xffff0000, v182
	v_fmac_f32_e32 v136, v16, v127
	v_fmac_f32_e32 v182, v17, v106
	v_cvt_pk_bf16_f32 v182, v136, v182
	v_lshlrev_b32_e32 v127, 16, v107
	v_and_b32_e32 v107, 0xffff0000, v107
	v_lshlrev_b32_e32 v136, 16, v183
	v_and_b32_e32 v183, 0xffff0000, v183
	v_fmac_f32_e32 v136, v18, v127
	v_fmac_f32_e32 v183, v19, v107
	v_cvt_pk_bf16_f32 v183, v136, v183
	v_add_u32_e32 v126, 0x48000, v123
	global_store_dwordx4 v126, v[180:183], s[58:59] offset:256
	s_waitcnt vmcnt(12)
	v_add_f32_e32 v12, v12, v150
	v_add_f32_e32 v13, v13, v151
	v_add_f32_e32 v14, v14, v152
	v_add_f32_e32 v15, v15, v153
	v_add_f32_e32 v8, v8, v154
	v_add_f32_e32 v9, v9, v155
	v_add_f32_e32 v10, v10, v156
	v_add_f32_e32 v11, v11, v157
	v_mul_f32_e32 v12, 0xbfb8aa3b, v12
	v_mul_f32_e32 v13, 0xbfb8aa3b, v13
	v_mul_f32_e32 v14, 0xbfb8aa3b, v14
	v_mul_f32_e32 v15, 0xbfb8aa3b, v15
	v_mul_f32_e32 v8, 0xbfb8aa3b, v8
	v_mul_f32_e32 v9, 0xbfb8aa3b, v9
	v_mul_f32_e32 v10, 0xbfb8aa3b, v10
	v_mul_f32_e32 v11, 0xbfb8aa3b, v11
	v_exp_f32_e32 v12, v12
	v_exp_f32_e32 v13, v13
	v_exp_f32_e32 v14, v14
	v_exp_f32_e32 v15, v15
	v_exp_f32_e32 v8, v8
	v_exp_f32_e32 v9, v9
	v_exp_f32_e32 v10, v10
	v_exp_f32_e32 v11, v11
	v_add_f32_e32 v12, 1.0, v12
	v_add_f32_e32 v13, 1.0, v13
	v_add_f32_e32 v14, 1.0, v14
	v_add_f32_e32 v15, 1.0, v15
	v_add_f32_e32 v8, 1.0, v8
	v_add_f32_e32 v9, 1.0, v9
	v_add_f32_e32 v10, 1.0, v10
	v_add_f32_e32 v11, 1.0, v11
	v_rcp_f32_e32 v12, v12
	v_rcp_f32_e32 v13, v13
	v_rcp_f32_e32 v14, v14
	v_rcp_f32_e32 v15, v15
	v_rcp_f32_e32 v8, v8
	v_rcp_f32_e32 v9, v9
	v_rcp_f32_e32 v10, v10
	v_rcp_f32_e32 v11, v11
	v_lshlrev_b32_e32 v127, 16, v184
	v_and_b32_e32 v184, 0xffff0000, v184
	v_lshlrev_b32_e32 v136, 16, v100
	v_and_b32_e32 v100, 0xffff0000, v100
	v_fmac_f32_e32 v136, v12, v127
	v_fmac_f32_e32 v100, v13, v184
	v_cvt_pk_bf16_f32 v100, v136, v100
	v_lshlrev_b32_e32 v127, 16, v185
	v_and_b32_e32 v185, 0xffff0000, v185
	v_lshlrev_b32_e32 v136, 16, v101
	v_and_b32_e32 v101, 0xffff0000, v101
	v_fmac_f32_e32 v136, v14, v127
	v_fmac_f32_e32 v101, v15, v185
	v_cvt_pk_bf16_f32 v101, v136, v101
	v_lshlrev_b32_e32 v127, 16, v186
	v_and_b32_e32 v186, 0xffff0000, v186
	v_lshlrev_b32_e32 v136, 16, v102
	v_and_b32_e32 v102, 0xffff0000, v102
	v_fmac_f32_e32 v136, v8, v127
	v_fmac_f32_e32 v102, v9, v186
	v_cvt_pk_bf16_f32 v102, v136, v102
	v_lshlrev_b32_e32 v127, 16, v187
	v_and_b32_e32 v187, 0xffff0000, v187
	v_lshlrev_b32_e32 v136, 16, v103
	v_and_b32_e32 v103, 0xffff0000, v103
	v_fmac_f32_e32 v136, v10, v127
	v_fmac_f32_e32 v103, v11, v187
	v_cvt_pk_bf16_f32 v103, v136, v103
	v_add_u32_e32 v126, 0x50000, v123
	global_store_dwordx4 v126, v[100:103], s[58:59] offset:256
	s_waitcnt vmcnt(11)
	v_add_f32_e32 v4, v4, v150
	v_add_f32_e32 v5, v5, v151
	v_add_f32_e32 v6, v6, v152
	v_add_f32_e32 v7, v7, v153
	v_add_f32_e32 v0, v0, v154
	v_add_f32_e32 v1, v1, v155
	v_add_f32_e32 v2, v2, v156
	v_add_f32_e32 v3, v3, v157
	v_mul_f32_e32 v4, 0xbfb8aa3b, v4
	v_mul_f32_e32 v5, 0xbfb8aa3b, v5
	v_mul_f32_e32 v6, 0xbfb8aa3b, v6
	v_mul_f32_e32 v7, 0xbfb8aa3b, v7
	v_mul_f32_e32 v0, 0xbfb8aa3b, v0
	v_mul_f32_e32 v1, 0xbfb8aa3b, v1
	v_mul_f32_e32 v2, 0xbfb8aa3b, v2
	v_mul_f32_e32 v3, 0xbfb8aa3b, v3
	v_exp_f32_e32 v4, v4
	v_exp_f32_e32 v5, v5
	v_exp_f32_e32 v6, v6
	v_exp_f32_e32 v7, v7
	v_exp_f32_e32 v0, v0
	v_exp_f32_e32 v1, v1
	v_exp_f32_e32 v2, v2
	v_exp_f32_e32 v3, v3
	v_add_f32_e32 v4, 1.0, v4
	v_add_f32_e32 v5, 1.0, v5
	v_add_f32_e32 v6, 1.0, v6
	v_add_f32_e32 v7, 1.0, v7
	v_add_f32_e32 v0, 1.0, v0
	v_add_f32_e32 v1, 1.0, v1
	v_add_f32_e32 v2, 1.0, v2
	v_add_f32_e32 v3, 1.0, v3
	v_rcp_f32_e32 v4, v4
	v_rcp_f32_e32 v5, v5
	v_rcp_f32_e32 v6, v6
	v_rcp_f32_e32 v7, v7
	v_rcp_f32_e32 v0, v0
	v_rcp_f32_e32 v1, v1
	v_rcp_f32_e32 v2, v2
	v_rcp_f32_e32 v3, v3
	v_lshlrev_b32_e32 v127, 16, v96
	v_and_b32_e32 v96, 0xffff0000, v96
	v_lshlrev_b32_e32 v136, 16, v188
	v_and_b32_e32 v188, 0xffff0000, v188
	v_fmac_f32_e32 v136, v4, v127
	v_fmac_f32_e32 v188, v5, v96
	v_cvt_pk_bf16_f32 v188, v136, v188
	v_lshlrev_b32_e32 v127, 16, v97
	v_and_b32_e32 v97, 0xffff0000, v97
	v_lshlrev_b32_e32 v136, 16, v189
	v_and_b32_e32 v189, 0xffff0000, v189
	v_fmac_f32_e32 v136, v6, v127
	v_fmac_f32_e32 v189, v7, v97
	v_cvt_pk_bf16_f32 v189, v136, v189
	v_lshlrev_b32_e32 v127, 16, v98
	v_and_b32_e32 v98, 0xffff0000, v98
	v_lshlrev_b32_e32 v136, 16, v190
	v_and_b32_e32 v190, 0xffff0000, v190
	v_fmac_f32_e32 v136, v0, v127
	v_fmac_f32_e32 v190, v1, v98
	v_cvt_pk_bf16_f32 v190, v136, v190
	v_lshlrev_b32_e32 v127, 16, v99
	v_and_b32_e32 v99, 0xffff0000, v99
	v_lshlrev_b32_e32 v136, 16, v191
	v_and_b32_e32 v191, 0xffff0000, v191
	v_fmac_f32_e32 v136, v2, v127
	v_fmac_f32_e32 v191, v3, v99
	v_cvt_pk_bf16_f32 v191, v136, v191
	v_add_u32_e32 v126, 0x58000, v123
	global_store_dwordx4 v126, v[188:191], s[58:59] offset:256
	s_branch .Lgate_epi_done
.Lgate_epi_b0:
	v_lshl_add_u32 v120, s10, 8, v212
	s_lshl_b32 s10, s38, 8
	v_or_b32_e32 v121, s10, v213
	v_lshlrev_b32_e32 v124, 2, v121
	global_load_dwordx4 v[142:145], v124, s[66:67]
	global_load_dwordx4 v[146:149], v124, s[66:67] offset:16
	global_load_dwordx4 v[150:153], v124, s[66:67] offset:512
	global_load_dwordx4 v[154:157], v124, s[66:67] offset:528
	v_lshlrev_b32_e32 v122, 13, v120
	v_lshl_add_u32 v122, v121, 1, v122
	v_and_b32_e32 v121, 0x3ff, v121
	v_lshlrev_b32_e32 v123, 11, v120
	v_lshl_add_u32 v123, v121, 1, v123
	v_mov_b32_e32 v138, 0xbfb8aa3b
	v_mov_b32_e32 v140, 1.0
	global_load_dwordx4 v[158:161], v122, s[54:55]
	v_add_u32_e32 v125, 0x20000, v122
	global_load_dwordx4 v[162:165], v125, s[54:55]
	v_add_u32_e32 v125, 0x40000, v122
	global_load_dwordx4 v[172:175], v125, s[54:55]
	v_add_u32_e32 v125, 0x60000, v122
	global_load_dwordx4 v[176:179], v125, s[54:55]
	v_add_u32_e32 v125, 0x100000, v122
	global_load_dwordx4 v[180:183], v125, s[54:55]
	v_add_u32_e32 v125, 0x120000, v122
	global_load_dwordx4 v[184:187], v125, s[54:55]
	v_add_u32_e32 v125, 0x140000, v122
	global_load_dwordx4 v[188:191], v125, s[54:55]
	v_add_u32_e32 v125, 0x160000, v122
	global_load_dwordx4 v[192:195], v125, s[54:55]
	global_load_dwordx4 v[216:219], v122, s[54:55] offset:256
	v_add_u32_e32 v125, 0x20000, v122
	global_load_dwordx4 v[220:223], v125, s[54:55] offset:256
	v_add_u32_e32 v125, 0x40000, v122
	global_load_dwordx4 v[224:227], v125, s[54:55] offset:256
	v_add_u32_e32 v125, 0x60000, v122
	global_load_dwordx4 v[228:231], v125, s[54:55] offset:256
	v_add_u32_e32 v125, 0x100000, v122
	global_load_dwordx4 v[236:239], v125, s[54:55] offset:256
	v_add_u32_e32 v125, 0x120000, v122
	global_load_dwordx4 v[240:243], v125, s[54:55] offset:256
	v_add_u32_e32 v125, 0x140000, v122
	global_load_dwordx4 v[244:247], v125, s[54:55] offset:256
	v_add_u32_e32 v125, 0x160000, v122
	global_load_dwordx4 v[248:251], v125, s[54:55] offset:256
	s_waitcnt vmcnt(15)
	v_add_f32_e32 v132, v132, v142
	v_add_f32_e32 v133, v133, v143
	v_add_f32_e32 v134, v134, v144
	v_add_f32_e32 v135, v135, v145
	v_add_f32_e32 v128, v128, v146
	v_add_f32_e32 v129, v129, v147
	v_add_f32_e32 v130, v130, v148
	v_add_f32_e32 v131, v131, v149
	v_mul_f32_e32 v132, 0xbfb8aa3b, v132
	v_mul_f32_e32 v133, 0xbfb8aa3b, v133
	v_mul_f32_e32 v134, 0xbfb8aa3b, v134
	v_mul_f32_e32 v135, 0xbfb8aa3b, v135
	v_mul_f32_e32 v128, 0xbfb8aa3b, v128
	v_mul_f32_e32 v129, 0xbfb8aa3b, v129
	v_mul_f32_e32 v130, 0xbfb8aa3b, v130
	v_mul_f32_e32 v131, 0xbfb8aa3b, v131
	v_exp_f32_e32 v132, v132
	v_exp_f32_e32 v133, v133
	v_exp_f32_e32 v134, v134
	v_exp_f32_e32 v135, v135
	v_exp_f32_e32 v128, v128
	v_exp_f32_e32 v129, v129
	v_exp_f32_e32 v130, v130
	v_exp_f32_e32 v131, v131
	v_add_f32_e32 v132, 1.0, v132
	v_add_f32_e32 v133, 1.0, v133
	v_add_f32_e32 v134, 1.0, v134
	v_add_f32_e32 v135, 1.0, v135
	v_add_f32_e32 v128, 1.0, v128
	v_add_f32_e32 v129, 1.0, v129
	v_add_f32_e32 v130, 1.0, v130
	v_add_f32_e32 v131, 1.0, v131
	v_rcp_f32_e32 v132, v132
	v_rcp_f32_e32 v133, v133
	v_rcp_f32_e32 v134, v134
	v_rcp_f32_e32 v135, v135
	v_rcp_f32_e32 v128, v128
	v_rcp_f32_e32 v129, v129
	v_rcp_f32_e32 v130, v130
	v_rcp_f32_e32 v131, v131
	v_lshlrev_b32_e32 v127, 16, v158
	v_and_b32_e32 v158, 0xffff0000, v158
	v_mul_f32_e32 v127, v132, v127
	v_mul_f32_e32 v158, v133, v158
	v_cvt_pk_bf16_f32 v158, v127, v158
	v_lshlrev_b32_e32 v127, 16, v159
	v_and_b32_e32 v159, 0xffff0000, v159
	v_mul_f32_e32 v127, v134, v127
	v_mul_f32_e32 v159, v135, v159
	v_cvt_pk_bf16_f32 v159, v127, v159
	v_lshlrev_b32_e32 v127, 16, v160
	v_and_b32_e32 v160, 0xffff0000, v160
	v_mul_f32_e32 v127, v128, v127
	v_mul_f32_e32 v160, v129, v160
	v_cvt_pk_bf16_f32 v160, v127, v160
	v_lshlrev_b32_e32 v127, 16, v161
	v_and_b32_e32 v161, 0xffff0000, v161
	v_mul_f32_e32 v127, v130, v127
	v_mul_f32_e32 v161, v131, v161
	v_cvt_pk_bf16_f32 v161, v127, v161
	global_store_dwordx4 v123, v[158:161], s[58:59]
	s_waitcnt vmcnt(15)
	v_add_f32_e32 v116, v116, v142
	v_add_f32_e32 v117, v117, v143
	v_add_f32_e32 v118, v118, v144
	v_add_f32_e32 v119, v119, v145
	v_add_f32_e32 v112, v112, v146
	v_add_f32_e32 v113, v113, v147
	v_add_f32_e32 v114, v114, v148
	v_add_f32_e32 v115, v115, v149
	v_mul_f32_e32 v116, 0xbfb8aa3b, v116
	v_mul_f32_e32 v117, 0xbfb8aa3b, v117
	v_mul_f32_e32 v118, 0xbfb8aa3b, v118
	v_mul_f32_e32 v119, 0xbfb8aa3b, v119
	v_mul_f32_e32 v112, 0xbfb8aa3b, v112
	v_mul_f32_e32 v113, 0xbfb8aa3b, v113
	v_mul_f32_e32 v114, 0xbfb8aa3b, v114
	v_mul_f32_e32 v115, 0xbfb8aa3b, v115
	v_exp_f32_e32 v116, v116
	v_exp_f32_e32 v117, v117
	v_exp_f32_e32 v118, v118
	v_exp_f32_e32 v119, v119
	v_exp_f32_e32 v112, v112
	v_exp_f32_e32 v113, v113
	v_exp_f32_e32 v114, v114
	v_exp_f32_e32 v115, v115
	v_add_f32_e32 v116, 1.0, v116
	v_add_f32_e32 v117, 1.0, v117
	v_add_f32_e32 v118, 1.0, v118
	v_add_f32_e32 v119, 1.0, v119
	v_add_f32_e32 v112, 1.0, v112
	v_add_f32_e32 v113, 1.0, v113
	v_add_f32_e32 v114, 1.0, v114
	v_add_f32_e32 v115, 1.0, v115
	v_rcp_f32_e32 v116, v116
	v_rcp_f32_e32 v117, v117
	v_rcp_f32_e32 v118, v118
	v_rcp_f32_e32 v119, v119
	v_rcp_f32_e32 v112, v112
	v_rcp_f32_e32 v113, v113
	v_rcp_f32_e32 v114, v114
	v_rcp_f32_e32 v115, v115
	v_lshlrev_b32_e32 v127, 16, v162
	v_and_b32_e32 v162, 0xffff0000, v162
	v_mul_f32_e32 v127, v116, v127
	v_mul_f32_e32 v162, v117, v162
	v_cvt_pk_bf16_f32 v162, v127, v162
	v_lshlrev_b32_e32 v127, 16, v163
	v_and_b32_e32 v163, 0xffff0000, v163
	v_mul_f32_e32 v127, v118, v127
	v_mul_f32_e32 v163, v119, v163
	v_cvt_pk_bf16_f32 v163, v127, v163
	v_lshlrev_b32_e32 v127, 16, v164
	v_and_b32_e32 v164, 0xffff0000, v164
	v_mul_f32_e32 v127, v112, v127
	v_mul_f32_e32 v164, v113, v164
	v_cvt_pk_bf16_f32 v164, v127, v164
	v_lshlrev_b32_e32 v127, 16, v165
	v_and_b32_e32 v165, 0xffff0000, v165
	v_mul_f32_e32 v127, v114, v127
	v_mul_f32_e32 v165, v115, v165
	v_cvt_pk_bf16_f32 v165, v127, v165
	v_add_u32_e32 v126, 0x8000, v123
	global_store_dwordx4 v126, v[162:165], s[58:59]
	s_waitcnt vmcnt(15)
	v_add_f32_e32 v108, v108, v142
	v_add_f32_e32 v109, v109, v143
	v_add_f32_e32 v110, v110, v144
	v_add_f32_e32 v111, v111, v145
	v_add_f32_e32 v104, v104, v146
	v_add_f32_e32 v105, v105, v147
	v_add_f32_e32 v106, v106, v148
	v_add_f32_e32 v107, v107, v149
	v_mul_f32_e32 v108, 0xbfb8aa3b, v108
	v_mul_f32_e32 v109, 0xbfb8aa3b, v109
	v_mul_f32_e32 v110, 0xbfb8aa3b, v110
	v_mul_f32_e32 v111, 0xbfb8aa3b, v111
	v_mul_f32_e32 v104, 0xbfb8aa3b, v104
	v_mul_f32_e32 v105, 0xbfb8aa3b, v105
	v_mul_f32_e32 v106, 0xbfb8aa3b, v106
	v_mul_f32_e32 v107, 0xbfb8aa3b, v107
	v_exp_f32_e32 v108, v108
	v_exp_f32_e32 v109, v109
	v_exp_f32_e32 v110, v110
	v_exp_f32_e32 v111, v111
	v_exp_f32_e32 v104, v104
	v_exp_f32_e32 v105, v105
	v_exp_f32_e32 v106, v106
	v_exp_f32_e32 v107, v107
	v_add_f32_e32 v108, 1.0, v108
	v_add_f32_e32 v109, 1.0, v109
	v_add_f32_e32 v110, 1.0, v110
	v_add_f32_e32 v111, 1.0, v111
	v_add_f32_e32 v104, 1.0, v104
	v_add_f32_e32 v105, 1.0, v105
	v_add_f32_e32 v106, 1.0, v106
	v_add_f32_e32 v107, 1.0, v107
	v_rcp_f32_e32 v108, v108
	v_rcp_f32_e32 v109, v109
	v_rcp_f32_e32 v110, v110
	v_rcp_f32_e32 v111, v111
	v_rcp_f32_e32 v104, v104
	v_rcp_f32_e32 v105, v105
	v_rcp_f32_e32 v106, v106
	v_rcp_f32_e32 v107, v107
	v_lshlrev_b32_e32 v127, 16, v172
	v_and_b32_e32 v172, 0xffff0000, v172
	v_mul_f32_e32 v127, v108, v127
	v_mul_f32_e32 v172, v109, v172
	v_cvt_pk_bf16_f32 v172, v127, v172
	v_lshlrev_b32_e32 v127, 16, v173
	v_and_b32_e32 v173, 0xffff0000, v173
	v_mul_f32_e32 v127, v110, v127
	v_mul_f32_e32 v173, v111, v173
	v_cvt_pk_bf16_f32 v173, v127, v173
	v_lshlrev_b32_e32 v127, 16, v174
	v_and_b32_e32 v174, 0xffff0000, v174
	v_mul_f32_e32 v127, v104, v127
	v_mul_f32_e32 v174, v105, v174
	v_cvt_pk_bf16_f32 v174, v127, v174
	v_lshlrev_b32_e32 v127, 16, v175
	v_and_b32_e32 v175, 0xffff0000, v175
	v_mul_f32_e32 v127, v106, v127
	v_mul_f32_e32 v175, v107, v175
	v_cvt_pk_bf16_f32 v175, v127, v175
	v_add_u32_e32 v126, 0x10000, v123
	global_store_dwordx4 v126, v[172:175], s[58:59]
	s_waitcnt vmcnt(15)
	v_add_f32_e32 v100, v100, v142
	v_add_f32_e32 v101, v101, v143
	v_add_f32_e32 v102, v102, v144
	v_add_f32_e32 v103, v103, v145
	v_add_f32_e32 v96, v96, v146
	v_add_f32_e32 v97, v97, v147
	v_add_f32_e32 v98, v98, v148
	v_add_f32_e32 v99, v99, v149
	v_mul_f32_e32 v100, 0xbfb8aa3b, v100
	v_mul_f32_e32 v101, 0xbfb8aa3b, v101
	v_mul_f32_e32 v102, 0xbfb8aa3b, v102
	v_mul_f32_e32 v103, 0xbfb8aa3b, v103
	v_mul_f32_e32 v96, 0xbfb8aa3b, v96
	v_mul_f32_e32 v97, 0xbfb8aa3b, v97
	v_mul_f32_e32 v98, 0xbfb8aa3b, v98
	v_mul_f32_e32 v99, 0xbfb8aa3b, v99
	v_exp_f32_e32 v100, v100
	v_exp_f32_e32 v101, v101
	v_exp_f32_e32 v102, v102
	v_exp_f32_e32 v103, v103
	v_exp_f32_e32 v96, v96
	v_exp_f32_e32 v97, v97
	v_exp_f32_e32 v98, v98
	v_exp_f32_e32 v99, v99
	v_add_f32_e32 v100, 1.0, v100
	v_add_f32_e32 v101, 1.0, v101
	v_add_f32_e32 v102, 1.0, v102
	v_add_f32_e32 v103, 1.0, v103
	v_add_f32_e32 v96, 1.0, v96
	v_add_f32_e32 v97, 1.0, v97
	v_add_f32_e32 v98, 1.0, v98
	v_add_f32_e32 v99, 1.0, v99
	v_rcp_f32_e32 v100, v100
	v_rcp_f32_e32 v101, v101
	v_rcp_f32_e32 v102, v102
	v_rcp_f32_e32 v103, v103
	v_rcp_f32_e32 v96, v96
	v_rcp_f32_e32 v97, v97
	v_rcp_f32_e32 v98, v98
	v_rcp_f32_e32 v99, v99
	v_lshlrev_b32_e32 v127, 16, v176
	v_and_b32_e32 v176, 0xffff0000, v176
	v_mul_f32_e32 v127, v100, v127
	v_mul_f32_e32 v176, v101, v176
	v_cvt_pk_bf16_f32 v176, v127, v176
	v_lshlrev_b32_e32 v127, 16, v177
	v_and_b32_e32 v177, 0xffff0000, v177
	v_mul_f32_e32 v127, v102, v127
	v_mul_f32_e32 v177, v103, v177
	v_cvt_pk_bf16_f32 v177, v127, v177
	v_lshlrev_b32_e32 v127, 16, v178
	v_and_b32_e32 v178, 0xffff0000, v178
	v_mul_f32_e32 v127, v96, v127
	v_mul_f32_e32 v178, v97, v178
	v_cvt_pk_bf16_f32 v178, v127, v178
	v_lshlrev_b32_e32 v127, 16, v179
	v_and_b32_e32 v179, 0xffff0000, v179
	v_mul_f32_e32 v127, v98, v127
	v_mul_f32_e32 v179, v99, v179
	v_cvt_pk_bf16_f32 v179, v127, v179
	v_add_u32_e32 v126, 0x18000, v123
	global_store_dwordx4 v126, v[176:179], s[58:59]
	s_waitcnt vmcnt(15)
	v_add_f32_e32 v92, v92, v142
	v_add_f32_e32 v93, v93, v143
	v_add_f32_e32 v94, v94, v144
	v_add_f32_e32 v95, v95, v145
	v_add_f32_e32 v88, v88, v146
	v_add_f32_e32 v89, v89, v147
	v_add_f32_e32 v90, v90, v148
	v_add_f32_e32 v91, v91, v149
	v_mul_f32_e32 v92, 0xbfb8aa3b, v92
	v_mul_f32_e32 v93, 0xbfb8aa3b, v93
	v_mul_f32_e32 v94, 0xbfb8aa3b, v94
	v_mul_f32_e32 v95, 0xbfb8aa3b, v95
	v_mul_f32_e32 v88, 0xbfb8aa3b, v88
	v_mul_f32_e32 v89, 0xbfb8aa3b, v89
	v_mul_f32_e32 v90, 0xbfb8aa3b, v90
	v_mul_f32_e32 v91, 0xbfb8aa3b, v91
	v_exp_f32_e32 v92, v92
	v_exp_f32_e32 v93, v93
	v_exp_f32_e32 v94, v94
	v_exp_f32_e32 v95, v95
	v_exp_f32_e32 v88, v88
	v_exp_f32_e32 v89, v89
	v_exp_f32_e32 v90, v90
	v_exp_f32_e32 v91, v91
	v_add_f32_e32 v92, 1.0, v92
	v_add_f32_e32 v93, 1.0, v93
	v_add_f32_e32 v94, 1.0, v94
	v_add_f32_e32 v95, 1.0, v95
	v_add_f32_e32 v88, 1.0, v88
	v_add_f32_e32 v89, 1.0, v89
	v_add_f32_e32 v90, 1.0, v90
	v_add_f32_e32 v91, 1.0, v91
	v_rcp_f32_e32 v92, v92
	v_rcp_f32_e32 v93, v93
	v_rcp_f32_e32 v94, v94
	v_rcp_f32_e32 v95, v95
	v_rcp_f32_e32 v88, v88
	v_rcp_f32_e32 v89, v89
	v_rcp_f32_e32 v90, v90
	v_rcp_f32_e32 v91, v91
	v_lshlrev_b32_e32 v127, 16, v180
	v_and_b32_e32 v180, 0xffff0000, v180
	v_mul_f32_e32 v127, v92, v127
	v_mul_f32_e32 v180, v93, v180
	v_cvt_pk_bf16_f32 v180, v127, v180
	v_lshlrev_b32_e32 v127, 16, v181
	v_and_b32_e32 v181, 0xffff0000, v181
	v_mul_f32_e32 v127, v94, v127
	v_mul_f32_e32 v181, v95, v181
	v_cvt_pk_bf16_f32 v181, v127, v181
	v_lshlrev_b32_e32 v127, 16, v182
	v_and_b32_e32 v182, 0xffff0000, v182
	v_mul_f32_e32 v127, v88, v127
	v_mul_f32_e32 v182, v89, v182
	v_cvt_pk_bf16_f32 v182, v127, v182
	v_lshlrev_b32_e32 v127, 16, v183
	v_and_b32_e32 v183, 0xffff0000, v183
	v_mul_f32_e32 v127, v90, v127
	v_mul_f32_e32 v183, v91, v183
	v_cvt_pk_bf16_f32 v183, v127, v183
	v_add_u32_e32 v126, 0x40000, v123
	global_store_dwordx4 v126, v[180:183], s[58:59]
	s_waitcnt vmcnt(15)
	v_add_f32_e32 v84, v84, v142
	v_add_f32_e32 v85, v85, v143
	v_add_f32_e32 v86, v86, v144
	v_add_f32_e32 v87, v87, v145
	v_add_f32_e32 v80, v80, v146
	v_add_f32_e32 v81, v81, v147
	v_add_f32_e32 v82, v82, v148
	v_add_f32_e32 v83, v83, v149
	v_mul_f32_e32 v84, 0xbfb8aa3b, v84
	v_mul_f32_e32 v85, 0xbfb8aa3b, v85
	v_mul_f32_e32 v86, 0xbfb8aa3b, v86
	v_mul_f32_e32 v87, 0xbfb8aa3b, v87
	v_mul_f32_e32 v80, 0xbfb8aa3b, v80
	v_mul_f32_e32 v81, 0xbfb8aa3b, v81
	v_mul_f32_e32 v82, 0xbfb8aa3b, v82
	v_mul_f32_e32 v83, 0xbfb8aa3b, v83
	v_exp_f32_e32 v84, v84
	v_exp_f32_e32 v85, v85
	v_exp_f32_e32 v86, v86
	v_exp_f32_e32 v87, v87
	v_exp_f32_e32 v80, v80
	v_exp_f32_e32 v81, v81
	v_exp_f32_e32 v82, v82
	v_exp_f32_e32 v83, v83
	v_add_f32_e32 v84, 1.0, v84
	v_add_f32_e32 v85, 1.0, v85
	v_add_f32_e32 v86, 1.0, v86
	v_add_f32_e32 v87, 1.0, v87
	v_add_f32_e32 v80, 1.0, v80
	v_add_f32_e32 v81, 1.0, v81
	v_add_f32_e32 v82, 1.0, v82
	v_add_f32_e32 v83, 1.0, v83
	v_rcp_f32_e32 v84, v84
	v_rcp_f32_e32 v85, v85
	v_rcp_f32_e32 v86, v86
	v_rcp_f32_e32 v87, v87
	v_rcp_f32_e32 v80, v80
	v_rcp_f32_e32 v81, v81
	v_rcp_f32_e32 v82, v82
	v_rcp_f32_e32 v83, v83
	v_lshlrev_b32_e32 v127, 16, v184
	v_and_b32_e32 v184, 0xffff0000, v184
	v_mul_f32_e32 v127, v84, v127
	v_mul_f32_e32 v184, v85, v184
	v_cvt_pk_bf16_f32 v184, v127, v184
	v_lshlrev_b32_e32 v127, 16, v185
	v_and_b32_e32 v185, 0xffff0000, v185
	v_mul_f32_e32 v127, v86, v127
	v_mul_f32_e32 v185, v87, v185
	v_cvt_pk_bf16_f32 v185, v127, v185
	v_lshlrev_b32_e32 v127, 16, v186
	v_and_b32_e32 v186, 0xffff0000, v186
	v_mul_f32_e32 v127, v80, v127
	v_mul_f32_e32 v186, v81, v186
	v_cvt_pk_bf16_f32 v186, v127, v186
	v_lshlrev_b32_e32 v127, 16, v187
	v_and_b32_e32 v187, 0xffff0000, v187
	v_mul_f32_e32 v127, v82, v127
	v_mul_f32_e32 v187, v83, v187
	v_cvt_pk_bf16_f32 v187, v127, v187
	v_add_u32_e32 v126, 0x48000, v123
	global_store_dwordx4 v126, v[184:187], s[58:59]
	s_waitcnt vmcnt(15)
	v_add_f32_e32 v76, v76, v142
	v_add_f32_e32 v77, v77, v143
	v_add_f32_e32 v78, v78, v144
	v_add_f32_e32 v79, v79, v145
	v_add_f32_e32 v72, v72, v146
	v_add_f32_e32 v73, v73, v147
	v_add_f32_e32 v74, v74, v148
	v_add_f32_e32 v75, v75, v149
	v_mul_f32_e32 v76, 0xbfb8aa3b, v76
	v_mul_f32_e32 v77, 0xbfb8aa3b, v77
	v_mul_f32_e32 v78, 0xbfb8aa3b, v78
	v_mul_f32_e32 v79, 0xbfb8aa3b, v79
	v_mul_f32_e32 v72, 0xbfb8aa3b, v72
	v_mul_f32_e32 v73, 0xbfb8aa3b, v73
	v_mul_f32_e32 v74, 0xbfb8aa3b, v74
	v_mul_f32_e32 v75, 0xbfb8aa3b, v75
	v_exp_f32_e32 v76, v76
	v_exp_f32_e32 v77, v77
	v_exp_f32_e32 v78, v78
	v_exp_f32_e32 v79, v79
	v_exp_f32_e32 v72, v72
	v_exp_f32_e32 v73, v73
	v_exp_f32_e32 v74, v74
	v_exp_f32_e32 v75, v75
	v_add_f32_e32 v76, 1.0, v76
	v_add_f32_e32 v77, 1.0, v77
	v_add_f32_e32 v78, 1.0, v78
	v_add_f32_e32 v79, 1.0, v79
	v_add_f32_e32 v72, 1.0, v72
	v_add_f32_e32 v73, 1.0, v73
	v_add_f32_e32 v74, 1.0, v74
	v_add_f32_e32 v75, 1.0, v75
	v_rcp_f32_e32 v76, v76
	v_rcp_f32_e32 v77, v77
	v_rcp_f32_e32 v78, v78
	v_rcp_f32_e32 v79, v79
	v_rcp_f32_e32 v72, v72
	v_rcp_f32_e32 v73, v73
	v_rcp_f32_e32 v74, v74
	v_rcp_f32_e32 v75, v75
	v_lshlrev_b32_e32 v127, 16, v188
	v_and_b32_e32 v188, 0xffff0000, v188
	v_mul_f32_e32 v127, v76, v127
	v_mul_f32_e32 v188, v77, v188
	v_cvt_pk_bf16_f32 v188, v127, v188
	v_lshlrev_b32_e32 v127, 16, v189
	v_and_b32_e32 v189, 0xffff0000, v189
	v_mul_f32_e32 v127, v78, v127
	v_mul_f32_e32 v189, v79, v189
	v_cvt_pk_bf16_f32 v189, v127, v189
	v_lshlrev_b32_e32 v127, 16, v190
	v_and_b32_e32 v190, 0xffff0000, v190
	v_mul_f32_e32 v127, v72, v127
	v_mul_f32_e32 v190, v73, v190
	v_cvt_pk_bf16_f32 v190, v127, v190
	v_lshlrev_b32_e32 v127, 16, v191
	v_and_b32_e32 v191, 0xffff0000, v191
	v_mul_f32_e32 v127, v74, v127
	v_mul_f32_e32 v191, v75, v191
	v_cvt_pk_bf16_f32 v191, v127, v191
	v_add_u32_e32 v126, 0x50000, v123
	global_store_dwordx4 v126, v[188:191], s[58:59]
	s_waitcnt vmcnt(15)
	v_add_f32_e32 v68, v68, v142
	v_add_f32_e32 v69, v69, v143
	v_add_f32_e32 v70, v70, v144
	v_add_f32_e32 v71, v71, v145
	v_add_f32_e32 v64, v64, v146
	v_add_f32_e32 v65, v65, v147
	v_add_f32_e32 v66, v66, v148
	v_add_f32_e32 v67, v67, v149
	v_mul_f32_e32 v68, 0xbfb8aa3b, v68
	v_mul_f32_e32 v69, 0xbfb8aa3b, v69
	v_mul_f32_e32 v70, 0xbfb8aa3b, v70
	v_mul_f32_e32 v71, 0xbfb8aa3b, v71
	v_mul_f32_e32 v64, 0xbfb8aa3b, v64
	v_mul_f32_e32 v65, 0xbfb8aa3b, v65
	v_mul_f32_e32 v66, 0xbfb8aa3b, v66
	v_mul_f32_e32 v67, 0xbfb8aa3b, v67
	v_exp_f32_e32 v68, v68
	v_exp_f32_e32 v69, v69
	v_exp_f32_e32 v70, v70
	v_exp_f32_e32 v71, v71
	v_exp_f32_e32 v64, v64
	v_exp_f32_e32 v65, v65
	v_exp_f32_e32 v66, v66
	v_exp_f32_e32 v67, v67
	v_add_f32_e32 v68, 1.0, v68
	v_add_f32_e32 v69, 1.0, v69
	v_add_f32_e32 v70, 1.0, v70
	v_add_f32_e32 v71, 1.0, v71
	v_add_f32_e32 v64, 1.0, v64
	v_add_f32_e32 v65, 1.0, v65
	v_add_f32_e32 v66, 1.0, v66
	v_add_f32_e32 v67, 1.0, v67
	v_rcp_f32_e32 v68, v68
	v_rcp_f32_e32 v69, v69
	v_rcp_f32_e32 v70, v70
	v_rcp_f32_e32 v71, v71
	v_rcp_f32_e32 v64, v64
	v_rcp_f32_e32 v65, v65
	v_rcp_f32_e32 v66, v66
	v_rcp_f32_e32 v67, v67
	v_lshlrev_b32_e32 v127, 16, v192
	v_and_b32_e32 v192, 0xffff0000, v192
	v_mul_f32_e32 v127, v68, v127
	v_mul_f32_e32 v192, v69, v192
	v_cvt_pk_bf16_f32 v192, v127, v192
	v_lshlrev_b32_e32 v127, 16, v193
	v_and_b32_e32 v193, 0xffff0000, v193
	v_mul_f32_e32 v127, v70, v127
	v_mul_f32_e32 v193, v71, v193
	v_cvt_pk_bf16_f32 v193, v127, v193
	v_lshlrev_b32_e32 v127, 16, v194
	v_and_b32_e32 v194, 0xffff0000, v194
	v_mul_f32_e32 v127, v64, v127
	v_mul_f32_e32 v194, v65, v194
	v_cvt_pk_bf16_f32 v194, v127, v194
	v_lshlrev_b32_e32 v127, 16, v195
	v_and_b32_e32 v195, 0xffff0000, v195
	v_mul_f32_e32 v127, v66, v127
	v_mul_f32_e32 v195, v67, v195
	v_cvt_pk_bf16_f32 v195, v127, v195
	v_add_u32_e32 v126, 0x58000, v123
	global_store_dwordx4 v126, v[192:195], s[58:59]
	s_waitcnt vmcnt(15)
	v_add_f32_e32 v60, v60, v150
	v_add_f32_e32 v61, v61, v151
	v_add_f32_e32 v62, v62, v152
	v_add_f32_e32 v63, v63, v153
	v_add_f32_e32 v56, v56, v154
	v_add_f32_e32 v57, v57, v155
	v_add_f32_e32 v58, v58, v156
	v_add_f32_e32 v59, v59, v157
	v_mul_f32_e32 v60, 0xbfb8aa3b, v60
	v_mul_f32_e32 v61, 0xbfb8aa3b, v61
	v_mul_f32_e32 v62, 0xbfb8aa3b, v62
	v_mul_f32_e32 v63, 0xbfb8aa3b, v63
	v_mul_f32_e32 v56, 0xbfb8aa3b, v56
	v_mul_f32_e32 v57, 0xbfb8aa3b, v57
	v_mul_f32_e32 v58, 0xbfb8aa3b, v58
	v_mul_f32_e32 v59, 0xbfb8aa3b, v59
	v_exp_f32_e32 v60, v60
	v_exp_f32_e32 v61, v61
	v_exp_f32_e32 v62, v62
	v_exp_f32_e32 v63, v63
	v_exp_f32_e32 v56, v56
	v_exp_f32_e32 v57, v57
	v_exp_f32_e32 v58, v58
	v_exp_f32_e32 v59, v59
	v_add_f32_e32 v60, 1.0, v60
	v_add_f32_e32 v61, 1.0, v61
	v_add_f32_e32 v62, 1.0, v62
	v_add_f32_e32 v63, 1.0, v63
	v_add_f32_e32 v56, 1.0, v56
	v_add_f32_e32 v57, 1.0, v57
	v_add_f32_e32 v58, 1.0, v58
	v_add_f32_e32 v59, 1.0, v59
	v_rcp_f32_e32 v60, v60
	v_rcp_f32_e32 v61, v61
	v_rcp_f32_e32 v62, v62
	v_rcp_f32_e32 v63, v63
	v_rcp_f32_e32 v56, v56
	v_rcp_f32_e32 v57, v57
	v_rcp_f32_e32 v58, v58
	v_rcp_f32_e32 v59, v59
	v_lshlrev_b32_e32 v127, 16, v216
	v_and_b32_e32 v216, 0xffff0000, v216
	v_mul_f32_e32 v127, v60, v127
	v_mul_f32_e32 v216, v61, v216
	v_cvt_pk_bf16_f32 v216, v127, v216
	v_lshlrev_b32_e32 v127, 16, v217
	v_and_b32_e32 v217, 0xffff0000, v217
	v_mul_f32_e32 v127, v62, v127
	v_mul_f32_e32 v217, v63, v217
	v_cvt_pk_bf16_f32 v217, v127, v217
	v_lshlrev_b32_e32 v127, 16, v218
	v_and_b32_e32 v218, 0xffff0000, v218
	v_mul_f32_e32 v127, v56, v127
	v_mul_f32_e32 v218, v57, v218
	v_cvt_pk_bf16_f32 v218, v127, v218
	v_lshlrev_b32_e32 v127, 16, v219
	v_and_b32_e32 v219, 0xffff0000, v219
	v_mul_f32_e32 v127, v58, v127
	v_mul_f32_e32 v219, v59, v219
	v_cvt_pk_bf16_f32 v219, v127, v219
	global_store_dwordx4 v123, v[216:219], s[58:59] offset:256
	s_waitcnt vmcnt(15)
	v_add_f32_e32 v52, v52, v150
	v_add_f32_e32 v53, v53, v151
	v_add_f32_e32 v54, v54, v152
	v_add_f32_e32 v55, v55, v153
	v_add_f32_e32 v48, v48, v154
	v_add_f32_e32 v49, v49, v155
	v_add_f32_e32 v50, v50, v156
	v_add_f32_e32 v51, v51, v157
	v_mul_f32_e32 v52, 0xbfb8aa3b, v52
	v_mul_f32_e32 v53, 0xbfb8aa3b, v53
	v_mul_f32_e32 v54, 0xbfb8aa3b, v54
	v_mul_f32_e32 v55, 0xbfb8aa3b, v55
	v_mul_f32_e32 v48, 0xbfb8aa3b, v48
	v_mul_f32_e32 v49, 0xbfb8aa3b, v49
	v_mul_f32_e32 v50, 0xbfb8aa3b, v50
	v_mul_f32_e32 v51, 0xbfb8aa3b, v51
	v_exp_f32_e32 v52, v52
	v_exp_f32_e32 v53, v53
	v_exp_f32_e32 v54, v54
	v_exp_f32_e32 v55, v55
	v_exp_f32_e32 v48, v48
	v_exp_f32_e32 v49, v49
	v_exp_f32_e32 v50, v50
	v_exp_f32_e32 v51, v51
	v_add_f32_e32 v52, 1.0, v52
	v_add_f32_e32 v53, 1.0, v53
	v_add_f32_e32 v54, 1.0, v54
	v_add_f32_e32 v55, 1.0, v55
	v_add_f32_e32 v48, 1.0, v48
	v_add_f32_e32 v49, 1.0, v49
	v_add_f32_e32 v50, 1.0, v50
	v_add_f32_e32 v51, 1.0, v51
	v_rcp_f32_e32 v52, v52
	v_rcp_f32_e32 v53, v53
	v_rcp_f32_e32 v54, v54
	v_rcp_f32_e32 v55, v55
	v_rcp_f32_e32 v48, v48
	v_rcp_f32_e32 v49, v49
	v_rcp_f32_e32 v50, v50
	v_rcp_f32_e32 v51, v51
	v_lshlrev_b32_e32 v127, 16, v220
	v_and_b32_e32 v220, 0xffff0000, v220
	v_mul_f32_e32 v127, v52, v127
	v_mul_f32_e32 v220, v53, v220
	v_cvt_pk_bf16_f32 v220, v127, v220
	v_lshlrev_b32_e32 v127, 16, v221
	v_and_b32_e32 v221, 0xffff0000, v221
	v_mul_f32_e32 v127, v54, v127
	v_mul_f32_e32 v221, v55, v221
	v_cvt_pk_bf16_f32 v221, v127, v221
	v_lshlrev_b32_e32 v127, 16, v222
	v_and_b32_e32 v222, 0xffff0000, v222
	v_mul_f32_e32 v127, v48, v127
	v_mul_f32_e32 v222, v49, v222
	v_cvt_pk_bf16_f32 v222, v127, v222
	v_lshlrev_b32_e32 v127, 16, v223
	v_and_b32_e32 v223, 0xffff0000, v223
	v_mul_f32_e32 v127, v50, v127
	v_mul_f32_e32 v223, v51, v223
	v_cvt_pk_bf16_f32 v223, v127, v223
	v_add_u32_e32 v126, 0x8000, v123
	global_store_dwordx4 v126, v[220:223], s[58:59] offset:256
	s_waitcnt vmcnt(15)
	v_add_f32_e32 v44, v44, v150
	v_add_f32_e32 v45, v45, v151
	v_add_f32_e32 v46, v46, v152
	v_add_f32_e32 v47, v47, v153
	v_add_f32_e32 v40, v40, v154
	v_add_f32_e32 v41, v41, v155
	v_add_f32_e32 v42, v42, v156
	v_add_f32_e32 v43, v43, v157
	v_mul_f32_e32 v44, 0xbfb8aa3b, v44
	v_mul_f32_e32 v45, 0xbfb8aa3b, v45
	v_mul_f32_e32 v46, 0xbfb8aa3b, v46
	v_mul_f32_e32 v47, 0xbfb8aa3b, v47
	v_mul_f32_e32 v40, 0xbfb8aa3b, v40
	v_mul_f32_e32 v41, 0xbfb8aa3b, v41
	v_mul_f32_e32 v42, 0xbfb8aa3b, v42
	v_mul_f32_e32 v43, 0xbfb8aa3b, v43
	v_exp_f32_e32 v44, v44
	v_exp_f32_e32 v45, v45
	v_exp_f32_e32 v46, v46
	v_exp_f32_e32 v47, v47
	v_exp_f32_e32 v40, v40
	v_exp_f32_e32 v41, v41
	v_exp_f32_e32 v42, v42
	v_exp_f32_e32 v43, v43
	v_add_f32_e32 v44, 1.0, v44
	v_add_f32_e32 v45, 1.0, v45
	v_add_f32_e32 v46, 1.0, v46
	v_add_f32_e32 v47, 1.0, v47
	v_add_f32_e32 v40, 1.0, v40
	v_add_f32_e32 v41, 1.0, v41
	v_add_f32_e32 v42, 1.0, v42
	v_add_f32_e32 v43, 1.0, v43
	v_rcp_f32_e32 v44, v44
	v_rcp_f32_e32 v45, v45
	v_rcp_f32_e32 v46, v46
	v_rcp_f32_e32 v47, v47
	v_rcp_f32_e32 v40, v40
	v_rcp_f32_e32 v41, v41
	v_rcp_f32_e32 v42, v42
	v_rcp_f32_e32 v43, v43
	v_lshlrev_b32_e32 v127, 16, v224
	v_and_b32_e32 v224, 0xffff0000, v224
	v_mul_f32_e32 v127, v44, v127
	v_mul_f32_e32 v224, v45, v224
	v_cvt_pk_bf16_f32 v224, v127, v224
	v_lshlrev_b32_e32 v127, 16, v225
	v_and_b32_e32 v225, 0xffff0000, v225
	v_mul_f32_e32 v127, v46, v127
	v_mul_f32_e32 v225, v47, v225
	v_cvt_pk_bf16_f32 v225, v127, v225
	v_lshlrev_b32_e32 v127, 16, v226
	v_and_b32_e32 v226, 0xffff0000, v226
	v_mul_f32_e32 v127, v40, v127
	v_mul_f32_e32 v226, v41, v226
	v_cvt_pk_bf16_f32 v226, v127, v226
	v_lshlrev_b32_e32 v127, 16, v227
	v_and_b32_e32 v227, 0xffff0000, v227
	v_mul_f32_e32 v127, v42, v127
	v_mul_f32_e32 v227, v43, v227
	v_cvt_pk_bf16_f32 v227, v127, v227
	v_add_u32_e32 v126, 0x10000, v123
	global_store_dwordx4 v126, v[224:227], s[58:59] offset:256
	s_waitcnt vmcnt(15)
	v_add_f32_e32 v36, v36, v150
	v_add_f32_e32 v37, v37, v151
	v_add_f32_e32 v38, v38, v152
	v_add_f32_e32 v39, v39, v153
	v_add_f32_e32 v32, v32, v154
	v_add_f32_e32 v33, v33, v155
	v_add_f32_e32 v34, v34, v156
	v_add_f32_e32 v35, v35, v157
	v_mul_f32_e32 v36, 0xbfb8aa3b, v36
	v_mul_f32_e32 v37, 0xbfb8aa3b, v37
	v_mul_f32_e32 v38, 0xbfb8aa3b, v38
	v_mul_f32_e32 v39, 0xbfb8aa3b, v39
	v_mul_f32_e32 v32, 0xbfb8aa3b, v32
	v_mul_f32_e32 v33, 0xbfb8aa3b, v33
	v_mul_f32_e32 v34, 0xbfb8aa3b, v34
	v_mul_f32_e32 v35, 0xbfb8aa3b, v35
	v_exp_f32_e32 v36, v36
	v_exp_f32_e32 v37, v37
	v_exp_f32_e32 v38, v38
	v_exp_f32_e32 v39, v39
	v_exp_f32_e32 v32, v32
	v_exp_f32_e32 v33, v33
	v_exp_f32_e32 v34, v34
	v_exp_f32_e32 v35, v35
	v_add_f32_e32 v36, 1.0, v36
	v_add_f32_e32 v37, 1.0, v37
	v_add_f32_e32 v38, 1.0, v38
	v_add_f32_e32 v39, 1.0, v39
	v_add_f32_e32 v32, 1.0, v32
	v_add_f32_e32 v33, 1.0, v33
	v_add_f32_e32 v34, 1.0, v34
	v_add_f32_e32 v35, 1.0, v35
	v_rcp_f32_e32 v36, v36
	v_rcp_f32_e32 v37, v37
	v_rcp_f32_e32 v38, v38
	v_rcp_f32_e32 v39, v39
	v_rcp_f32_e32 v32, v32
	v_rcp_f32_e32 v33, v33
	v_rcp_f32_e32 v34, v34
	v_rcp_f32_e32 v35, v35
	v_lshlrev_b32_e32 v127, 16, v228
	v_and_b32_e32 v228, 0xffff0000, v228
	v_mul_f32_e32 v127, v36, v127
	v_mul_f32_e32 v228, v37, v228
	v_cvt_pk_bf16_f32 v228, v127, v228
	v_lshlrev_b32_e32 v127, 16, v229
	v_and_b32_e32 v229, 0xffff0000, v229
	v_mul_f32_e32 v127, v38, v127
	v_mul_f32_e32 v229, v39, v229
	v_cvt_pk_bf16_f32 v229, v127, v229
	v_lshlrev_b32_e32 v127, 16, v230
	v_and_b32_e32 v230, 0xffff0000, v230
	v_mul_f32_e32 v127, v32, v127
	v_mul_f32_e32 v230, v33, v230
	v_cvt_pk_bf16_f32 v230, v127, v230
	v_lshlrev_b32_e32 v127, 16, v231
	v_and_b32_e32 v231, 0xffff0000, v231
	v_mul_f32_e32 v127, v34, v127
	v_mul_f32_e32 v231, v35, v231
	v_cvt_pk_bf16_f32 v231, v127, v231
	v_add_u32_e32 v126, 0x18000, v123
	global_store_dwordx4 v126, v[228:231], s[58:59] offset:256
	s_waitcnt vmcnt(15)
	v_add_f32_e32 v28, v28, v150
	v_add_f32_e32 v29, v29, v151
	v_add_f32_e32 v30, v30, v152
	v_add_f32_e32 v31, v31, v153
	v_add_f32_e32 v24, v24, v154
	v_add_f32_e32 v25, v25, v155
	v_add_f32_e32 v26, v26, v156
	v_add_f32_e32 v27, v27, v157
	v_mul_f32_e32 v28, 0xbfb8aa3b, v28
	v_mul_f32_e32 v29, 0xbfb8aa3b, v29
	v_mul_f32_e32 v30, 0xbfb8aa3b, v30
	v_mul_f32_e32 v31, 0xbfb8aa3b, v31
	v_mul_f32_e32 v24, 0xbfb8aa3b, v24
	v_mul_f32_e32 v25, 0xbfb8aa3b, v25
	v_mul_f32_e32 v26, 0xbfb8aa3b, v26
	v_mul_f32_e32 v27, 0xbfb8aa3b, v27
	v_exp_f32_e32 v28, v28
	v_exp_f32_e32 v29, v29
	v_exp_f32_e32 v30, v30
	v_exp_f32_e32 v31, v31
	v_exp_f32_e32 v24, v24
	v_exp_f32_e32 v25, v25
	v_exp_f32_e32 v26, v26
	v_exp_f32_e32 v27, v27
	v_add_f32_e32 v28, 1.0, v28
	v_add_f32_e32 v29, 1.0, v29
	v_add_f32_e32 v30, 1.0, v30
	v_add_f32_e32 v31, 1.0, v31
	v_add_f32_e32 v24, 1.0, v24
	v_add_f32_e32 v25, 1.0, v25
	v_add_f32_e32 v26, 1.0, v26
	v_add_f32_e32 v27, 1.0, v27
	v_rcp_f32_e32 v28, v28
	v_rcp_f32_e32 v29, v29
	v_rcp_f32_e32 v30, v30
	v_rcp_f32_e32 v31, v31
	v_rcp_f32_e32 v24, v24
	v_rcp_f32_e32 v25, v25
	v_rcp_f32_e32 v26, v26
	v_rcp_f32_e32 v27, v27
	v_lshlrev_b32_e32 v127, 16, v236
	v_and_b32_e32 v236, 0xffff0000, v236
	v_mul_f32_e32 v127, v28, v127
	v_mul_f32_e32 v236, v29, v236
	v_cvt_pk_bf16_f32 v236, v127, v236
	v_lshlrev_b32_e32 v127, 16, v237
	v_and_b32_e32 v237, 0xffff0000, v237
	v_mul_f32_e32 v127, v30, v127
	v_mul_f32_e32 v237, v31, v237
	v_cvt_pk_bf16_f32 v237, v127, v237
	v_lshlrev_b32_e32 v127, 16, v238
	v_and_b32_e32 v238, 0xffff0000, v238
	v_mul_f32_e32 v127, v24, v127
	v_mul_f32_e32 v238, v25, v238
	v_cvt_pk_bf16_f32 v238, v127, v238
	v_lshlrev_b32_e32 v127, 16, v239
	v_and_b32_e32 v239, 0xffff0000, v239
	v_mul_f32_e32 v127, v26, v127
	v_mul_f32_e32 v239, v27, v239
	v_cvt_pk_bf16_f32 v239, v127, v239
	v_add_u32_e32 v126, 0x40000, v123
	global_store_dwordx4 v126, v[236:239], s[58:59] offset:256
	s_waitcnt vmcnt(15)
	v_add_f32_e32 v20, v20, v150
	v_add_f32_e32 v21, v21, v151
	v_add_f32_e32 v22, v22, v152
	v_add_f32_e32 v23, v23, v153
	v_add_f32_e32 v16, v16, v154
	v_add_f32_e32 v17, v17, v155
	v_add_f32_e32 v18, v18, v156
	v_add_f32_e32 v19, v19, v157
	v_mul_f32_e32 v20, 0xbfb8aa3b, v20
	v_mul_f32_e32 v21, 0xbfb8aa3b, v21
	v_mul_f32_e32 v22, 0xbfb8aa3b, v22
	v_mul_f32_e32 v23, 0xbfb8aa3b, v23
	v_mul_f32_e32 v16, 0xbfb8aa3b, v16
	v_mul_f32_e32 v17, 0xbfb8aa3b, v17
	v_mul_f32_e32 v18, 0xbfb8aa3b, v18
	v_mul_f32_e32 v19, 0xbfb8aa3b, v19
	v_exp_f32_e32 v20, v20
	v_exp_f32_e32 v21, v21
	v_exp_f32_e32 v22, v22
	v_exp_f32_e32 v23, v23
	v_exp_f32_e32 v16, v16
	v_exp_f32_e32 v17, v17
	v_exp_f32_e32 v18, v18
	v_exp_f32_e32 v19, v19
	v_add_f32_e32 v20, 1.0, v20
	v_add_f32_e32 v21, 1.0, v21
	v_add_f32_e32 v22, 1.0, v22
	v_add_f32_e32 v23, 1.0, v23
	v_add_f32_e32 v16, 1.0, v16
	v_add_f32_e32 v17, 1.0, v17
	v_add_f32_e32 v18, 1.0, v18
	v_add_f32_e32 v19, 1.0, v19
	v_rcp_f32_e32 v20, v20
	v_rcp_f32_e32 v21, v21
	v_rcp_f32_e32 v22, v22
	v_rcp_f32_e32 v23, v23
	v_rcp_f32_e32 v16, v16
	v_rcp_f32_e32 v17, v17
	v_rcp_f32_e32 v18, v18
	v_rcp_f32_e32 v19, v19
	v_lshlrev_b32_e32 v127, 16, v240
	v_and_b32_e32 v240, 0xffff0000, v240
	v_mul_f32_e32 v127, v20, v127
	v_mul_f32_e32 v240, v21, v240
	v_cvt_pk_bf16_f32 v240, v127, v240
	v_lshlrev_b32_e32 v127, 16, v241
	v_and_b32_e32 v241, 0xffff0000, v241
	v_mul_f32_e32 v127, v22, v127
	v_mul_f32_e32 v241, v23, v241
	v_cvt_pk_bf16_f32 v241, v127, v241
	v_lshlrev_b32_e32 v127, 16, v242
	v_and_b32_e32 v242, 0xffff0000, v242
	v_mul_f32_e32 v127, v16, v127
	v_mul_f32_e32 v242, v17, v242
	v_cvt_pk_bf16_f32 v242, v127, v242
	v_lshlrev_b32_e32 v127, 16, v243
	v_and_b32_e32 v243, 0xffff0000, v243
	v_mul_f32_e32 v127, v18, v127
	v_mul_f32_e32 v243, v19, v243
	v_cvt_pk_bf16_f32 v243, v127, v243
	v_add_u32_e32 v126, 0x48000, v123
	global_store_dwordx4 v126, v[240:243], s[58:59] offset:256
	s_waitcnt vmcnt(15)
	v_add_f32_e32 v12, v12, v150
	v_add_f32_e32 v13, v13, v151
	v_add_f32_e32 v14, v14, v152
	v_add_f32_e32 v15, v15, v153
	v_add_f32_e32 v8, v8, v154
	v_add_f32_e32 v9, v9, v155
	v_add_f32_e32 v10, v10, v156
	v_add_f32_e32 v11, v11, v157
	v_mul_f32_e32 v12, 0xbfb8aa3b, v12
	v_mul_f32_e32 v13, 0xbfb8aa3b, v13
	v_mul_f32_e32 v14, 0xbfb8aa3b, v14
	v_mul_f32_e32 v15, 0xbfb8aa3b, v15
	v_mul_f32_e32 v8, 0xbfb8aa3b, v8
	v_mul_f32_e32 v9, 0xbfb8aa3b, v9
	v_mul_f32_e32 v10, 0xbfb8aa3b, v10
	v_mul_f32_e32 v11, 0xbfb8aa3b, v11
	v_exp_f32_e32 v12, v12
	v_exp_f32_e32 v13, v13
	v_exp_f32_e32 v14, v14
	v_exp_f32_e32 v15, v15
	v_exp_f32_e32 v8, v8
	v_exp_f32_e32 v9, v9
	v_exp_f32_e32 v10, v10
	v_exp_f32_e32 v11, v11
	v_add_f32_e32 v12, 1.0, v12
	v_add_f32_e32 v13, 1.0, v13
	v_add_f32_e32 v14, 1.0, v14
	v_add_f32_e32 v15, 1.0, v15
	v_add_f32_e32 v8, 1.0, v8
	v_add_f32_e32 v9, 1.0, v9
	v_add_f32_e32 v10, 1.0, v10
	v_add_f32_e32 v11, 1.0, v11
	v_rcp_f32_e32 v12, v12
	v_rcp_f32_e32 v13, v13
	v_rcp_f32_e32 v14, v14
	v_rcp_f32_e32 v15, v15
	v_rcp_f32_e32 v8, v8
	v_rcp_f32_e32 v9, v9
	v_rcp_f32_e32 v10, v10
	v_rcp_f32_e32 v11, v11
	v_lshlrev_b32_e32 v127, 16, v244
	v_and_b32_e32 v244, 0xffff0000, v244
	v_mul_f32_e32 v127, v12, v127
	v_mul_f32_e32 v244, v13, v244
	v_cvt_pk_bf16_f32 v244, v127, v244
	v_lshlrev_b32_e32 v127, 16, v245
	v_and_b32_e32 v245, 0xffff0000, v245
	v_mul_f32_e32 v127, v14, v127
	v_mul_f32_e32 v245, v15, v245
	v_cvt_pk_bf16_f32 v245, v127, v245
	v_lshlrev_b32_e32 v127, 16, v246
	v_and_b32_e32 v246, 0xffff0000, v246
	v_mul_f32_e32 v127, v8, v127
	v_mul_f32_e32 v246, v9, v246
	v_cvt_pk_bf16_f32 v246, v127, v246
	v_lshlrev_b32_e32 v127, 16, v247
	v_and_b32_e32 v247, 0xffff0000, v247
	v_mul_f32_e32 v127, v10, v127
	v_mul_f32_e32 v247, v11, v247
	v_cvt_pk_bf16_f32 v247, v127, v247
	v_add_u32_e32 v126, 0x50000, v123
	global_store_dwordx4 v126, v[244:247], s[58:59] offset:256
	s_waitcnt vmcnt(15)
	v_add_f32_e32 v4, v4, v150
	v_add_f32_e32 v5, v5, v151
	v_add_f32_e32 v6, v6, v152
	v_add_f32_e32 v7, v7, v153
	v_add_f32_e32 v0, v0, v154
	v_add_f32_e32 v1, v1, v155
	v_add_f32_e32 v2, v2, v156
	v_add_f32_e32 v3, v3, v157
	v_mul_f32_e32 v4, 0xbfb8aa3b, v4
	v_mul_f32_e32 v5, 0xbfb8aa3b, v5
	v_mul_f32_e32 v6, 0xbfb8aa3b, v6
	v_mul_f32_e32 v7, 0xbfb8aa3b, v7
	v_mul_f32_e32 v0, 0xbfb8aa3b, v0
	v_mul_f32_e32 v1, 0xbfb8aa3b, v1
	v_mul_f32_e32 v2, 0xbfb8aa3b, v2
	v_mul_f32_e32 v3, 0xbfb8aa3b, v3
	v_exp_f32_e32 v4, v4
	v_exp_f32_e32 v5, v5
	v_exp_f32_e32 v6, v6
	v_exp_f32_e32 v7, v7
	v_exp_f32_e32 v0, v0
	v_exp_f32_e32 v1, v1
	v_exp_f32_e32 v2, v2
	v_exp_f32_e32 v3, v3
	v_add_f32_e32 v4, 1.0, v4
	v_add_f32_e32 v5, 1.0, v5
	v_add_f32_e32 v6, 1.0, v6
	v_add_f32_e32 v7, 1.0, v7
	v_add_f32_e32 v0, 1.0, v0
	v_add_f32_e32 v1, 1.0, v1
	v_add_f32_e32 v2, 1.0, v2
	v_add_f32_e32 v3, 1.0, v3
	v_rcp_f32_e32 v4, v4
	v_rcp_f32_e32 v5, v5
	v_rcp_f32_e32 v6, v6
	v_rcp_f32_e32 v7, v7
	v_rcp_f32_e32 v0, v0
	v_rcp_f32_e32 v1, v1
	v_rcp_f32_e32 v2, v2
	v_rcp_f32_e32 v3, v3
	v_lshlrev_b32_e32 v127, 16, v248
	v_and_b32_e32 v248, 0xffff0000, v248
	v_mul_f32_e32 v127, v4, v127
	v_mul_f32_e32 v248, v5, v248
	v_cvt_pk_bf16_f32 v248, v127, v248
	v_lshlrev_b32_e32 v127, 16, v249
	v_and_b32_e32 v249, 0xffff0000, v249
	v_mul_f32_e32 v127, v6, v127
	v_mul_f32_e32 v249, v7, v249
	v_cvt_pk_bf16_f32 v249, v127, v249
	v_lshlrev_b32_e32 v127, 16, v250
	v_and_b32_e32 v250, 0xffff0000, v250
	v_mul_f32_e32 v127, v0, v127
	v_mul_f32_e32 v250, v1, v250
	v_cvt_pk_bf16_f32 v250, v127, v250
	v_lshlrev_b32_e32 v127, 16, v251
	v_and_b32_e32 v251, 0xffff0000, v251
	v_mul_f32_e32 v127, v2, v127
	v_mul_f32_e32 v251, v3, v251
	v_cvt_pk_bf16_f32 v251, v127, v251
	v_add_u32_e32 v126, 0x58000, v123
	global_store_dwordx4 v126, v[248:251], s[58:59] offset:256

.LBB0_230:
	v_exp_f32_e32 v64, v64
	v_exp_f32_e32 v65, v65
	v_exp_f32_e32 v62, v71
	v_exp_f32_e32 v71, v66
	v_exp_f32_e32 v63, v70
	v_exp_f32_e32 v70, v67
	v_exp_f32_e32 v61, v72
	v_exp_f32_e32 v68, v68
	v_exp_f32_e32 v72, v16
	v_add_f32_e32 v16, 0, v64
	v_exp_f32_e32 v69, v69
	v_add_f32_e32 v16, v65, v16
	v_add_f32_e32 v16, v71, v16
	v_add_f32_e32 v16, v70, v16
	v_add_f32_e32 v16, v68, v16
	v_exp_f32_e32 v60, v73
	v_add_f32_e32 v16, v69, v16
	v_exp_f32_e32 v59, v74
	v_add_f32_e32 v16, v63, v16
	v_exp_f32_e32 v58, v75
	v_add_f32_e32 v16, v62, v16
	v_exp_f32_e32 v57, v76
	v_add_f32_e32 v16, v61, v16
	v_exp_f32_e32 v56, v77
	v_add_f32_e32 v16, v60, v16
	v_exp_f32_e32 v55, v78
	v_add_f32_e32 v16, v59, v16
	v_exp_f32_e32 v54, v79
	v_add_f32_e32 v16, v58, v16
	v_add_f32_e32 v16, v57, v16
	v_exp_f32_e32 v73, v17
	v_add_f32_e32 v16, v56, v16
	v_exp_f32_e32 v74, v18
	v_add_f32_e32 v16, v55, v16
	v_exp_f32_e32 v75, v19
	v_add_f32_e32 v16, v54, v16
	v_exp_f32_e32 v76, v20
	v_add_f32_e32 v16, v72, v16
	v_exp_f32_e32 v77, v21
	v_add_f32_e32 v16, v73, v16
	v_exp_f32_e32 v78, v22
	v_add_f32_e32 v16, v74, v16
	v_exp_f32_e32 v79, v23
	v_add_f32_e32 v16, v75, v16
	v_exp_f32_e32 v80, v24
	v_add_f32_e32 v16, v76, v16
	v_exp_f32_e32 v81, v25
	v_add_f32_e32 v16, v77, v16
	v_exp_f32_e32 v82, v26
	v_add_f32_e32 v16, v78, v16
	v_exp_f32_e32 v83, v27
	v_add_f32_e32 v16, v79, v16
	v_exp_f32_e32 v84, v28
	v_add_f32_e32 v16, v80, v16
	v_exp_f32_e32 v85, v29
	v_add_f32_e32 v16, v81, v16
	v_exp_f32_e32 v86, v30
	v_add_f32_e32 v16, v82, v16
	v_exp_f32_e32 v31, v31
	v_add_f32_e32 v16, v83, v16
	s_lshl_b32 s2, s2, 12
	v_add_f32_e32 v16, v84, v16
	s_add_i32 s2, s2, s3
	v_add_f32_e32 v16, v85, v16
	s_mul_hi_i32 s3, s2, 0x1800
	s_mulk_i32 s2, 0x1800
	v_add_f32_e32 v16, v86, v16
	s_add_u32 s2, s50, s2
	v_add_f32_e32 v53, v31, v16
	s_addc_u32 s3, s51, s3
	s_lshl_b32 s4, s46, 7
	v_add_f32_e32 v50, v50, v51
	v_mov_b32_e32 v51, v53
	s_and_b32 s4, s4, 0x380
	v_mul_f32_e32 v52, v186, v176
	v_permlane32_swap_b32_e32 v53, v51
	s_add_u32 s2, s2, s4
	v_pk_add_f32 v[66:67], v[52:53], v[50:51]
	s_addc_u32 s3, s3, 0
	v_fmac_f32_e32 v67, v66, v48
	v_cvt_pk_bf16_f32 v16, v64, v65
	v_cvt_pk_bf16_f32 v17, v71, v70
	v_cvt_pk_bf16_f32 v18, v68, v69
	v_cvt_pk_bf16_f32 v19, v63, v62
	v_cvt_pk_bf16_f32 v20, v61, v60
	v_cvt_pk_bf16_f32 v21, v59, v58
	v_cvt_pk_bf16_f32 v22, v57, v56
	v_cvt_pk_bf16_f32 v23, v55, v54
	v_cvt_pk_bf16_f32 v24, v72, v73
	v_cvt_pk_bf16_f32 v25, v74, v75
	v_cvt_pk_bf16_f32 v26, v76, v77
	v_cvt_pk_bf16_f32 v27, v78, v79
	v_cvt_pk_bf16_f32 v28, v80, v81
	v_cvt_pk_bf16_f32 v29, v82, v83
	v_cvt_pk_bf16_f32 v30, v84, v85
	v_cvt_pk_bf16_f32 v31, v86, v31
	v_lshl_add_u64 v[84:85], s[2:3], 0, v[150:151]
	v_lshl_add_u64 v[84:85], v[84:85], 0, v[168:169]
	s_mov_b64 s[2:3], 0x6a01000
	v_lshl_add_u64 v[84:85], v[84:85], 0, s[2:3]
	global_load_dwordx2 v[68:69], v[84:85], off
	global_load_dwordx2 v[70:71], v[84:85], off offset:16
	global_load_dwordx2 v[72:73], v[84:85], off offset:32
	global_load_dwordx2 v[74:75], v[84:85], off offset:48
	global_load_dwordx2 v[76:77], v[84:85], off offset:64
	global_load_dwordx2 v[78:79], v[84:85], off offset:80
	global_load_dwordx2 v[80:81], v[84:85], off offset:96
	global_load_dwordx2 v[82:83], v[84:85], off offset:112
	ds_read_b64_tr_b16 v[50:51], v49
	ds_read_b64_tr_b16 v[52:53], v49 offset:1024
	ds_read_b64_tr_b16 v[54:55], v49 offset:2048
	ds_read_b64_tr_b16 v[56:57], v49 offset:3072
	ds_read_b64_tr_b16 v[58:59], v49 offset:4096
	ds_read_b64_tr_b16 v[60:61], v49 offset:5120
	ds_read_b64_tr_b16 v[62:63], v49 offset:6144
	ds_read_b64_tr_b16 v[64:65], v49 offset:7168
	s_waitcnt lgkmcnt(6)
	v_mfma_f32_32x32x16_bf16 v[0:15], v[50:53], v[16:19], v[0:15]
	s_add_i32 s6, s6, 1
	s_mov_b64 s[4:5], 0
	s_waitcnt lgkmcnt(4)
	v_mfma_f32_32x32x16_bf16 v[0:15], v[54:57], v[20:23], v[0:15]
	s_waitcnt lgkmcnt(2)
	v_mfma_f32_32x32x16_bf16 v[0:15], v[58:61], v[24:27], v[0:15]
	s_waitcnt lgkmcnt(0)
	v_mfma_f32_32x32x16_bf16 v[0:15], v[62:65], v[28:31], v[0:15]
	ds_read_b64_tr_b16 v[50:51], v49 offset:512
	ds_read_b64_tr_b16 v[52:53], v49 offset:1536
	ds_read_b64_tr_b16 v[54:55], v49 offset:2560
	ds_read_b64_tr_b16 v[56:57], v49 offset:3584
	ds_read_b64_tr_b16 v[58:59], v49 offset:4608
	ds_read_b64_tr_b16 v[60:61], v49 offset:5632
	ds_read_b64_tr_b16 v[62:63], v49 offset:6656
	ds_read_b64_tr_b16 v[64:65], v49 offset:7680
	s_waitcnt lgkmcnt(6)
	v_mfma_f32_32x32x16_bf16 v[32:47], v[50:53], v[16:19], v[32:47]
	v_rcp_f32_e32 v86, v67
	s_waitcnt lgkmcnt(4)
	v_mfma_f32_32x32x16_bf16 v[32:47], v[54:57], v[20:23], v[32:47]
	s_waitcnt lgkmcnt(2)
	v_mfma_f32_32x32x16_bf16 v[32:47], v[58:61], v[24:27], v[32:47]
	s_waitcnt lgkmcnt(0)
	v_mfma_f32_32x32x16_bf16 v[32:47], v[62:65], v[28:31], v[32:47]
	s_waitcnt vmcnt(0)
	v_lshlrev_b32_e32 v87, 16, v68
	v_and_b32_e32 v68, 0xffff0000, v68
	v_mul_f32_e32 v0, v86, v0
	v_mul_f32_e32 v1, v86, v1
	v_mul_f32_e32 v0, v0, v87
	v_mul_f32_e32 v1, v1, v68
	v_cvt_pk_bf16_f32 v68, v0, v1
	v_lshlrev_b32_e32 v87, 16, v69
	v_and_b32_e32 v69, 0xffff0000, v69
	v_mul_f32_e32 v2, v86, v2
	v_mul_f32_e32 v3, v86, v3
	v_mul_f32_e32 v2, v2, v87
	v_mul_f32_e32 v3, v3, v69
	v_cvt_pk_bf16_f32 v69, v2, v3
	global_store_dwordx2 v[84:85], v[68:69], off
	v_lshlrev_b32_e32 v87, 16, v70
	v_and_b32_e32 v70, 0xffff0000, v70
	v_mul_f32_e32 v4, v86, v4
	v_mul_f32_e32 v5, v86, v5
	v_mul_f32_e32 v4, v4, v87
	v_mul_f32_e32 v5, v5, v70
	v_cvt_pk_bf16_f32 v70, v4, v5
	v_lshlrev_b32_e32 v87, 16, v71
	v_and_b32_e32 v71, 0xffff0000, v71
	v_mul_f32_e32 v6, v86, v6
	v_mul_f32_e32 v7, v86, v7
	v_mul_f32_e32 v6, v6, v87
	v_mul_f32_e32 v7, v7, v71
	v_cvt_pk_bf16_f32 v71, v6, v7
	global_store_dwordx2 v[84:85], v[70:71], off offset:16
	v_lshlrev_b32_e32 v87, 16, v72
	v_and_b32_e32 v72, 0xffff0000, v72
	v_mul_f32_e32 v8, v86, v8
	v_mul_f32_e32 v9, v86, v9
	v_mul_f32_e32 v8, v8, v87
	v_mul_f32_e32 v9, v9, v72
	v_cvt_pk_bf16_f32 v72, v8, v9
	v_lshlrev_b32_e32 v87, 16, v73
	v_and_b32_e32 v73, 0xffff0000, v73
	v_mul_f32_e32 v10, v86, v10
	v_mul_f32_e32 v11, v86, v11
	v_mul_f32_e32 v10, v10, v87
	v_mul_f32_e32 v11, v11, v73
	v_cvt_pk_bf16_f32 v73, v10, v11
	global_store_dwordx2 v[84:85], v[72:73], off offset:32
	v_lshlrev_b32_e32 v87, 16, v74
	v_and_b32_e32 v74, 0xffff0000, v74
	v_mul_f32_e32 v12, v86, v12
	v_mul_f32_e32 v13, v86, v13
	v_mul_f32_e32 v12, v12, v87
	v_mul_f32_e32 v13, v13, v74
	v_cvt_pk_bf16_f32 v74, v12, v13
	v_lshlrev_b32_e32 v87, 16, v75
	v_and_b32_e32 v75, 0xffff0000, v75
	v_mul_f32_e32 v14, v86, v14
	v_mul_f32_e32 v15, v86, v15
	v_mul_f32_e32 v14, v14, v87
	v_mul_f32_e32 v15, v15, v75
	v_cvt_pk_bf16_f32 v75, v14, v15
	global_store_dwordx2 v[84:85], v[74:75], off offset:48
	v_lshlrev_b32_e32 v87, 16, v76
	v_and_b32_e32 v76, 0xffff0000, v76
	v_mul_f32_e32 v32, v86, v32
	v_mul_f32_e32 v33, v86, v33
	v_mul_f32_e32 v32, v32, v87
	v_mul_f32_e32 v33, v33, v76
	v_cvt_pk_bf16_f32 v76, v32, v33
	v_lshlrev_b32_e32 v87, 16, v77
	v_and_b32_e32 v77, 0xffff0000, v77
	v_mul_f32_e32 v34, v86, v34
	v_mul_f32_e32 v35, v86, v35
	v_mul_f32_e32 v34, v34, v87
	v_mul_f32_e32 v35, v35, v77
	v_cvt_pk_bf16_f32 v77, v34, v35
	global_store_dwordx2 v[84:85], v[76:77], off offset:64
	v_lshlrev_b32_e32 v87, 16, v78
	v_and_b32_e32 v78, 0xffff0000, v78
	v_mul_f32_e32 v36, v86, v36
	v_mul_f32_e32 v37, v86, v37
	v_mul_f32_e32 v36, v36, v87
	v_mul_f32_e32 v37, v37, v78
	v_cvt_pk_bf16_f32 v78, v36, v37
	v_lshlrev_b32_e32 v87, 16, v79
	v_and_b32_e32 v79, 0xffff0000, v79
	v_mul_f32_e32 v38, v86, v38
	v_mul_f32_e32 v39, v86, v39
	v_mul_f32_e32 v38, v38, v87
	v_mul_f32_e32 v39, v39, v79
	v_cvt_pk_bf16_f32 v79, v38, v39
	global_store_dwordx2 v[84:85], v[78:79], off offset:80
	v_lshlrev_b32_e32 v87, 16, v80
	v_and_b32_e32 v80, 0xffff0000, v80
	v_mul_f32_e32 v40, v86, v40
	v_mul_f32_e32 v41, v86, v41
	v_mul_f32_e32 v40, v40, v87
	v_mul_f32_e32 v41, v41, v80
	v_cvt_pk_bf16_f32 v80, v40, v41
	v_lshlrev_b32_e32 v87, 16, v81
	v_and_b32_e32 v81, 0xffff0000, v81
	v_mul_f32_e32 v42, v86, v42
	v_mul_f32_e32 v43, v86, v43
	v_mul_f32_e32 v42, v42, v87
	v_mul_f32_e32 v43, v43, v81
	v_cvt_pk_bf16_f32 v81, v42, v43
	global_store_dwordx2 v[84:85], v[80:81], off offset:96
	v_lshlrev_b32_e32 v87, 16, v82
	v_and_b32_e32 v82, 0xffff0000, v82
	v_mul_f32_e32 v44, v86, v44
	v_mul_f32_e32 v45, v86, v45
	v_mul_f32_e32 v44, v44, v87
	v_mul_f32_e32 v45, v45, v82
	v_cvt_pk_bf16_f32 v82, v44, v45
	v_lshlrev_b32_e32 v87, 16, v83
	v_and_b32_e32 v83, 0xffff0000, v83
	v_mul_f32_e32 v46, v86, v46
	v_mul_f32_e32 v47, v86, v47
	v_mul_f32_e32 v46, v46, v87
	v_mul_f32_e32 v47, v47, v83
	v_cvt_pk_bf16_f32 v83, v46, v47
	global_store_dwordx2 v[84:85], v[82:83], off offset:112
	s_barrier

.LBB0_241:
	s_mov_b64 s[4:5], -1
	s_and_b64 vcc, exec, s[2:3]
	s_cbranch_vccz .LBB0_231
	s_ashr_i32 s47, s46, 31
	s_ashr_i32 s2, s46, 3
	s_lshl_b64 s[4:5], s[46:47], 12
	s_lshl_b32 s3, s10, 8
	s_add_u32 s4, s4, s3
	s_addc_u32 s5, s5, 0
	s_lshl_b64 s[54:55], s[46:47], 19
	s_add_u32 s10, s50, s54
	v_add_lshl_u32 v8, v145, s3, 4
	s_addc_u32 s11, s51, s55
	v_ashrrev_i32_e32 v9, 31, v8
	s_add_u32 s56, s10, 0xf300000
	s_mul_i32 s10, s5, 0xc0
	v_mad_u64_u32 v[4:5], s[4:5], s4, v206, v[138:139]
	v_lshlrev_b64 v[12:13], 2, v[8:9]
	v_add_u32_e32 v5, s10, v5
	v_lshl_add_u64 v[14:15], v[140:141], 0, v[12:13]
	v_lshl_add_u64 v[20:21], v[142:143], 0, v[12:13]
	global_load_dwordx4 v[108:111], v[4:5], off
	global_load_dwordx4 v[104:107], v[4:5], off offset:32
	global_load_dwordx4 v[100:103], v[4:5], off offset:64
	global_load_dwordx4 v[96:99], v[4:5], off offset:96
	global_load_dwordx4 v[0:3], v[4:5], off offset:128
	s_nop 0
	global_load_dwordx4 v[4:7], v[4:5], off offset:160
	s_nop 0
	global_load_dwordx4 v[8:11], v[14:15], off offset:16
	global_load_dwordx4 v[16:19], v[14:15], off
	s_nop 0
	global_load_dwordx4 v[12:15], v[20:21], off offset:16
	s_nop 0
	global_load_dwordx4 v[20:23], v[20:21], off
	s_addc_u32 s57, s11, 0
	s_lshl_b32 s4, s2, 18
	s_sub_i32 s4, s4, s54
	v_lshl_add_u64 v[64:65], v[156:157], 0, s[54:55]
	s_mov_b32 s64, s65
	s_mov_b32 s66, s65
	s_mov_b32 s67, s65
	s_mov_b32 s68, s65
	s_mov_b32 s69, s65
	s_mov_b32 s70, s65
	s_mov_b32 s71, s65
	s_mov_b32 s72, s65
	s_mov_b32 s73, s65
	s_mov_b32 s74, s65
	s_mov_b32 s75, s65
	s_mov_b32 s76, s65
	s_mov_b32 s77, s65
	s_mov_b32 s78, s65
	s_mov_b32 s79, s65
	v_lshl_add_u64 v[166:167], v[158:159], 0, s[54:55]
	v_mov_b32_e32 v186, 0
	v_mov_b32_e32 v187, 1.0
	s_movk_i32 s5, 0x100
	s_mov_b32 s10, 1
	s_waitcnt vmcnt(5)
	v_lshlrev_b32_e32 v25, 16, v0
	s_waitcnt vmcnt(4)
	v_lshlrev_b32_e32 v24, 16, v4
	s_waitcnt vmcnt(2)
	v_mov_b32_e32 v27, v16
	s_waitcnt vmcnt(0)
	v_mov_b32_e32 v26, v20
	v_pk_mul_f32 v[26:27], v[26:27], v[24:25]
	s_nop 0
	v_sub_f32_e32 v28, v27, v26
	v_mov_b32_e32 v26, v16
	v_mov_b32_e32 v27, v20
	v_pk_mul_f32 v[24:25], v[26:27], v[24:25]
	v_mov_b32_e32 v16, v21
	v_add_f32_e32 v29, v24, v25
	v_and_b32_e32 v25, 0xffff0000, v0
	v_and_b32_e32 v24, 0xffff0000, v4
	v_mov_b32_e32 v20, v17
	v_pk_mul_f32 v[26:27], v[16:17], v[24:25]
	v_pk_mul_f32 v[16:17], v[20:21], v[24:25]
	v_mov_b32_e32 v20, v22
	v_add_f32_e32 v24, v16, v17
	v_lshlrev_b32_e32 v17, 16, v1
	v_lshlrev_b32_e32 v16, 16, v5
	v_mov_b32_e32 v21, v18
	v_sub_f32_e32 v0, v27, v26
	v_pk_mul_f32 v[20:21], v[20:21], v[16:17]
	v_cvt_pk_bf16_f32 v112, v28, v0
	v_and_b32_e32 v1, 0xffff0000, v1
	v_sub_f32_e32 v25, v21, v20
	v_mov_b32_e32 v20, v18
	v_and_b32_e32 v0, 0xffff0000, v5
	v_mov_b32_e32 v18, v23
	v_mov_b32_e32 v21, v22
	v_pk_mul_f32 v[4:5], v[18:19], v[0:1]
	v_mov_b32_e32 v22, v19
	v_pk_mul_f32 v[16:17], v[20:21], v[16:17]
	v_sub_f32_e32 v4, v5, v4
	v_pk_mul_f32 v[0:1], v[22:23], v[0:1]
	v_add_f32_e32 v16, v16, v17
	v_cvt_pk_bf16_f32 v113, v25, v4
	v_add_f32_e32 v17, v0, v1
	v_lshlrev_b32_e32 v1, 16, v2
	v_lshlrev_b32_e32 v0, 16, v6
	v_mov_b32_e32 v4, v12
	v_mov_b32_e32 v5, v8
	v_pk_mul_f32 v[4:5], v[4:5], v[0:1]
	s_nop 0
	v_sub_f32_e32 v18, v5, v4
	v_mov_b32_e32 v4, v8
	v_mov_b32_e32 v5, v12
	v_pk_mul_f32 v[0:1], v[4:5], v[0:1]
	v_mov_b32_e32 v8, v13
	v_add_f32_e32 v19, v0, v1
	v_and_b32_e32 v1, 0xffff0000, v2
	v_and_b32_e32 v0, 0xffff0000, v6
	v_mov_b32_e32 v12, v9
	v_pk_mul_f32 v[4:5], v[8:9], v[0:1]
	v_pk_mul_f32 v[0:1], v[12:13], v[0:1]
	v_sub_f32_e32 v2, v5, v4
	v_add_f32_e32 v6, v0, v1
	v_lshlrev_b32_e32 v1, 16, v3
	v_lshlrev_b32_e32 v0, 16, v7
	v_mov_b32_e32 v4, v14
	v_mov_b32_e32 v5, v10
	v_pk_mul_f32 v[4:5], v[4:5], v[0:1]
	v_cvt_pk_bf16_f32 v114, v18, v2
	s_nop 0
	v_sub_f32_e32 v8, v5, v4
	v_mov_b32_e32 v4, v10
	v_mov_b32_e32 v5, v14
	v_pk_mul_f32 v[0:1], v[4:5], v[0:1]
	v_mov_b32_e32 v10, v15
	v_add_f32_e32 v4, v0, v1
	v_and_b32_e32 v1, 0xffff0000, v3
	v_and_b32_e32 v0, 0xffff0000, v7
	v_mov_b32_e32 v14, v11
	v_pk_mul_f32 v[2:3], v[10:11], v[0:1]
	v_pk_mul_f32 v[0:1], v[14:15], v[0:1]
	v_sub_f32_e32 v2, v3, v2
	v_add_f32_e32 v0, v0, v1
	v_cvt_pk_bf16_f32 v115, v8, v2
	v_cvt_pk_bf16_f32 v116, v29, v24
	v_cvt_pk_bf16_f32 v117, v16, v17
	v_cvt_pk_bf16_f32 v118, v19, v6
	v_cvt_pk_bf16_f32 v119, v4, v0
	v_add_u32_e32 v0, s4, v147
	v_cndmask_b32_e64 v68, v0, v144, s[38:39]
	v_add_u32_e32 v0, s4, v175
	v_cndmask_b32_e64 v0, v0, v146, s[40:41]
	v_or_b32_e32 v66, v0, v137
	v_ashrrev_i32_e32 v69, 31, v68
	v_ashrrev_i32_e32 v67, 31, v66
	v_lshl_add_u64 v[160:161], s[56:57], 0, v[68:69]
	v_lshl_add_u64 v[162:163], s[56:57], 0, v[66:67]
	global_load_dwordx4 v[0:3], v[160:161], off
	global_load_dwordx4 v[4:7], v[64:65], off
	global_load_dwordx2 v[8:9], v[162:163], off
	v_add_u32_e32 v67, 0, v148
	v_add_u32_e32 v69, 0, v149
	s_waitcnt vmcnt(0)
	s_movk_i32 s4, 0x2000
	s_waitcnt vmcnt(1)
	ds_write_b128 v179, v[4:7]
	ds_write_b128 v67, v[0:3] offset:24576
	s_waitcnt vmcnt(0)
	ds_write_b64 v69, v[8:9] offset:24576
	s_waitcnt lgkmcnt(0)
	s_barrier
	ds_read_b128 v[16:19], v181 offset:31232
	ds_read_b128 v[20:23], v181 offset:24576
	ds_read_b128 v[50:53], v181 offset:24608
	s_waitcnt lgkmcnt(1)
	v_mfma_f32_32x32x16_bf16 v[34:49], v[20:23], v[108:111], 0
	ds_read_b128 v[54:57], v181 offset:31264
	v_mov_b64_e32 v[0:1], s[64:65]
	v_mov_b64_e32 v[14:15], s[78:79]
	v_mov_b64_e32 v[2:3], s[66:67]
	v_mov_b64_e32 v[4:5], s[68:69]
	v_mov_b64_e32 v[6:7], s[70:71]
	v_mov_b64_e32 v[8:9], s[72:73]
	v_mfma_f32_32x32x16_bf16 v[18:33], v[16:19], v[108:111], 0
	v_mov_b64_e32 v[10:11], s[74:75]
	v_mov_b64_e32 v[12:13], s[76:77]
	s_waitcnt lgkmcnt(1)
	v_mfma_f32_32x32x16_bf16 v[34:49], v[50:53], v[104:107], v[34:49]
	s_waitcnt lgkmcnt(0)
	v_mfma_f32_32x32x16_bf16 v[18:33], v[54:57], v[104:107], v[18:33]
	ds_read_b128 v[50:53], v181 offset:31296
	ds_read_b128 v[54:57], v181 offset:24640
	s_waitcnt lgkmcnt(0)
	v_mfma_f32_32x32x16_bf16 v[34:49], v[54:57], v[100:103], v[34:49]
	v_mfma_f32_32x32x16_bf16 v[18:33], v[50:53], v[100:103], v[18:33]
	ds_read_b128 v[50:53], v181 offset:31328
	ds_read_b128 v[54:57], v181 offset:24672
	s_waitcnt lgkmcnt(0)
	v_mfma_f32_32x32x16_bf16 v[34:49], v[54:57], v[96:99], v[34:49]
	v_mfma_f32_32x32x16_bf16 v[18:33], v[50:53], v[96:99], v[18:33]
	ds_read_b128 v[50:53], v181 offset:31360
	ds_read_b128 v[54:57], v181 offset:24704
	s_waitcnt lgkmcnt(0)
	v_mfma_f32_32x32x16_bf16 v[34:49], v[54:57], v[112:115], v[34:49]
	v_mfma_f32_32x32x16_bf16 v[18:33], v[50:53], v[112:115], v[18:33]
	ds_read_b128 v[50:53], v181 offset:31392
	ds_read_b128 v[54:57], v181 offset:24736
	s_waitcnt lgkmcnt(0)
	v_mfma_f32_32x32x16_bf16 v[34:49], v[54:57], v[116:119], v[34:49]
	v_mfma_f32_32x32x16_bf16 v[18:33], v[50:53], v[116:119], v[18:33]
	s_nop 10
	v_max_f32_e32 v16, v35, v35
	v_max_f32_e32 v17, v34, v34
	v_max_f32_e32 v16, v17, v16
	v_max3_f32 v16, v16, v36, v37
	v_max3_f32 v16, v16, v38, v39
	v_max3_f32 v16, v16, v40, v41
	v_max3_f32 v16, v16, v42, v43
	v_max3_f32 v16, v16, v44, v45
	v_max3_f32 v16, v16, v46, v47
	v_max3_f32 v16, v16, v48, v49
	v_max3_f32 v16, v16, v18, v19
	v_max3_f32 v16, v16, v20, v21
	v_max3_f32 v16, v16, v22, v23
	v_max3_f32 v16, v16, v24, v25
	v_max3_f32 v16, v16, v26, v27
	v_max3_f32 v16, v16, v28, v29
	v_max3_f32 v16, v16, v30, v31
	v_max3_f32 v16, v16, v32, v33
	v_mov_b32_e32 v17, v16
	s_nop 1
	v_permlane32_swap_b32_e32 v16, v17
	v_max_f32_e32 v17, v17, v17
	v_max_f32_e32 v16, v16, v16
	v_max_f32_e32 v17, v16, v17
	v_sub_f32_e32 v36, v36, v17
	v_sub_f32_e32 v37, v37, v17
	v_sub_f32_e32 v42, v42, v17
	v_sub_f32_e32 v34, v34, v17
	v_sub_f32_e32 v35, v35, v17
	v_sub_f32_e32 v40, v40, v17
	v_sub_f32_e32 v41, v41, v17
	v_sub_f32_e32 v43, v43, v17
	v_sub_f32_e32 v63, v33, v17
	v_sub_f32_e32 v62, v32, v17
	v_exp_f32_e32 v191, v36
	v_exp_f32_e32 v193, v37
	v_exp_f32_e32 v133, v42
	v_lshl_add_u64 v[32:33], v[160:161], 0, v[152:153]
	v_lshl_add_u64 v[36:37], v[162:163], 0, v[154:155]
	v_add_u32_e32 v42, v68, v184
	v_exp_f32_e32 v194, v34
	v_exp_f32_e32 v195, v35
	v_exp_f32_e32 v172, v40
	v_exp_f32_e32 v189, v41
	v_exp_f32_e32 v135, v43
	global_load_dwordx4 v[32:35], v[32:33], off
	v_ashrrev_i32_e32 v43, 31, v42
	global_load_dwordx2 v[40:41], v[36:37], off
	v_add_co_u32_e32 v36, vcc, s4, v64
	v_sub_f32_e32 v38, v38, v17
	v_sub_f32_e32 v39, v39, v17
	v_addc_co_u32_e32 v37, vcc, 0, v65, vcc
	v_lshl_add_u64 v[42:43], s[56:57], 0, v[42:43]
	v_exp_f32_e32 v173, v38
	v_exp_f32_e32 v192, v39
	global_load_dwordx4 v[36:39], v[36:37], off
	v_sub_f32_e32 v44, v44, v17
	global_load_dwordx4 v[120:123], v[42:43], off
	v_add_u32_e32 v42, v66, v185
	v_ashrrev_i32_e32 v43, 31, v42
	v_lshl_add_u64 v[42:43], s[56:57], 0, v[42:43]
	global_load_dwordx2 v[164:165], v[42:43], off
	v_add_co_u32_e32 v42, vcc, s13, v64
	v_sub_f32_e32 v45, v45, v17
	s_nop 0
	v_addc_co_u32_e32 v43, vcc, 0, v65, vcc
	global_load_dwordx4 v[124:127], v[42:43], off
	v_sub_f32_e32 v46, v46, v17
	v_sub_f32_e32 v47, v47, v17
	v_sub_f32_e32 v70, v48, v17
	v_sub_f32_e32 v71, v49, v17
	v_exp_f32_e32 v131, v44
	v_exp_f32_e32 v134, v45
	v_exp_f32_e32 v129, v46
	v_exp_f32_e32 v132, v47
	v_exp_f32_e32 v128, v70
	v_exp_f32_e32 v130, v71
	s_waitcnt vmcnt(3)
	v_sub_f32_e32 v16, 0, v17
	s_waitcnt vmcnt(3)
	ds_write_b128 v179, v[36:39] offset:8192
	ds_write_b128 v67, v[32:35] offset:37888
	ds_write_b64 v69, v[40:41] offset:37888
	v_mov_b64_e32 v[46:47], v[14:15]
	v_sub_f32_e32 v61, v31, v17
	v_sub_f32_e32 v60, v30, v17
	v_sub_f32_e32 v59, v29, v17
	v_sub_f32_e32 v58, v28, v17
	v_sub_f32_e32 v57, v27, v17
	v_sub_f32_e32 v56, v26, v17
	v_sub_f32_e32 v55, v25, v17
	v_sub_f32_e32 v54, v24, v17
	v_sub_f32_e32 v53, v23, v17
	v_sub_f32_e32 v52, v22, v17
	v_sub_f32_e32 v51, v21, v17
	v_sub_f32_e32 v50, v20, v17
	v_sub_f32_e32 v49, v19, v17
	v_sub_f32_e32 v48, v18, v17
	v_mov_b32_e32 v17, v16
	v_mov_b32_e32 v18, v16
	v_mov_b32_e32 v19, v16
	v_mov_b32_e32 v20, v16
	v_mov_b32_e32 v21, v16
	v_mov_b32_e32 v22, v16
	v_mov_b32_e32 v23, v16
	v_mov_b32_e32 v24, v16
	v_mov_b32_e32 v25, v16
	v_mov_b32_e32 v26, v16
	v_mov_b32_e32 v27, v16
	v_mov_b32_e32 v28, v16
	v_mov_b32_e32 v29, v16
	v_mov_b32_e32 v30, v16
	v_mov_b32_e32 v31, v16
	s_mov_b32 s4, 1
	v_mov_b64_e32 v[44:45], v[12:13]
	v_mov_b64_e32 v[42:43], v[10:11]
	v_mov_b64_e32 v[40:41], v[8:9]
	v_mov_b64_e32 v[38:39], v[6:7]
	v_mov_b64_e32 v[36:37], v[4:5]
	v_mov_b64_e32 v[34:35], v[2:3]
	v_mov_b64_e32 v[32:33], v[0:1]
	s_waitcnt lgkmcnt(0)
	s_barrier

.LBB0_269:
	v_readlane_b32 s0, v232, 0
	s_cmp_lt_i32 s0, 1
	s_mov_b64 s[2:3], -1
	s_cbranch_scc1 .LBB0_387
	v_readlane_b32 s0, v232, 0
	s_cmp_gt_i32 s0, 1
	s_cbranch_scc0 .LBB0_307
	s_lshl_b32 s1, s30, 3
	v_readlane_b32 s2, v233, 57
	s_add_i32 s40, s2, s1
	s_mov_b32 s0, 0x358637bd
	s_cmpk_gt_i32 s40, 0x3fff
	s_cbranch_scc1 .LBB0_276
	s_lshl_b32 s42, s31, 3
	s_add_u32 s44, s50, 0x40000
	s_addc_u32 s45, s51, 0
	s_bfe_i64 s[2:3], s[48:49], 0x200000
	s_lshl_b64 s[2:3], s[2:3], 3
	s_add_u32 s2, s94, s2
	s_addc_u32 s3, s95, s3
	s_load_dwordx2 s[4:5], s[2:3], 0x40
	v_readlane_b32 s8, v233, 60
	s_load_dwordx2 s[2:3], s[2:3], 0x30
	v_readlane_b32 s9, v233, 61
	s_lshl_b64 s[6:7], s[8:9], 9
	s_waitcnt lgkmcnt(0)
	s_add_u32 s4, s4, s6
	s_addc_u32 s5, s5, s7
	s_lshl_b64 s[6:7], s[8:9], 10
	v_and_b32_e32 v16, 63, v207
	s_add_u32 s2, s2, s6
	s_addc_u32 s3, s3, s7
	v_lshlrev_b32_e32 v0, 4, v16
	v_mov_b32_e32 v1, v169
	v_lshl_add_u64 v[0:1], s[2:3], 0, v[0:1]
	v_readlane_b32 s2, v233, 57
	v_lshlrev_b32_e32 v12, 3, v16
	v_mov_b32_e32 v13, v169
	s_lshl_b32 s1, s30, 7
	s_lshl_b32 s2, s2, 4
	s_ashr_i32 s41, s40, 31
	v_readlane_b32 s8, v233, 40
	v_lshl_add_u64 v[2:3], s[4:5], 0, v[12:13]
	s_add_i32 s1, s1, s2
	s_lshl_b32 s4, s31, 7
	s_lshl_b64 s[2:3], s[40:41], 6
	v_readlane_b32 s10, v233, 42
	v_readlane_b32 s11, v233, 43
	s_add_u32 s2, s10, s2
	v_lshlrev_b32_e32 v14, 1, v16
	v_mov_b32_e32 v15, v169
	s_addc_u32 s3, s11, s3
	s_ashr_i32 s43, s42, 31
	v_lshl_add_u64 v[4:5], s[2:3], 0, v[14:15]
	s_lshl_b64 s[46:47], s[42:43], 6
	s_lshl_b64 s[2:3], s[40:41], 9
	s_add_u32 s6, s10, s2
	s_addc_u32 s7, s11, s3
	s_lshl_b64 s[54:55], s[42:43], 9
	v_readlane_b32 s5, v233, 29
	s_add_u32 s2, s5, s2
	v_readlane_b32 s5, v233, 30
	v_lshlrev_b32_e32 v168, 2, v16
	s_addc_u32 s3, s5, s3
	v_lshl_add_u64 v[6:7], s[6:7], 0, v[168:169]
	v_lshl_add_u64 v[8:9], s[2:3], 0, v[12:13]
	s_mul_i32 s6, s40, 0x1800
	v_readlane_b32 s2, v233, 31
	s_mul_hi_i32 s5, s40, 0x1800
	s_add_u32 s2, s2, s6
	v_readlane_b32 s3, v233, 32
	s_addc_u32 s3, s3, s5
	v_xor_b32_e32 v17, 4, v168
	v_lshl_add_u64 v[10:11], s[2:3], 0, v[168:169]
	v_readlane_b32 s2, v233, 33
	s_add_u32 s2, s2, s6
	v_readlane_b32 s3, v233, 34
	s_addc_u32 s3, s3, s5
	v_xor_b32_e32 v18, 8, v168
	v_lshl_add_u64 v[12:13], s[2:3], 0, v[12:13]
	s_add_u32 s2, s10, s6
	s_addc_u32 s3, s11, s5
	v_xor_b32_e32 v19, 16, v168
	v_xor_b32_e32 v20, 32, v168
	v_xor_b32_e32 v21, 64, v168
	v_xor_b32_e32 v22, 0x80, v168
	v_cmp_gt_u32_e64 s[38:39], 16, v16
	s_mul_i32 s56, s31, 0xc000
	s_mul_hi_i32 s57, s42, 0x1800
	v_lshl_add_u64 v[14:15], s[2:3], 0, v[14:15]
	v_readlane_b32 s9, v233, 41
	s_cmpk_eq_i32 s31, 0x100
	s_cbranch_scc0 .LBB0_274
	v_lshl_add_u64 v[4:5], v[4:5], 0, s[48:49]
	v_lshl_add_u64 v[6:7], v[6:7], 0, s[48:49]
	v_lshl_add_u64 v[8:9], v[8:9], 0, s[48:49]
	v_lshl_add_u64 v[10:11], v[10:11], 0, s[48:49]
	v_lshl_add_u64 v[12:13], v[12:13], 0, s[48:49]
	v_lshl_add_u64 v[14:15], v[14:15], 0, s[48:49]
	s_mov_b64 s[6:7], 0x6a00000
	v_lshl_add_u64 v[14:15], v[14:15], 0, s[6:7]
	s_mov_b64 s[6:7], 0xd200000
	v_lshl_add_u64 v[6:7], v[6:7], 0, s[6:7]
	s_mov_b64 s[6:7], 0xda00000
	v_lshl_add_u64 v[4:5], v[4:5], 0, s[6:7]
	global_load_dwordx4 v[96:99], v[0:1], off
	global_load_dwordx2 v[100:101], v[2:3], off
	v_mov_b32_e32 v102, s0
	global_load_dwordx2 v[40:41], v[12:13], off
	global_load_dword v56, v[10:11], off
	v_lshl_add_u64 v[12:13], v[12:13], 0, s[56:57]
	v_lshl_add_u64 v[10:11], v[10:11], 0, s[56:57]
	global_load_dwordx2 v[42:43], v[12:13], off
	global_load_dword v57, v[10:11], off
	v_lshl_add_u64 v[12:13], v[12:13], 0, s[56:57]
	v_lshl_add_u64 v[10:11], v[10:11], 0, s[56:57]
	global_load_dwordx2 v[44:45], v[12:13], off
	global_load_dword v58, v[10:11], off
	v_lshl_add_u64 v[12:13], v[12:13], 0, s[56:57]
	v_lshl_add_u64 v[10:11], v[10:11], 0, s[56:57]
	global_load_dwordx2 v[46:47], v[12:13], off
	global_load_dword v59, v[10:11], off
	v_lshl_add_u64 v[12:13], v[12:13], 0, s[56:57]
	v_lshl_add_u64 v[10:11], v[10:11], 0, s[56:57]
	global_load_dwordx2 v[48:49], v[12:13], off
	global_load_dword v60, v[10:11], off
	v_lshl_add_u64 v[12:13], v[12:13], 0, s[56:57]
	v_lshl_add_u64 v[10:11], v[10:11], 0, s[56:57]
	global_load_dwordx2 v[50:51], v[12:13], off
	global_load_dword v61, v[10:11], off
	v_lshl_add_u64 v[12:13], v[12:13], 0, s[56:57]
	v_lshl_add_u64 v[10:11], v[10:11], 0, s[56:57]
	global_load_dwordx2 v[52:53], v[12:13], off
	global_load_dword v62, v[10:11], off
	v_lshl_add_u64 v[12:13], v[12:13], 0, s[56:57]
	v_lshl_add_u64 v[10:11], v[10:11], 0, s[56:57]
	global_load_dwordx2 v[54:55], v[12:13], off
	global_load_dword v63, v[10:11], off
	s_and_saveexec_b64 s[2:3], s[38:39]
	s_and_b32 s5, s1, 0xfff0
	v_or_b32_e32 v24, s5, v16
	v_lshlrev_b32_e32 v24, 2, v24
	global_load_ushort v64, v[14:15], off offset:1280
	global_load_ushort v72, v[14:15], off offset:1312
	global_load_dword v80, v24, s[44:45]
	global_load_dword v88, v24, s[50:51]
	s_add_i32 s1, s1, s4
	v_lshl_add_u64 v[14:15], v[14:15], 0, s[56:57]
	s_and_b32 s5, s1, 0xfff0
	v_or_b32_e32 v24, s5, v16
	v_lshlrev_b32_e32 v24, 2, v24
	global_load_ushort v65, v[14:15], off offset:1280
	global_load_ushort v73, v[14:15], off offset:1312
	global_load_dword v81, v24, s[44:45]
	global_load_dword v89, v24, s[50:51]
	s_add_i32 s1, s1, s4
	v_lshl_add_u64 v[14:15], v[14:15], 0, s[56:57]
	s_and_b32 s5, s1, 0xfff0
	v_or_b32_e32 v24, s5, v16
	v_lshlrev_b32_e32 v24, 2, v24
	global_load_ushort v66, v[14:15], off offset:1280
	global_load_ushort v74, v[14:15], off offset:1312
	global_load_dword v82, v24, s[44:45]
	global_load_dword v90, v24, s[50:51]
	s_add_i32 s1, s1, s4
	v_lshl_add_u64 v[14:15], v[14:15], 0, s[56:57]
	s_and_b32 s5, s1, 0xfff0
	v_or_b32_e32 v24, s5, v16
	v_lshlrev_b32_e32 v24, 2, v24
	global_load_ushort v67, v[14:15], off offset:1280
	global_load_ushort v75, v[14:15], off offset:1312
	global_load_dword v83, v24, s[44:45]
	global_load_dword v91, v24, s[50:51]
	s_add_i32 s1, s1, s4
	v_lshl_add_u64 v[14:15], v[14:15], 0, s[56:57]
	s_and_b32 s5, s1, 0xfff0
	v_or_b32_e32 v24, s5, v16
	v_lshlrev_b32_e32 v24, 2, v24
	global_load_ushort v68, v[14:15], off offset:1280
	global_load_ushort v76, v[14:15], off offset:1312
	global_load_dword v84, v24, s[44:45]
	global_load_dword v92, v24, s[50:51]
	s_add_i32 s1, s1, s4
	v_lshl_add_u64 v[14:15], v[14:15], 0, s[56:57]
	s_and_b32 s5, s1, 0xfff0
	v_or_b32_e32 v24, s5, v16
	v_lshlrev_b32_e32 v24, 2, v24
	global_load_ushort v69, v[14:15], off offset:1280
	global_load_ushort v77, v[14:15], off offset:1312
	global_load_dword v85, v24, s[44:45]
	global_load_dword v93, v24, s[50:51]
	s_add_i32 s1, s1, s4
	v_lshl_add_u64 v[14:15], v[14:15], 0, s[56:57]
	s_and_b32 s5, s1, 0xfff0
	v_or_b32_e32 v24, s5, v16
	v_lshlrev_b32_e32 v24, 2, v24
	global_load_ushort v70, v[14:15], off offset:1280
	global_load_ushort v78, v[14:15], off offset:1312
	global_load_dword v86, v24, s[44:45]
	global_load_dword v94, v24, s[50:51]
	s_add_i32 s1, s1, s4
	v_lshl_add_u64 v[14:15], v[14:15], 0, s[56:57]
	s_and_b32 s5, s1, 0xfff0
	v_or_b32_e32 v24, s5, v16
	v_lshlrev_b32_e32 v24, 2, v24
	global_load_ushort v71, v[14:15], off offset:1280
	global_load_ushort v79, v[14:15], off offset:1312
	global_load_dword v87, v24, s[44:45]
	global_load_dword v95, v24, s[50:51]
	s_or_b64 exec, exec, s[2:3]
	s_waitcnt vmcnt(32)
	v_and_b32_e32 v105, 0xffff0000, v40
	v_lshlrev_b32_e32 v104, 16, v40
	v_mul_f32_e32 v136, v105, v105
	v_and_b32_e32 v106, 0xffff0000, v41
	v_lshlrev_b32_e32 v107, 16, v41
	v_fmac_f32_e32 v136, v104, v104
	v_mul_f32_e32 v24, v106, v106
	v_mul_f32_e32 v25, v107, v107
	v_add_f32_e32 v136, v25, v136
	v_add_f32_e32 v136, v24, v136
	v_and_b32_e32 v109, 0xffff0000, v42
	v_lshlrev_b32_e32 v108, 16, v42
	v_mul_f32_e32 v137, v109, v109
	v_and_b32_e32 v110, 0xffff0000, v43
	v_lshlrev_b32_e32 v111, 16, v43
	v_fmac_f32_e32 v137, v108, v108
	v_mul_f32_e32 v24, v110, v110
	v_mul_f32_e32 v25, v111, v111
	v_add_f32_e32 v137, v25, v137
	v_add_f32_e32 v137, v24, v137
	v_and_b32_e32 v113, 0xffff0000, v44
	v_lshlrev_b32_e32 v112, 16, v44
	v_mul_f32_e32 v138, v113, v113
	v_and_b32_e32 v114, 0xffff0000, v45
	v_lshlrev_b32_e32 v115, 16, v45
	v_fmac_f32_e32 v138, v112, v112
	v_mul_f32_e32 v24, v114, v114
	v_mul_f32_e32 v25, v115, v115
	v_add_f32_e32 v138, v25, v138
	v_add_f32_e32 v138, v24, v138
	v_and_b32_e32 v117, 0xffff0000, v46
	v_lshlrev_b32_e32 v116, 16, v46
	v_mul_f32_e32 v139, v117, v117
	v_and_b32_e32 v118, 0xffff0000, v47
	v_lshlrev_b32_e32 v119, 16, v47
	v_fmac_f32_e32 v139, v116, v116
	v_mul_f32_e32 v24, v118, v118
	v_mul_f32_e32 v25, v119, v119
	v_add_f32_e32 v139, v25, v139
	v_add_f32_e32 v139, v24, v139
	v_and_b32_e32 v121, 0xffff0000, v48
	v_lshlrev_b32_e32 v120, 16, v48
	v_mul_f32_e32 v140, v121, v121
	v_and_b32_e32 v122, 0xffff0000, v49
	v_lshlrev_b32_e32 v123, 16, v49
	v_fmac_f32_e32 v140, v120, v120
	v_mul_f32_e32 v24, v122, v122
	v_mul_f32_e32 v25, v123, v123
	v_add_f32_e32 v140, v25, v140
	v_add_f32_e32 v140, v24, v140
	v_and_b32_e32 v125, 0xffff0000, v50
	v_lshlrev_b32_e32 v124, 16, v50
	v_mul_f32_e32 v141, v125, v125
	v_and_b32_e32 v126, 0xffff0000, v51
	v_lshlrev_b32_e32 v127, 16, v51
	v_fmac_f32_e32 v141, v124, v124
	v_mul_f32_e32 v24, v126, v126
	v_mul_f32_e32 v25, v127, v127
	v_add_f32_e32 v141, v25, v141
	v_add_f32_e32 v141, v24, v141
	v_and_b32_e32 v129, 0xffff0000, v52
	v_lshlrev_b32_e32 v128, 16, v52
	v_mul_f32_e32 v142, v129, v129
	v_and_b32_e32 v130, 0xffff0000, v53
	v_lshlrev_b32_e32 v131, 16, v53
	v_fmac_f32_e32 v142, v128, v128
	v_mul_f32_e32 v24, v130, v130
	v_mul_f32_e32 v25, v131, v131
	v_add_f32_e32 v142, v25, v142
	v_add_f32_e32 v142, v24, v142
	v_and_b32_e32 v133, 0xffff0000, v54
	v_lshlrev_b32_e32 v132, 16, v54
	v_mul_f32_e32 v143, v133, v133
	v_and_b32_e32 v134, 0xffff0000, v55
	v_lshlrev_b32_e32 v135, 16, v55
	v_fmac_f32_e32 v143, v132, v132
	v_mul_f32_e32 v24, v134, v134
	v_mul_f32_e32 v25, v135, v135
	v_add_f32_e32 v143, v25, v143
	v_add_f32_e32 v143, v24, v143
	ds_bpermute_b32 v144, v17, v136
	ds_bpermute_b32 v145, v17, v137
	ds_bpermute_b32 v146, v17, v138
	ds_bpermute_b32 v147, v17, v139
	ds_bpermute_b32 v148, v17, v140
	ds_bpermute_b32 v149, v17, v141
	ds_bpermute_b32 v150, v17, v142
	ds_bpermute_b32 v151, v17, v143
	s_waitcnt lgkmcnt(7)
	v_add_f32_e32 v136, v136, v144
	s_waitcnt lgkmcnt(6)
	v_add_f32_e32 v137, v137, v145
	s_waitcnt lgkmcnt(5)
	v_add_f32_e32 v138, v138, v146
	s_waitcnt lgkmcnt(4)
	v_add_f32_e32 v139, v139, v147
	s_waitcnt lgkmcnt(3)
	v_add_f32_e32 v140, v140, v148
	s_waitcnt lgkmcnt(2)
	v_add_f32_e32 v141, v141, v149
	s_waitcnt lgkmcnt(1)
	v_add_f32_e32 v142, v142, v150
	s_waitcnt lgkmcnt(0)
	v_add_f32_e32 v143, v143, v151
	ds_bpermute_b32 v144, v18, v136
	ds_bpermute_b32 v145, v18, v137
	ds_bpermute_b32 v146, v18, v138
	ds_bpermute_b32 v147, v18, v139
	ds_bpermute_b32 v148, v18, v140
	ds_bpermute_b32 v149, v18, v141
	ds_bpermute_b32 v150, v18, v142
	ds_bpermute_b32 v151, v18, v143
	s_waitcnt lgkmcnt(7)
	v_add_f32_e32 v136, v136, v144
	s_waitcnt lgkmcnt(6)
	v_add_f32_e32 v137, v137, v145
	s_waitcnt lgkmcnt(5)
	v_add_f32_e32 v138, v138, v146
	s_waitcnt lgkmcnt(4)
	v_add_f32_e32 v139, v139, v147
	s_waitcnt lgkmcnt(3)
	v_add_f32_e32 v140, v140, v148
	s_waitcnt lgkmcnt(2)
	v_add_f32_e32 v141, v141, v149
	s_waitcnt lgkmcnt(1)
	v_add_f32_e32 v142, v142, v150
	s_waitcnt lgkmcnt(0)
	v_add_f32_e32 v143, v143, v151
	ds_bpermute_b32 v144, v19, v136
	ds_bpermute_b32 v145, v19, v137
	ds_bpermute_b32 v146, v19, v138
	ds_bpermute_b32 v147, v19, v139
	ds_bpermute_b32 v148, v19, v140
	ds_bpermute_b32 v149, v19, v141
	ds_bpermute_b32 v150, v19, v142
	ds_bpermute_b32 v151, v19, v143
	s_waitcnt lgkmcnt(7)
	v_add_f32_e32 v136, v136, v144
	s_waitcnt lgkmcnt(6)
	v_add_f32_e32 v137, v137, v145
	s_waitcnt lgkmcnt(5)
	v_add_f32_e32 v138, v138, v146
	s_waitcnt lgkmcnt(4)
	v_add_f32_e32 v139, v139, v147
	s_waitcnt lgkmcnt(3)
	v_add_f32_e32 v140, v140, v148
	s_waitcnt lgkmcnt(2)
	v_add_f32_e32 v141, v141, v149
	s_waitcnt lgkmcnt(1)
	v_add_f32_e32 v142, v142, v150
	s_waitcnt lgkmcnt(0)
	v_add_f32_e32 v143, v143, v151
	ds_bpermute_b32 v144, v20, v136
	ds_bpermute_b32 v145, v20, v137
	ds_bpermute_b32 v146, v20, v138
	ds_bpermute_b32 v147, v20, v139
	ds_bpermute_b32 v148, v20, v140
	ds_bpermute_b32 v149, v20, v141
	ds_bpermute_b32 v150, v20, v142
	ds_bpermute_b32 v151, v20, v143
	s_waitcnt lgkmcnt(7)
	v_add_f32_e32 v136, v136, v144
	s_waitcnt lgkmcnt(6)
	v_add_f32_e32 v137, v137, v145
	s_waitcnt lgkmcnt(5)
	v_add_f32_e32 v138, v138, v146
	s_waitcnt lgkmcnt(4)
	v_add_f32_e32 v139, v139, v147
	s_waitcnt lgkmcnt(3)
	v_add_f32_e32 v140, v140, v148
	s_waitcnt lgkmcnt(2)
	v_add_f32_e32 v141, v141, v149
	s_waitcnt lgkmcnt(1)
	v_add_f32_e32 v142, v142, v150
	s_waitcnt lgkmcnt(0)
	v_add_f32_e32 v143, v143, v151
	ds_bpermute_b32 v144, v21, v136
	ds_bpermute_b32 v145, v21, v137
	ds_bpermute_b32 v146, v21, v138
	ds_bpermute_b32 v147, v21, v139
	ds_bpermute_b32 v148, v21, v140
	ds_bpermute_b32 v149, v21, v141
	ds_bpermute_b32 v150, v21, v142
	ds_bpermute_b32 v151, v21, v143
	s_waitcnt lgkmcnt(7)
	v_add_f32_e32 v136, v136, v144
	s_waitcnt lgkmcnt(6)
	v_add_f32_e32 v137, v137, v145
	s_waitcnt lgkmcnt(5)
	v_add_f32_e32 v138, v138, v146
	s_waitcnt lgkmcnt(4)
	v_add_f32_e32 v139, v139, v147
	s_waitcnt lgkmcnt(3)
	v_add_f32_e32 v140, v140, v148
	s_waitcnt lgkmcnt(2)
	v_add_f32_e32 v141, v141, v149
	s_waitcnt lgkmcnt(1)
	v_add_f32_e32 v142, v142, v150
	s_waitcnt lgkmcnt(0)
	v_add_f32_e32 v143, v143, v151
	ds_bpermute_b32 v144, v22, v136
	ds_bpermute_b32 v145, v22, v137
	ds_bpermute_b32 v146, v22, v138
	ds_bpermute_b32 v147, v22, v139
	ds_bpermute_b32 v148, v22, v140
	ds_bpermute_b32 v149, v22, v141
	ds_bpermute_b32 v150, v22, v142
	ds_bpermute_b32 v151, v22, v143
	s_waitcnt lgkmcnt(7)
	v_add_f32_e32 v136, v136, v144
	s_waitcnt lgkmcnt(6)
	v_add_f32_e32 v137, v137, v145
	s_waitcnt lgkmcnt(5)
	v_add_f32_e32 v138, v138, v146
	s_waitcnt lgkmcnt(4)
	v_add_f32_e32 v139, v139, v147
	s_waitcnt lgkmcnt(3)
	v_add_f32_e32 v140, v140, v148
	s_waitcnt lgkmcnt(2)
	v_add_f32_e32 v141, v141, v149
	s_waitcnt lgkmcnt(1)
	v_add_f32_e32 v142, v142, v150
	s_waitcnt lgkmcnt(0)
	v_add_f32_e32 v143, v143, v151
	s_waitcnt vmcnt(32)
	v_fmamk_f32 v136, v136, 0x3b800000, v102
	v_rsq_f32_e32 v136, v136
	v_fmamk_f32 v137, v137, 0x3b800000, v102
	v_rsq_f32_e32 v137, v137
	v_fmamk_f32 v138, v138, 0x3b800000, v102
	v_rsq_f32_e32 v138, v138
	v_fmamk_f32 v139, v139, 0x3b800000, v102
	v_rsq_f32_e32 v139, v139
	v_fmamk_f32 v140, v140, 0x3b800000, v102
	v_rsq_f32_e32 v140, v140
	v_fmamk_f32 v141, v141, 0x3b800000, v102
	v_rsq_f32_e32 v141, v141
	v_fmamk_f32 v142, v142, 0x3b800000, v102
	v_rsq_f32_e32 v142, v142
	v_fmamk_f32 v143, v143, 0x3b800000, v102
	v_rsq_f32_e32 v143, v143
	v_mul_f32_e32 v104, v104, v136
	v_mul_f32_e32 v105, v105, v136
	v_mul_f32_e32 v24, v107, v136
	v_mul_f32_e32 v25, v106, v136
	v_mul_f32_e32 v104, v96, v104
	v_mul_f32_e32 v105, v97, v105
	v_mul_f32_e32 v24, v98, v24
	v_mul_f32_e32 v25, v99, v25
	v_cvt_pk_bf16_f32 v104, v104, v105
	v_cvt_pk_bf16_f32 v105, v24, v25
	global_store_dwordx2 v[8:9], v[104:105], off
	v_lshl_add_u64 v[8:9], v[8:9], 0, s[54:55]
	v_mul_f32_e32 v108, v108, v137
	v_mul_f32_e32 v109, v109, v137
	v_mul_f32_e32 v24, v111, v137
	v_mul_f32_e32 v25, v110, v137
	v_mul_f32_e32 v108, v96, v108
	v_mul_f32_e32 v109, v97, v109
	v_mul_f32_e32 v24, v98, v24
	v_mul_f32_e32 v25, v99, v25
	v_cvt_pk_bf16_f32 v108, v108, v109
	v_cvt_pk_bf16_f32 v109, v24, v25
	global_store_dwordx2 v[8:9], v[108:109], off
	v_lshl_add_u64 v[8:9], v[8:9], 0, s[54:55]
	v_mul_f32_e32 v112, v112, v138
	v_mul_f32_e32 v113, v113, v138
	v_mul_f32_e32 v24, v115, v138
	v_mul_f32_e32 v25, v114, v138
	v_mul_f32_e32 v112, v96, v112
	v_mul_f32_e32 v113, v97, v113
	v_mul_f32_e32 v24, v98, v24
	v_mul_f32_e32 v25, v99, v25
	v_cvt_pk_bf16_f32 v112, v112, v113
	v_cvt_pk_bf16_f32 v113, v24, v25
	global_store_dwordx2 v[8:9], v[112:113], off
	v_lshl_add_u64 v[8:9], v[8:9], 0, s[54:55]
	v_mul_f32_e32 v116, v116, v139
	v_mul_f32_e32 v117, v117, v139
	v_mul_f32_e32 v24, v119, v139
	v_mul_f32_e32 v25, v118, v139
	v_mul_f32_e32 v116, v96, v116
	v_mul_f32_e32 v117, v97, v117
	v_mul_f32_e32 v24, v98, v24
	v_mul_f32_e32 v25, v99, v25
	v_cvt_pk_bf16_f32 v116, v116, v117
	v_cvt_pk_bf16_f32 v117, v24, v25
	global_store_dwordx2 v[8:9], v[116:117], off
	v_lshl_add_u64 v[8:9], v[8:9], 0, s[54:55]
	v_mul_f32_e32 v120, v120, v140
	v_mul_f32_e32 v121, v121, v140
	v_mul_f32_e32 v24, v123, v140
	v_mul_f32_e32 v25, v122, v140
	v_mul_f32_e32 v120, v96, v120
	v_mul_f32_e32 v121, v97, v121
	v_mul_f32_e32 v24, v98, v24
	v_mul_f32_e32 v25, v99, v25
	v_cvt_pk_bf16_f32 v120, v120, v121
	v_cvt_pk_bf16_f32 v121, v24, v25
	global_store_dwordx2 v[8:9], v[120:121], off
	v_lshl_add_u64 v[8:9], v[8:9], 0, s[54:55]
	v_mul_f32_e32 v124, v124, v141
	v_mul_f32_e32 v125, v125, v141
	v_mul_f32_e32 v24, v127, v141
	v_mul_f32_e32 v25, v126, v141
	v_mul_f32_e32 v124, v96, v124
	v_mul_f32_e32 v125, v97, v125
	v_mul_f32_e32 v24, v98, v24
	v_mul_f32_e32 v25, v99, v25
	v_cvt_pk_bf16_f32 v124, v124, v125
	v_cvt_pk_bf16_f32 v125, v24, v25
	global_store_dwordx2 v[8:9], v[124:125], off
	v_lshl_add_u64 v[8:9], v[8:9], 0, s[54:55]
	v_mul_f32_e32 v128, v128, v142
	v_mul_f32_e32 v129, v129, v142
	v_mul_f32_e32 v24, v131, v142
	v_mul_f32_e32 v25, v130, v142
	v_mul_f32_e32 v128, v96, v128
	v_mul_f32_e32 v129, v97, v129
	v_mul_f32_e32 v24, v98, v24
	v_mul_f32_e32 v25, v99, v25
	v_cvt_pk_bf16_f32 v128, v128, v129
	v_cvt_pk_bf16_f32 v129, v24, v25
	global_store_dwordx2 v[8:9], v[128:129], off
	v_lshl_add_u64 v[8:9], v[8:9], 0, s[54:55]
	v_mul_f32_e32 v132, v132, v143
	v_mul_f32_e32 v133, v133, v143
	v_mul_f32_e32 v24, v135, v143
	v_mul_f32_e32 v25, v134, v143
	v_mul_f32_e32 v132, v96, v132
	v_mul_f32_e32 v133, v97, v133
	v_mul_f32_e32 v24, v98, v24
	v_mul_f32_e32 v25, v99, v25
	v_cvt_pk_bf16_f32 v132, v132, v133
	v_cvt_pk_bf16_f32 v133, v24, v25
	global_store_dwordx2 v[8:9], v[132:133], off
	v_lshlrev_b32_e32 v152, 16, v56
	v_and_b32_e32 v153, 0xffff0000, v56
	v_mul_f32_e32 v136, v153, v153
	v_fmac_f32_e32 v136, v152, v152
	v_lshlrev_b32_e32 v154, 16, v57
	v_and_b32_e32 v155, 0xffff0000, v57
	v_mul_f32_e32 v137, v155, v155
	v_fmac_f32_e32 v137, v154, v154
	v_lshlrev_b32_e32 v156, 16, v58
	v_and_b32_e32 v157, 0xffff0000, v58
	v_mul_f32_e32 v138, v157, v157
	v_fmac_f32_e32 v138, v156, v156
	v_lshlrev_b32_e32 v158, 16, v59
	v_and_b32_e32 v159, 0xffff0000, v59
	v_mul_f32_e32 v139, v159, v159
	v_fmac_f32_e32 v139, v158, v158
	v_lshlrev_b32_e32 v160, 16, v60
	v_and_b32_e32 v161, 0xffff0000, v60
	v_mul_f32_e32 v140, v161, v161
	v_fmac_f32_e32 v140, v160, v160
	v_lshlrev_b32_e32 v162, 16, v61
	v_and_b32_e32 v163, 0xffff0000, v61
	v_mul_f32_e32 v141, v163, v163
	v_fmac_f32_e32 v141, v162, v162
	v_lshlrev_b32_e32 v164, 16, v62
	v_and_b32_e32 v165, 0xffff0000, v62
	v_mul_f32_e32 v142, v165, v165
	v_fmac_f32_e32 v142, v164, v164
	v_lshlrev_b32_e32 v166, 16, v63
	v_and_b32_e32 v167, 0xffff0000, v63
	v_mul_f32_e32 v143, v167, v167
	v_fmac_f32_e32 v143, v166, v166
	ds_bpermute_b32 v144, v17, v136
	ds_bpermute_b32 v145, v17, v137
	ds_bpermute_b32 v146, v17, v138
	ds_bpermute_b32 v147, v17, v139
	ds_bpermute_b32 v148, v17, v140
	ds_bpermute_b32 v149, v17, v141
	ds_bpermute_b32 v150, v17, v142
	ds_bpermute_b32 v151, v17, v143
	s_waitcnt lgkmcnt(7)
	v_add_f32_e32 v136, v136, v144
	s_waitcnt lgkmcnt(6)
	v_add_f32_e32 v137, v137, v145
	s_waitcnt lgkmcnt(5)
	v_add_f32_e32 v138, v138, v146
	s_waitcnt lgkmcnt(4)
	v_add_f32_e32 v139, v139, v147
	s_waitcnt lgkmcnt(3)
	v_add_f32_e32 v140, v140, v148
	s_waitcnt lgkmcnt(2)
	v_add_f32_e32 v141, v141, v149
	s_waitcnt lgkmcnt(1)
	v_add_f32_e32 v142, v142, v150
	s_waitcnt lgkmcnt(0)
	v_add_f32_e32 v143, v143, v151
	ds_bpermute_b32 v144, v18, v136
	ds_bpermute_b32 v145, v18, v137
	ds_bpermute_b32 v146, v18, v138
	ds_bpermute_b32 v147, v18, v139
	ds_bpermute_b32 v148, v18, v140
	ds_bpermute_b32 v149, v18, v141
	ds_bpermute_b32 v150, v18, v142
	ds_bpermute_b32 v151, v18, v143
	s_waitcnt lgkmcnt(7)
	v_add_f32_e32 v136, v136, v144
	s_waitcnt lgkmcnt(6)
	v_add_f32_e32 v137, v137, v145
	s_waitcnt lgkmcnt(5)
	v_add_f32_e32 v138, v138, v146
	s_waitcnt lgkmcnt(4)
	v_add_f32_e32 v139, v139, v147
	s_waitcnt lgkmcnt(3)
	v_add_f32_e32 v140, v140, v148
	s_waitcnt lgkmcnt(2)
	v_add_f32_e32 v141, v141, v149
	s_waitcnt lgkmcnt(1)
	v_add_f32_e32 v142, v142, v150
	s_waitcnt lgkmcnt(0)
	v_add_f32_e32 v143, v143, v151
	ds_bpermute_b32 v144, v19, v136
	ds_bpermute_b32 v145, v19, v137
	ds_bpermute_b32 v146, v19, v138
	ds_bpermute_b32 v147, v19, v139
	ds_bpermute_b32 v148, v19, v140
	ds_bpermute_b32 v149, v19, v141
	ds_bpermute_b32 v150, v19, v142
	ds_bpermute_b32 v151, v19, v143
	s_waitcnt lgkmcnt(7)
	v_add_f32_e32 v136, v136, v144
	s_waitcnt lgkmcnt(6)
	v_add_f32_e32 v137, v137, v145
	s_waitcnt lgkmcnt(5)
	v_add_f32_e32 v138, v138, v146
	s_waitcnt lgkmcnt(4)
	v_add_f32_e32 v139, v139, v147
	s_waitcnt lgkmcnt(3)
	v_add_f32_e32 v140, v140, v148
	s_waitcnt lgkmcnt(2)
	v_add_f32_e32 v141, v141, v149
	s_waitcnt lgkmcnt(1)
	v_add_f32_e32 v142, v142, v150
	s_waitcnt lgkmcnt(0)
	v_add_f32_e32 v143, v143, v151
	ds_bpermute_b32 v144, v20, v136
	ds_bpermute_b32 v145, v20, v137
	ds_bpermute_b32 v146, v20, v138
	ds_bpermute_b32 v147, v20, v139
	ds_bpermute_b32 v148, v20, v140
	ds_bpermute_b32 v149, v20, v141
	ds_bpermute_b32 v150, v20, v142
	ds_bpermute_b32 v151, v20, v143
	s_waitcnt lgkmcnt(7)
	v_add_f32_e32 v136, v136, v144
	s_waitcnt lgkmcnt(6)
	v_add_f32_e32 v137, v137, v145
	s_waitcnt lgkmcnt(5)
	v_add_f32_e32 v138, v138, v146
	s_waitcnt lgkmcnt(4)
	v_add_f32_e32 v139, v139, v147
	s_waitcnt lgkmcnt(3)
	v_add_f32_e32 v140, v140, v148
	s_waitcnt lgkmcnt(2)
	v_add_f32_e32 v141, v141, v149
	s_waitcnt lgkmcnt(1)
	v_add_f32_e32 v142, v142, v150
	s_waitcnt lgkmcnt(0)
	v_add_f32_e32 v143, v143, v151
	ds_bpermute_b32 v144, v21, v136
	ds_bpermute_b32 v145, v21, v137
	ds_bpermute_b32 v146, v21, v138
	ds_bpermute_b32 v147, v21, v139
	ds_bpermute_b32 v148, v21, v140
	ds_bpermute_b32 v149, v21, v141
	ds_bpermute_b32 v150, v21, v142
	ds_bpermute_b32 v151, v21, v143
	s_waitcnt lgkmcnt(7)
	v_add_f32_e32 v136, v136, v144
	s_waitcnt lgkmcnt(6)
	v_add_f32_e32 v137, v137, v145
	s_waitcnt lgkmcnt(5)
	v_add_f32_e32 v138, v138, v146
	s_waitcnt lgkmcnt(4)
	v_add_f32_e32 v139, v139, v147
	s_waitcnt lgkmcnt(3)
	v_add_f32_e32 v140, v140, v148
	s_waitcnt lgkmcnt(2)
	v_add_f32_e32 v141, v141, v149
	s_waitcnt lgkmcnt(1)
	v_add_f32_e32 v142, v142, v150
	s_waitcnt lgkmcnt(0)
	v_add_f32_e32 v143, v143, v151
	ds_bpermute_b32 v144, v22, v136
	ds_bpermute_b32 v145, v22, v137
	ds_bpermute_b32 v146, v22, v138
	ds_bpermute_b32 v147, v22, v139
	ds_bpermute_b32 v148, v22, v140
	ds_bpermute_b32 v149, v22, v141
	ds_bpermute_b32 v150, v22, v142
	ds_bpermute_b32 v151, v22, v143
	s_waitcnt lgkmcnt(7)
	v_add_f32_e32 v136, v136, v144
	s_waitcnt lgkmcnt(6)
	v_add_f32_e32 v137, v137, v145
	s_waitcnt lgkmcnt(5)
	v_add_f32_e32 v138, v138, v146
	s_waitcnt lgkmcnt(4)
	v_add_f32_e32 v139, v139, v147
	s_waitcnt lgkmcnt(3)
	v_add_f32_e32 v140, v140, v148
	s_waitcnt lgkmcnt(2)
	v_add_f32_e32 v141, v141, v149
	s_waitcnt lgkmcnt(1)
	v_add_f32_e32 v142, v142, v150
	s_waitcnt lgkmcnt(0)
	v_add_f32_e32 v143, v143, v151
	v_fmamk_f32 v136, v136, 0x3c000000, v102
	v_rsq_f32_e32 v136, v136
	v_fmamk_f32 v137, v137, 0x3c000000, v102
	v_rsq_f32_e32 v137, v137
	v_fmamk_f32 v138, v138, 0x3c000000, v102
	v_rsq_f32_e32 v138, v138
	v_fmamk_f32 v139, v139, 0x3c000000, v102
	v_rsq_f32_e32 v139, v139
	v_fmamk_f32 v140, v140, 0x3c000000, v102
	v_rsq_f32_e32 v140, v140
	v_fmamk_f32 v141, v141, 0x3c000000, v102
	v_rsq_f32_e32 v141, v141
	v_fmamk_f32 v142, v142, 0x3c000000, v102
	v_rsq_f32_e32 v142, v142
	v_fmamk_f32 v143, v143, 0x3c000000, v102
	v_rsq_f32_e32 v143, v143
	v_mul_f32_e32 v152, v136, v152
	v_mul_f32_e32 v153, v136, v153
	v_mul_f32_e32 v152, v100, v152
	v_mul_f32_e32 v153, v101, v153
	v_cvt_pk_bf16_f32 v152, v152, v153
	global_store_dword v[6:7], v152, off
	global_store_dword v[6:7], v169, off offset:256
	v_lshl_add_u64 v[6:7], v[6:7], 0, s[54:55]
	v_mul_f32_e32 v154, v137, v154
	v_mul_f32_e32 v155, v137, v155
	v_mul_f32_e32 v154, v100, v154
	v_mul_f32_e32 v155, v101, v155
	v_cvt_pk_bf16_f32 v154, v154, v155
	global_store_dword v[6:7], v154, off
	global_store_dword v[6:7], v169, off offset:256
	v_lshl_add_u64 v[6:7], v[6:7], 0, s[54:55]
	v_mul_f32_e32 v156, v138, v156
	v_mul_f32_e32 v157, v138, v157
	v_mul_f32_e32 v156, v100, v156
	v_mul_f32_e32 v157, v101, v157
	v_cvt_pk_bf16_f32 v156, v156, v157
	global_store_dword v[6:7], v156, off
	global_store_dword v[6:7], v169, off offset:256
	v_lshl_add_u64 v[6:7], v[6:7], 0, s[54:55]
	v_mul_f32_e32 v158, v139, v158
	v_mul_f32_e32 v159, v139, v159
	v_mul_f32_e32 v158, v100, v158
	v_mul_f32_e32 v159, v101, v159
	v_cvt_pk_bf16_f32 v158, v158, v159
	global_store_dword v[6:7], v158, off
	global_store_dword v[6:7], v169, off offset:256
	v_lshl_add_u64 v[6:7], v[6:7], 0, s[54:55]
	v_mul_f32_e32 v160, v140, v160
	v_mul_f32_e32 v161, v140, v161
	v_mul_f32_e32 v160, v100, v160
	v_mul_f32_e32 v161, v101, v161
	v_cvt_pk_bf16_f32 v160, v160, v161
	global_store_dword v[6:7], v160, off
	global_store_dword v[6:7], v169, off offset:256
	v_lshl_add_u64 v[6:7], v[6:7], 0, s[54:55]
	v_mul_f32_e32 v162, v141, v162
	v_mul_f32_e32 v163, v141, v163
	v_mul_f32_e32 v162, v100, v162
	v_mul_f32_e32 v163, v101, v163
	v_cvt_pk_bf16_f32 v162, v162, v163
	global_store_dword v[6:7], v162, off
	global_store_dword v[6:7], v169, off offset:256
	v_lshl_add_u64 v[6:7], v[6:7], 0, s[54:55]
	v_mul_f32_e32 v164, v142, v164
	v_mul_f32_e32 v165, v142, v165
	v_mul_f32_e32 v164, v100, v164
	v_mul_f32_e32 v165, v101, v165
	v_cvt_pk_bf16_f32 v164, v164, v165
	global_store_dword v[6:7], v164, off
	global_store_dword v[6:7], v169, off offset:256
	v_lshl_add_u64 v[6:7], v[6:7], 0, s[54:55]
	v_mul_f32_e32 v166, v143, v166
	v_mul_f32_e32 v167, v143, v167
	v_mul_f32_e32 v166, v100, v166
	v_mul_f32_e32 v167, v101, v167
	v_cvt_pk_bf16_f32 v166, v166, v167
	global_store_dword v[6:7], v166, off
	global_store_dword v[6:7], v169, off offset:256
	s_waitcnt vmcnt(0)
	s_and_saveexec_b64 s[2:3], s[38:39]
	v_lshlrev_b32_e32 v64, 16, v64
	v_lshlrev_b32_e32 v72, 16, v72
	v_mul_f32_e32 v24, v80, v72
	v_mul_f32_e32 v25, v88, v72
	v_fma_f32 v26, v88, v64, -v24
	v_fmac_f32_e32 v25, v80, v64
	v_bfe_u32 v24, v26, 16, 1
	v_bfe_u32 v27, v25, 16, 1
	v_add3_u32 v26, v26, v24, s20
	v_add3_u32 v25, v25, v27, s20
	global_store_short_d16_hi v[4:5], v26, off
	global_store_short_d16_hi v[4:5], v25, off offset:32
	v_lshl_add_u64 v[4:5], v[4:5], 0, s[46:47]
	v_lshlrev_b32_e32 v65, 16, v65
	v_lshlrev_b32_e32 v73, 16, v73
	v_mul_f32_e32 v24, v81, v73
	v_mul_f32_e32 v25, v89, v73
	v_fma_f32 v26, v89, v65, -v24
	v_fmac_f32_e32 v25, v81, v65
	v_bfe_u32 v24, v26, 16, 1
	v_bfe_u32 v27, v25, 16, 1
	v_add3_u32 v26, v26, v24, s20
	v_add3_u32 v25, v25, v27, s20
	global_store_short_d16_hi v[4:5], v26, off
	global_store_short_d16_hi v[4:5], v25, off offset:32
	v_lshl_add_u64 v[4:5], v[4:5], 0, s[46:47]
	v_lshlrev_b32_e32 v66, 16, v66
	v_lshlrev_b32_e32 v74, 16, v74
	v_mul_f32_e32 v24, v82, v74
	v_mul_f32_e32 v25, v90, v74
	v_fma_f32 v26, v90, v66, -v24
	v_fmac_f32_e32 v25, v82, v66
	v_bfe_u32 v24, v26, 16, 1
	v_bfe_u32 v27, v25, 16, 1
	v_add3_u32 v26, v26, v24, s20
	v_add3_u32 v25, v25, v27, s20
	global_store_short_d16_hi v[4:5], v26, off
	global_store_short_d16_hi v[4:5], v25, off offset:32
	v_lshl_add_u64 v[4:5], v[4:5], 0, s[46:47]
	v_lshlrev_b32_e32 v67, 16, v67
	v_lshlrev_b32_e32 v75, 16, v75
	v_mul_f32_e32 v24, v83, v75
	v_mul_f32_e32 v25, v91, v75
	v_fma_f32 v26, v91, v67, -v24
	v_fmac_f32_e32 v25, v83, v67
	v_bfe_u32 v24, v26, 16, 1
	v_bfe_u32 v27, v25, 16, 1
	v_add3_u32 v26, v26, v24, s20
	v_add3_u32 v25, v25, v27, s20
	global_store_short_d16_hi v[4:5], v26, off
	global_store_short_d16_hi v[4:5], v25, off offset:32
	v_lshl_add_u64 v[4:5], v[4:5], 0, s[46:47]
	v_lshlrev_b32_e32 v68, 16, v68
	v_lshlrev_b32_e32 v76, 16, v76
	v_mul_f32_e32 v24, v84, v76
	v_mul_f32_e32 v25, v92, v76
	v_fma_f32 v26, v92, v68, -v24
	v_fmac_f32_e32 v25, v84, v68
	v_bfe_u32 v24, v26, 16, 1
	v_bfe_u32 v27, v25, 16, 1
	v_add3_u32 v26, v26, v24, s20
	v_add3_u32 v25, v25, v27, s20
	global_store_short_d16_hi v[4:5], v26, off
	global_store_short_d16_hi v[4:5], v25, off offset:32
	v_lshl_add_u64 v[4:5], v[4:5], 0, s[46:47]
	v_lshlrev_b32_e32 v69, 16, v69
	v_lshlrev_b32_e32 v77, 16, v77
	v_mul_f32_e32 v24, v85, v77
	v_mul_f32_e32 v25, v93, v77
	v_fma_f32 v26, v93, v69, -v24
	v_fmac_f32_e32 v25, v85, v69
	v_bfe_u32 v24, v26, 16, 1
	v_bfe_u32 v27, v25, 16, 1
	v_add3_u32 v26, v26, v24, s20
	v_add3_u32 v25, v25, v27, s20
	global_store_short_d16_hi v[4:5], v26, off
	global_store_short_d16_hi v[4:5], v25, off offset:32
	v_lshl_add_u64 v[4:5], v[4:5], 0, s[46:47]
	v_lshlrev_b32_e32 v70, 16, v70
	v_lshlrev_b32_e32 v78, 16, v78
	v_mul_f32_e32 v24, v86, v78
	v_mul_f32_e32 v25, v94, v78
	v_fma_f32 v26, v94, v70, -v24
	v_fmac_f32_e32 v25, v86, v70
	v_bfe_u32 v24, v26, 16, 1
	v_bfe_u32 v27, v25, 16, 1
	v_add3_u32 v26, v26, v24, s20
	v_add3_u32 v25, v25, v27, s20
	global_store_short_d16_hi v[4:5], v26, off
	global_store_short_d16_hi v[4:5], v25, off offset:32
	v_lshl_add_u64 v[4:5], v[4:5], 0, s[46:47]
	v_lshlrev_b32_e32 v71, 16, v71
	v_lshlrev_b32_e32 v79, 16, v79
	v_mul_f32_e32 v24, v87, v79
	v_mul_f32_e32 v25, v95, v79
	v_fma_f32 v26, v95, v71, -v24
	v_fmac_f32_e32 v25, v87, v71
	v_bfe_u32 v24, v26, 16, 1
	v_bfe_u32 v27, v25, 16, 1
	v_add3_u32 v26, v26, v24, s20
	v_add3_u32 v25, v25, v27, s20
	global_store_short_d16_hi v[4:5], v26, off
	global_store_short_d16_hi v[4:5], v25, off offset:32
	s_or_b64 exec, exec, s[2:3]
	s_branch .LBB0_276
